# next tile's first K-tile prefetched into fragment registers before the epilogue (P2, P5, P11 multi-tile GEMMs)
# baseline (speedup 1.0000x reference)
.LBB0_463:
	s_or_b64 exec, exec, s[14:15]
	s_mov_b64 s[6:7], s[60:61]
	s_waitcnt lgkmcnt(0)
	s_barrier
	s_load_dwordx2 s[16:17], s[6:7], 0x130
	v_mov_b32_e32 v2, v172
	s_mov_b32 s11, s42
	s_mov_b32 s20, s94
	s_waitcnt lgkmcnt(0)
	s_add_u32 s14, s16, 0x6035800
	s_addc_u32 s15, s17, 0
	s_add_u32 s18, s16, 0x3200000
	s_addc_u32 s19, s17, 0
	s_cmpk_lt_i32 s20, 0x600
	s_cbranch_scc0 .LBB0_468
	v_ashrrev_i32_e32 v204, 3, v2
	v_bfe_u32 v3, v2, 4, 2
	v_and_b32_e32 v4, 15, v2
	v_lshlrev_b32_e32 v0, 4, v2
	v_ashrrev_i32_e32 v5, 1, v2
	s_movk_i32 s2, 0xffc0
	v_lshlrev_b32_e32 v2, 1, v2
	v_and_b32_e32 v0, 0x70, v0
	v_and_or_b32 v205, v5, s2, v4
	v_and_b32_e32 v207, 0x80, v2
	s_movk_i32 s2, 0x90
	v_or_b32_e32 v2, v207, v4
	v_and_b32_e32 v100, 7, v204
	v_lshlrev_b32_e32 v100, 4, v100
	v_xor_b32_e32 v100, v100, v0
	v_lshl_add_u32 v166, v204, 7, v100
	v_lshl_add_u64 v[162:163], s[18:19], 0, v[0:1]
	v_lshl_add_u64 v[164:165], s[16:17], 0, v[0:1]
	v_and_b32_e32 v100, 7, v4
	v_xor_b32_e32 v100, v100, v3
	v_lshlrev_b32_e32 v206, 4, v100
	v_lshlrev_b32_e32 v208, 2, v3
	v_lshlrev_b32_e32 v0, 7, v205
	v_lshlrev_b32_e32 v167, 7, v2
	s_mov_b32 m0, s20
	s_mul_hi_i32 s101, m0, 0x38e38e39
	s_lshr_b32 vcc_lo, s101, 31
	s_ashr_i32 s101, s101, 4
	s_add_i32 s101, s101, vcc_lo
	s_mul_i32 vcc_lo, s101, 0x48
	s_sub_i32 m0, m0, vcc_lo
	s_lshl_b32 m0, m0, 19
	s_lshl_b32 s101, s101, 19
	v_readfirstlane_b32 vcc_lo, v162
	v_readfirstlane_b32 vcc_hi, v163
	v_and_b32_e32 v242, 7, v172
	v_lshlrev_b32_e32 v242, 4, v242
	v_lshl_add_u32 v242, v204, 11, v242
	s_add_u32 vcc_lo, vcc_lo, m0
	s_addc_u32 vcc_hi, vcc_hi, 0
	s_mov_b32 m0, s101
	v_readfirstlane_b32 s100, v164
	v_readfirstlane_b32 s101, v165
	s_nop 0
	s_add_u32 s100, s100, m0
	s_addc_u32 s101, s101, 0
	global_load_dwordx4 v[210:213], v242, vcc
	v_add_u32_e32 v214, s34, v242
	global_load_dwordx4 v[214:217], v214, vcc
	v_add_u32_e32 v218, s35, v242
	global_load_dwordx4 v[218:221], v218, vcc
	v_add_u32_e32 v222, s36, v242
	global_load_dwordx4 v[222:225], v222, vcc
	global_load_dwordx4 v[226:229], v242, s[100:101]
	v_add_u32_e32 v230, s34, v242
	global_load_dwordx4 v[230:233], v230, s[100:101]
	v_add_u32_e32 v234, s35, v242
	global_load_dwordx4 v[234:237], v234, s[100:101]
	v_add_u32_e32 v238, s36, v242
	global_load_dwordx4 v[238:241], v238, s[100:101]
.LBB0_465:
	s_mul_hi_i32 s4, s20, 0x38e38e39
	s_lshr_b32 s6, s4, 31
	s_ashr_i32 s4, s4, 4
	s_add_i32 s4, s4, s6
	s_mul_i32 s6, s4, 0x48
	s_sub_i32 s6, s20, s6
	s_lshl_b32 s6, s6, 8
	v_add_u32_e32 v2, s6, v204
	v_ashrrev_i32_e32 v3, 31, v2
	v_lshlrev_b64 v[2:3], 11, v[2:3]
	v_lshl_add_u64 v[168:169], v[162:163], 0, v[2:3]
	v_add_co_u32_e32 v56, vcc, s34, v168
	s_lshl_b32 s7, s4, 8
	s_nop 0
	v_addc_co_u32_e32 v57, vcc, 0, v169, vcc
	v_add_u32_e32 v2, s7, v204
	s_waitcnt vmcnt(9)
	v_add_co_u32_e32 v58, vcc, s35, v168
	v_ashrrev_i32_e32 v3, 31, v2
	s_nop 0
	v_addc_co_u32_e32 v59, vcc, 0, v169, vcc
	v_lshlrev_b64 v[2:3], 11, v[2:3]
	v_add_co_u32_e32 v60, vcc, s36, v168
	v_lshl_add_u64 v[170:171], v[164:165], 0, v[2:3]
	s_nop 0
	v_addc_co_u32_e32 v61, vcc, 0, v169, vcc
	s_waitcnt vmcnt(8)
	v_add_co_u32_e32 v62, vcc, s35, v170
	s_nop 1
	s_nop 1
	v_addc_co_u32_e32 v63, vcc, 0, v171, vcc
	v_add_co_u32_e32 v64, vcc, s36, v170
	s_nop 1
	s_nop 1
	v_addc_co_u32_e32 v65, vcc, 0, v171, vcc
	v_add_co_u32_e32 v66, vcc, s34, v170
	s_nop 1
	s_nop 1
	v_addc_co_u32_e32 v67, vcc, 0, v171, vcc
	s_nop 1
	s_nop 1
	s_barrier
	global_load_dwordx4 v[114:117], v[168:169], off offset:128
	global_load_dwordx4 v[106:109], v[56:57], off offset:128
	global_load_dwordx4 v[110:113], v[58:59], off offset:128
	global_load_dwordx4 v[126:129], v[60:61], off offset:128
	global_load_dwordx4 v[122:125], v[170:171], off offset:128
	global_load_dwordx4 v[118:121], v[66:67], off offset:128
	global_load_dwordx4 v[134:137], v[62:63], off offset:128
	global_load_dwordx4 v[130:133], v[64:65], off offset:128
	v_readfirstlane_b32 vcc_lo, v168
	v_readfirstlane_b32 vcc_hi, v169
	v_readfirstlane_b32 s100, v170
	v_readfirstlane_b32 s101, v171
	s_nop 1
	v_subrev_u32_e32 v168, vcc_lo, v168
	v_subrev_u32_e32 v170, s100, v170
	v_mov_b32_e32 v2, 0
	s_mov_b32 s4, 0
	v_mov_b32_e32 v3, v2
	v_mov_b32_e32 v4, v2
	v_mov_b32_e32 v5, v2
	v_mov_b32_e32 v6, v2
	v_mov_b32_e32 v7, v2
	v_mov_b32_e32 v8, v2
	v_mov_b32_e32 v9, v2
	v_mov_b32_e32 v10, v2
	v_mov_b32_e32 v11, v2
	v_mov_b32_e32 v12, v2
	v_mov_b32_e32 v13, v2
	v_mov_b32_e32 v14, v2
	v_mov_b32_e32 v15, v2
	v_mov_b32_e32 v16, v2
	v_mov_b32_e32 v17, v2
	v_mov_b32_e32 v18, v2
	v_mov_b32_e32 v19, v2
	v_mov_b32_e32 v20, v2
	v_mov_b32_e32 v21, v2
	v_mov_b32_e32 v22, v2
	v_mov_b32_e32 v23, v2
	v_mov_b32_e32 v56, v2
	v_mov_b32_e32 v57, v2
	v_mov_b32_e32 v58, v2
	v_mov_b32_e32 v59, v2
	v_mov_b32_e32 v60, v2
	v_mov_b32_e32 v61, v2
	v_mov_b32_e32 v62, v2
	v_mov_b32_e32 v63, v2
	v_mov_b32_e32 v64, v2
	v_mov_b32_e32 v65, v2
	v_mov_b32_e32 v66, v2
	v_mov_b32_e32 v67, v2
	v_mov_b32_e32 v68, v2
	v_mov_b32_e32 v69, v2
	v_mov_b32_e32 v70, v2
	v_mov_b32_e32 v71, v2
	v_mov_b32_e32 v72, v2
	v_mov_b32_e32 v73, v2
	v_mov_b32_e32 v74, v2
	v_mov_b32_e32 v75, v2
	v_mov_b32_e32 v76, v2
	v_mov_b32_e32 v77, v2
	v_mov_b32_e32 v78, v2
	v_mov_b32_e32 v79, v2
	v_mov_b32_e32 v80, v2
	v_mov_b32_e32 v81, v2
	v_mov_b32_e32 v82, v2
	v_mov_b32_e32 v83, v2
	v_mov_b32_e32 v84, v2
	v_mov_b32_e32 v85, v2
	s_waitcnt vmcnt(8)
	ds_write_b128 v166, v[234:237] offset:49152
	ds_write_b128 v166, v[238:241] offset:57344
	ds_write_b128 v166, v[210:213]
	ds_write_b128 v166, v[226:229] offset:32768
	ds_write_b128 v166, v[214:217] offset:8192
	ds_write_b128 v166, v[218:221] offset:16384
	ds_write_b128 v166, v[222:225] offset:24576
	ds_write_b128 v166, v[230:233] offset:40960
	v_mov_b32_e32 v24, v2
	v_mov_b32_e32 v25, v2
	v_mov_b32_e32 v26, v2
	v_mov_b32_e32 v27, v2
	v_mov_b32_e32 v28, v2
	v_mov_b32_e32 v29, v2
	v_mov_b32_e32 v30, v2
	v_mov_b32_e32 v31, v2
	v_mov_b32_e32 v32, v2
	v_mov_b32_e32 v33, v2
	v_mov_b32_e32 v34, v2
	v_mov_b32_e32 v35, v2
	v_mov_b32_e32 v36, v2
	v_mov_b32_e32 v37, v2
	v_mov_b32_e32 v38, v2
	v_mov_b32_e32 v39, v2
	v_mov_b32_e32 v40, v2
	v_mov_b32_e32 v41, v2
	v_mov_b32_e32 v42, v2
	v_mov_b32_e32 v43, v2
	v_mov_b32_e32 v44, v2
	v_mov_b32_e32 v45, v2
	v_mov_b32_e32 v46, v2
	v_mov_b32_e32 v47, v2
	v_mov_b32_e32 v48, v2
	v_mov_b32_e32 v49, v2
	v_mov_b32_e32 v50, v2
	v_mov_b32_e32 v51, v2
	v_mov_b32_e32 v52, v2
	v_mov_b32_e32 v53, v2
	v_mov_b32_e32 v54, v2
	v_mov_b32_e32 v55, v2
	v_mov_b32_e32 v86, v2
	v_mov_b32_e32 v87, v2
	v_mov_b32_e32 v88, v2
	v_mov_b32_e32 v89, v2
	v_mov_b32_e32 v90, v2
	v_mov_b32_e32 v91, v2
	v_mov_b32_e32 v92, v2
	v_mov_b32_e32 v93, v2
	v_mov_b32_e32 v94, v2
	v_mov_b32_e32 v95, v2
	v_mov_b32_e32 v96, v2
	v_mov_b32_e32 v97, v2
	v_mov_b32_e32 v98, v2
	v_mov_b32_e32 v99, v2
	v_mov_b32_e32 v100, v2
	v_mov_b32_e32 v101, v2
	v_mov_b32_e32 v102, v2
	v_mov_b32_e32 v103, v2
	v_mov_b32_e32 v104, v2
	v_mov_b32_e32 v105, v2
	v_mov_b32_e32 v138, v2
	v_mov_b32_e32 v139, v2
	v_mov_b32_e32 v140, v2
	v_mov_b32_e32 v141, v2
	v_mov_b32_e32 v142, v2
	v_mov_b32_e32 v143, v2
	v_mov_b32_e32 v144, v2
	v_mov_b32_e32 v145, v2
	v_mov_b32_e32 v146, v2
	v_mov_b32_e32 v147, v2
	v_mov_b32_e32 v148, v2
	v_mov_b32_e32 v149, v2
	v_mov_b32_e32 v150, v2
	v_mov_b32_e32 v151, v2
	v_mov_b32_e32 v152, v2
	v_mov_b32_e32 v153, v2
	v_mov_b32_e32 v154, v2
	v_mov_b32_e32 v155, v2
	v_mov_b32_e32 v156, v2
	v_mov_b32_e32 v157, v2
	v_mov_b32_e32 v158, v2
	v_mov_b32_e32 v159, v2
	v_mov_b32_e32 v160, v2
	v_mov_b32_e32 v161, v2
	s_waitcnt lgkmcnt(0)
	s_barrier
.LBB0_466:
	s_bitcmp1_b32 s4, 0
	s_cselect_b32 s21, 0x12000, 0
	v_or_b32_e32 v184, s21, v206
	v_add_u32_e32 v185, v184, v0
	v_add_u32_e32 v184, v184, v167
	ds_read_b128 v[210:213], v185
	ds_read_b128 v[226:229], v184 offset:32768
	ds_read_b128 v[214:217], v185 offset:2048
	ds_read_b128 v[218:221], v185 offset:4096
	ds_read_b128 v[222:225], v185 offset:6144
	ds_read_b128 v[230:233], v184 offset:34816
	ds_read_b128 v[234:237], v184 offset:36864
	ds_read_b128 v[238:241], v184 offset:38912
	ds_read_b128 v[242:245], v184 offset:40960
	ds_read_b128 v[246:249], v184 offset:43008
	ds_read_b128 v[198:201], v184 offset:45056
	ds_read_b128 v[184:187], v184 offset:47104
	s_add_i32 s10, s4, 1
	s_bitcmp1_b32 s10, 0
	s_cselect_b32 s23, 0x12000, 0
	v_add_u32_e32 v171, s23, v166
	v_xor_b32_e32 v169, 64, v206
	v_add3_u32 v169, s21, v167, v169
	s_waitcnt lgkmcnt(10)
	v_mfma_f32_16x16x32_bf16 v[158:161], v[226:229], v[210:213], v[158:161]
	s_waitcnt lgkmcnt(9)
	v_mfma_f32_16x16x32_bf16 v[94:97], v[226:229], v[214:217], v[94:97]
	s_waitcnt lgkmcnt(8)
	v_mfma_f32_16x16x32_bf16 v[62:65], v[226:229], v[218:221], v[62:65]
	s_waitcnt lgkmcnt(7)
	v_mfma_f32_16x16x32_bf16 v[30:33], v[226:229], v[222:225], v[30:33]
	ds_read_b128 v[226:229], v169 offset:32768
	s_waitcnt lgkmcnt(7)
	v_mfma_f32_16x16x32_bf16 v[154:157], v[230:233], v[210:213], v[154:157]
	v_mfma_f32_16x16x32_bf16 v[90:93], v[230:233], v[214:217], v[90:93]
	v_mfma_f32_16x16x32_bf16 v[58:61], v[230:233], v[218:221], v[58:61]
	v_mfma_f32_16x16x32_bf16 v[26:29], v[230:233], v[222:225], v[26:29]
	ds_read_b128 v[230:233], v169 offset:34816
	s_waitcnt lgkmcnt(7)
	v_mfma_f32_16x16x32_bf16 v[150:153], v[234:237], v[210:213], v[150:153]
	v_mfma_f32_16x16x32_bf16 v[86:89], v[234:237], v[214:217], v[86:89]
	v_mfma_f32_16x16x32_bf16 v[54:57], v[234:237], v[218:221], v[54:57]
	v_mfma_f32_16x16x32_bf16 v[22:25], v[234:237], v[222:225], v[22:25]
	ds_read_b128 v[234:237], v169 offset:36864
	s_waitcnt lgkmcnt(7)
	v_mfma_f32_16x16x32_bf16 v[146:149], v[238:241], v[210:213], v[146:149]
	v_mfma_f32_16x16x32_bf16 v[82:85], v[238:241], v[214:217], v[82:85]
	v_mfma_f32_16x16x32_bf16 v[50:53], v[238:241], v[218:221], v[50:53]
	v_mfma_f32_16x16x32_bf16 v[18:21], v[238:241], v[222:225], v[18:21]
	ds_read_b128 v[238:241], v169 offset:38912
	s_waitcnt lgkmcnt(7)
	v_mfma_f32_16x16x32_bf16 v[142:145], v[242:245], v[210:213], v[142:145]
	v_mfma_f32_16x16x32_bf16 v[78:81], v[242:245], v[214:217], v[78:81]
	v_mfma_f32_16x16x32_bf16 v[46:49], v[242:245], v[218:221], v[46:49]
	v_mfma_f32_16x16x32_bf16 v[14:17], v[242:245], v[222:225], v[14:17]
	ds_read_b128 v[242:245], v169 offset:40960
	s_waitcnt lgkmcnt(7)
	v_mfma_f32_16x16x32_bf16 v[138:141], v[246:249], v[210:213], v[138:141]
	v_mfma_f32_16x16x32_bf16 v[74:77], v[246:249], v[214:217], v[74:77]
	v_mfma_f32_16x16x32_bf16 v[42:45], v[246:249], v[218:221], v[42:45]
	v_mfma_f32_16x16x32_bf16 v[10:13], v[246:249], v[222:225], v[10:13]
	ds_read_b128 v[246:249], v169 offset:43008
	s_waitcnt lgkmcnt(7)
	v_mfma_f32_16x16x32_bf16 v[102:105], v[198:201], v[210:213], v[102:105]
	v_mfma_f32_16x16x32_bf16 v[70:73], v[198:201], v[214:217], v[70:73]
	v_mfma_f32_16x16x32_bf16 v[38:41], v[198:201], v[218:221], v[38:41]
	v_mfma_f32_16x16x32_bf16 v[6:9], v[198:201], v[222:225], v[6:9]
	ds_read_b128 v[198:201], v169 offset:45056
	s_waitcnt lgkmcnt(7)
	v_mfma_f32_16x16x32_bf16 v[98:101], v[184:187], v[210:213], v[98:101]
	v_mfma_f32_16x16x32_bf16 v[66:69], v[184:187], v[214:217], v[66:69]
	v_xor_b32_e32 v169, 64, v206
	v_add3_u32 v169, s21, v0, v169
	ds_read_b128 v[210:213], v169
	ds_read_b128 v[214:217], v169 offset:2048
	v_mfma_f32_16x16x32_bf16 v[34:37], v[184:187], v[218:221], v[34:37]
	ds_read_b128 v[218:221], v169 offset:4096
	v_mfma_f32_16x16x32_bf16 v[2:5], v[184:187], v[222:225], v[2:5]
	ds_read_b128 v[222:225], v169 offset:6144
	v_xor_b32_e32 v169, 64, v206
	v_add3_u32 v169, s21, v167, v169
	ds_read_b128 v[184:187], v169 offset:47104
	s_waitcnt lgkmcnt(4)
	v_mfma_f32_16x16x32_bf16 v[158:161], v[226:229], v[210:213], v[158:161]
	s_waitcnt lgkmcnt(3)
	v_mfma_f32_16x16x32_bf16 v[94:97], v[226:229], v[214:217], v[94:97]
	s_waitcnt lgkmcnt(2)
	v_mfma_f32_16x16x32_bf16 v[62:65], v[226:229], v[218:221], v[62:65]
	s_waitcnt lgkmcnt(1)
	v_mfma_f32_16x16x32_bf16 v[30:33], v[226:229], v[222:225], v[30:33]
	s_waitcnt vmcnt(7)
	ds_write_b128 v171, v[114:117]
	v_mfma_f32_16x16x32_bf16 v[154:157], v[230:233], v[210:213], v[154:157]
	v_mfma_f32_16x16x32_bf16 v[90:93], v[230:233], v[214:217], v[90:93]
	global_load_dwordx4 v[114:117], v168, vcc offset:256
	v_mfma_f32_16x16x32_bf16 v[58:61], v[230:233], v[218:221], v[58:61]
	v_mfma_f32_16x16x32_bf16 v[26:29], v[230:233], v[222:225], v[26:29]
	s_waitcnt vmcnt(7)
	ds_write_b128 v171, v[106:109] offset:8192
	v_mfma_f32_16x16x32_bf16 v[150:153], v[234:237], v[210:213], v[150:153]
	v_mfma_f32_16x16x32_bf16 v[86:89], v[234:237], v[214:217], v[86:89]
	v_add_u32_e32 v106, s34, v168
	global_load_dwordx4 v[106:109], v106, vcc offset:256
	v_mfma_f32_16x16x32_bf16 v[54:57], v[234:237], v[218:221], v[54:57]
	v_mfma_f32_16x16x32_bf16 v[22:25], v[234:237], v[222:225], v[22:25]
	s_waitcnt vmcnt(7)
	ds_write_b128 v171, v[110:113] offset:16384
	v_mfma_f32_16x16x32_bf16 v[146:149], v[238:241], v[210:213], v[146:149]
	v_mfma_f32_16x16x32_bf16 v[82:85], v[238:241], v[214:217], v[82:85]
	v_add_u32_e32 v110, s35, v168
	global_load_dwordx4 v[110:113], v110, vcc offset:256
	v_mfma_f32_16x16x32_bf16 v[50:53], v[238:241], v[218:221], v[50:53]
	v_mfma_f32_16x16x32_bf16 v[18:21], v[238:241], v[222:225], v[18:21]
	s_waitcnt vmcnt(7)
	ds_write_b128 v171, v[126:129] offset:24576
	v_mfma_f32_16x16x32_bf16 v[142:145], v[242:245], v[210:213], v[142:145]
	v_mfma_f32_16x16x32_bf16 v[78:81], v[242:245], v[214:217], v[78:81]
	v_add_u32_e32 v126, s36, v168
	global_load_dwordx4 v[126:129], v126, vcc offset:256
	v_mfma_f32_16x16x32_bf16 v[46:49], v[242:245], v[218:221], v[46:49]
	v_mfma_f32_16x16x32_bf16 v[14:17], v[242:245], v[222:225], v[14:17]
	s_waitcnt vmcnt(7)
	ds_write_b128 v171, v[122:125] offset:32768
	v_mfma_f32_16x16x32_bf16 v[138:141], v[246:249], v[210:213], v[138:141]
	v_mfma_f32_16x16x32_bf16 v[74:77], v[246:249], v[214:217], v[74:77]
	global_load_dwordx4 v[122:125], v170, s[100:101] offset:256
	v_mfma_f32_16x16x32_bf16 v[42:45], v[246:249], v[218:221], v[42:45]
	v_mfma_f32_16x16x32_bf16 v[10:13], v[246:249], v[222:225], v[10:13]
	s_waitcnt vmcnt(7)
	ds_write_b128 v171, v[118:121] offset:40960
	v_mfma_f32_16x16x32_bf16 v[102:105], v[198:201], v[210:213], v[102:105]
	v_mfma_f32_16x16x32_bf16 v[70:73], v[198:201], v[214:217], v[70:73]
	v_add_u32_e32 v118, s34, v170
	global_load_dwordx4 v[118:121], v118, s[100:101] offset:256
	v_mfma_f32_16x16x32_bf16 v[38:41], v[198:201], v[218:221], v[38:41]
	v_mfma_f32_16x16x32_bf16 v[6:9], v[198:201], v[222:225], v[6:9]
	s_waitcnt vmcnt(7)
	ds_write_b128 v171, v[134:137] offset:49152
	s_waitcnt lgkmcnt(7)
	v_mfma_f32_16x16x32_bf16 v[98:101], v[184:187], v[210:213], v[98:101]
	v_mfma_f32_16x16x32_bf16 v[66:69], v[184:187], v[214:217], v[66:69]
	v_add_u32_e32 v134, s35, v170
	global_load_dwordx4 v[134:137], v134, s[100:101] offset:256
	v_mfma_f32_16x16x32_bf16 v[34:37], v[184:187], v[218:221], v[34:37]
	v_mfma_f32_16x16x32_bf16 v[2:5], v[184:187], v[222:225], v[2:5]
	s_waitcnt vmcnt(7)
	ds_write_b128 v171, v[130:133] offset:57344
	v_add_u32_e32 v130, s36, v170
	global_load_dwordx4 v[130:133], v130, s[100:101] offset:256
	v_add_u32_e32 v168, 0x80, v168
	v_add_u32_e32 v170, 0x80, v170
	s_waitcnt lgkmcnt(0)
	s_barrier
	s_cmp_eq_u32 s10, 16
	s_mov_b32 s4, s10
	s_cbranch_scc0 .LBB0_466
	s_add_i32 m0, s20, s11
	s_cmpk_lt_i32 m0, 0x600
	s_cselect_b32 m0, m0, s20
	s_mul_hi_i32 s101, m0, 0x38e38e39
	s_lshr_b32 vcc_lo, s101, 31
	s_ashr_i32 s101, s101, 4
	s_add_i32 s101, s101, vcc_lo
	s_mul_i32 vcc_lo, s101, 0x48
	s_sub_i32 m0, m0, vcc_lo
	s_lshl_b32 m0, m0, 19
	s_lshl_b32 s101, s101, 19
	v_readfirstlane_b32 vcc_lo, v162
	v_readfirstlane_b32 vcc_hi, v163
	v_and_b32_e32 v242, 7, v172
	v_lshlrev_b32_e32 v242, 4, v242
	v_lshl_add_u32 v242, v204, 11, v242
	s_add_u32 vcc_lo, vcc_lo, m0
	s_addc_u32 vcc_hi, vcc_hi, 0
	s_mov_b32 m0, s101
	v_readfirstlane_b32 s100, v164
	v_readfirstlane_b32 s101, v165
	s_nop 0
	s_add_u32 s100, s100, m0
	s_addc_u32 s101, s101, 0
	global_load_dwordx4 v[210:213], v242, vcc
	v_add_u32_e32 v214, s34, v242
	global_load_dwordx4 v[214:217], v214, vcc
	v_add_u32_e32 v218, s35, v242
	global_load_dwordx4 v[218:221], v218, vcc
	v_add_u32_e32 v222, s36, v242
	global_load_dwordx4 v[222:225], v222, vcc
	global_load_dwordx4 v[226:229], v242, s[100:101]
	v_add_u32_e32 v230, s34, v242
	global_load_dwordx4 v[230:233], v230, s[100:101]
	v_add_u32_e32 v234, s35, v242
	global_load_dwordx4 v[234:237], v234, s[100:101]
	v_add_u32_e32 v238, s36, v242
	global_load_dwordx4 v[238:241], v238, s[100:101]
	s_waitcnt vmcnt(14)
	v_mul_f32_e32 v109, 0xbfb8aa3b, v158
	v_exp_f32_e32 v109, v109
	s_waitcnt vmcnt(13)
	v_mul_f32_e32 v111, 0xbfb8aa3b, v159
	v_exp_f32_e32 v111, v111
	v_mul_f32_e32 v115, 0xbfb8aa3b, v161
	v_add_f32_e32 v109, 1.0, v109
	v_rcp_f32_e32 v114, v109
	v_add_f32_e32 v109, 1.0, v111
	v_mul_f32_e32 v111, 0xbfb8aa3b, v160
	v_exp_f32_e32 v111, v111
	v_exp_f32_e32 v117, v115
	v_rcp_f32_e32 v116, v109
	s_waitcnt vmcnt(10)
	v_mov_b32_e32 v118, v158
	v_add_f32_e32 v109, 1.0, v111
	v_rcp_f32_e32 v115, v109
	v_add_f32_e32 v109, 1.0, v117
	v_rcp_f32_e32 v117, v109
	v_mov_b32_e32 v119, v160
	v_pk_mul_f32 v[114:115], v[118:119], v[114:115]
	v_mov_b32_e32 v118, v154
	v_mov_b32_e32 v119, v156
	v_mov_b32_e32 v160, v159
	v_pk_mul_f32 v[114:115], v[118:119], v[114:115]
	v_pk_mul_f32 v[116:117], v[160:161], v[116:117]
	v_mov_b32_e32 v156, v155
	v_pk_mul_f32 v[116:117], v[156:157], v[116:117]
	v_and_b32_sdwa v111, v115, v177 dst_sel:DWORD dst_unused:UNUSED_PAD src0_sel:WORD_1 src1_sel:DWORD
	v_and_b32_sdwa v118, v114, v177 dst_sel:DWORD dst_unused:UNUSED_PAD src0_sel:WORD_1 src1_sel:DWORD
	v_add3_u32 v111, v115, v111, s28
	v_and_b32_sdwa v115, v117, v177 dst_sel:DWORD dst_unused:UNUSED_PAD src0_sel:WORD_1 src1_sel:DWORD
	v_add3_u32 v114, v114, v118, s28
	v_and_b32_sdwa v118, v116, v177 dst_sel:DWORD dst_unused:UNUSED_PAD src0_sel:WORD_1 src1_sel:DWORD
	v_add3_u32 v115, v117, v115, s28
	v_or_b32_e32 v106, s7, v207
	v_add3_u32 v116, v116, v118, s28
	v_and_b32_e32 v115, 0xffff0000, v115
	v_ashrrev_i32_e32 v106, 1, v106
	v_and_b32_e32 v116, 0xffff0000, v116
	v_or_b32_sdwa v115, v115, v111 dst_sel:DWORD dst_unused:UNUSED_PAD src0_sel:DWORD src1_sel:WORD_1
	v_mul_f32_e32 v111, 0xbfb8aa3b, v150
	v_or_b32_e32 v108, v106, v208
	v_or_b32_sdwa v114, v116, v114 dst_sel:DWORD dst_unused:UNUSED_PAD src0_sel:DWORD src1_sel:WORD_1
	v_exp_f32_e32 v111, v111
	v_mul_f32_e32 v116, 0xbfb8aa3b, v151
	v_add_u32_e32 v110, s6, v205
	v_mov_b64_e32 v[106:107], s[14:15]
	v_ashrrev_i32_e32 v109, 31, v108
	v_exp_f32_e32 v116, v116
	v_mad_i64_i32 v[112:113], s[6:7], v110, s52, v[106:107]
	v_lshlrev_b64 v[108:109], 1, v[108:109]
	v_lshl_add_u64 v[112:113], v[112:113], 0, v[108:109]
	s_waitcnt vmcnt(8)
	global_store_dwordx2 v[112:113], v[114:115], off
	v_add_f32_e32 v111, 1.0, v111
	v_mul_f32_e32 v115, 0xbfb8aa3b, v152
	v_rcp_f32_e32 v114, v111
	v_add_f32_e32 v111, 1.0, v116
	v_exp_f32_e32 v115, v115
	v_mul_f32_e32 v116, 0xbfb8aa3b, v153
	v_exp_f32_e32 v117, v116
	v_rcp_f32_e32 v116, v111
	v_add_f32_e32 v111, 1.0, v115
	v_rcp_f32_e32 v115, v111
	v_add_f32_e32 v111, 1.0, v117
	v_rcp_f32_e32 v117, v111
	v_mov_b32_e32 v118, v150
	v_mov_b32_e32 v119, v152
	v_pk_mul_f32 v[114:115], v[118:119], v[114:115]
	v_mov_b32_e32 v118, v146
	v_mov_b32_e32 v119, v148
	v_mov_b32_e32 v152, v151
	v_pk_mul_f32 v[114:115], v[118:119], v[114:115]
	v_pk_mul_f32 v[116:117], v[152:153], v[116:117]
	v_mov_b32_e32 v148, v147
	v_pk_mul_f32 v[116:117], v[148:149], v[116:117]
	v_and_b32_sdwa v111, v115, v177 dst_sel:DWORD dst_unused:UNUSED_PAD src0_sel:WORD_1 src1_sel:DWORD
	v_and_b32_sdwa v118, v114, v177 dst_sel:DWORD dst_unused:UNUSED_PAD src0_sel:WORD_1 src1_sel:DWORD
	v_add3_u32 v111, v115, v111, s28
	v_and_b32_sdwa v115, v117, v177 dst_sel:DWORD dst_unused:UNUSED_PAD src0_sel:WORD_1 src1_sel:DWORD
	v_add3_u32 v114, v114, v118, s28
	v_and_b32_sdwa v118, v116, v177 dst_sel:DWORD dst_unused:UNUSED_PAD src0_sel:WORD_1 src1_sel:DWORD
	v_add3_u32 v115, v117, v115, s28
	v_add3_u32 v116, v116, v118, s28
	v_and_b32_e32 v115, 0xffff0000, v115
	v_and_b32_e32 v116, 0xffff0000, v116
	v_or_b32_sdwa v115, v115, v111 dst_sel:DWORD dst_unused:UNUSED_PAD src0_sel:DWORD src1_sel:WORD_1
	v_mul_f32_e32 v111, 0xbfb8aa3b, v142
	v_or_b32_sdwa v114, v116, v114 dst_sel:DWORD dst_unused:UNUSED_PAD src0_sel:DWORD src1_sel:WORD_1
	v_exp_f32_e32 v111, v111
	v_mul_f32_e32 v116, 0xbfb8aa3b, v143
	v_exp_f32_e32 v116, v116
	global_store_dwordx2 v[112:113], v[114:115], off offset:32
	v_add_f32_e32 v111, 1.0, v111
	v_mul_f32_e32 v115, 0xbfb8aa3b, v144
	v_rcp_f32_e32 v114, v111
	v_add_f32_e32 v111, 1.0, v116
	v_exp_f32_e32 v115, v115
	v_mul_f32_e32 v116, 0xbfb8aa3b, v145
	v_exp_f32_e32 v117, v116
	v_rcp_f32_e32 v116, v111
	v_add_f32_e32 v111, 1.0, v115
	v_rcp_f32_e32 v115, v111
	v_add_f32_e32 v111, 1.0, v117
	v_rcp_f32_e32 v117, v111
	v_mov_b32_e32 v118, v142
	v_mov_b32_e32 v119, v144
	v_pk_mul_f32 v[114:115], v[118:119], v[114:115]
	v_mov_b32_e32 v118, v138
	v_mov_b32_e32 v119, v140
	v_mov_b32_e32 v144, v143
	v_pk_mul_f32 v[114:115], v[118:119], v[114:115]
	v_pk_mul_f32 v[116:117], v[144:145], v[116:117]
	v_mov_b32_e32 v140, v139
	v_pk_mul_f32 v[116:117], v[140:141], v[116:117]
	v_and_b32_sdwa v111, v115, v177 dst_sel:DWORD dst_unused:UNUSED_PAD src0_sel:WORD_1 src1_sel:DWORD
	v_and_b32_sdwa v118, v114, v177 dst_sel:DWORD dst_unused:UNUSED_PAD src0_sel:WORD_1 src1_sel:DWORD
	v_add3_u32 v111, v115, v111, s28
	v_and_b32_sdwa v115, v117, v177 dst_sel:DWORD dst_unused:UNUSED_PAD src0_sel:WORD_1 src1_sel:DWORD
	v_add3_u32 v114, v114, v118, s28
	v_and_b32_sdwa v118, v116, v177 dst_sel:DWORD dst_unused:UNUSED_PAD src0_sel:WORD_1 src1_sel:DWORD
	v_add3_u32 v115, v117, v115, s28
	v_add3_u32 v116, v116, v118, s28
	v_and_b32_e32 v115, 0xffff0000, v115
	v_and_b32_e32 v116, 0xffff0000, v116
	v_or_b32_sdwa v115, v115, v111 dst_sel:DWORD dst_unused:UNUSED_PAD src0_sel:DWORD src1_sel:WORD_1
	v_mul_f32_e32 v111, 0xbfb8aa3b, v102
	v_or_b32_sdwa v114, v116, v114 dst_sel:DWORD dst_unused:UNUSED_PAD src0_sel:DWORD src1_sel:WORD_1
	v_exp_f32_e32 v111, v111
	v_mul_f32_e32 v116, 0xbfb8aa3b, v103
	v_exp_f32_e32 v116, v116
	global_store_dwordx2 v[112:113], v[114:115], off offset:64
	v_add_f32_e32 v111, 1.0, v111
	v_mul_f32_e32 v115, 0xbfb8aa3b, v104
	v_rcp_f32_e32 v114, v111
	v_add_f32_e32 v111, 1.0, v116
	v_exp_f32_e32 v115, v115
	v_mul_f32_e32 v116, 0xbfb8aa3b, v105
	v_exp_f32_e32 v117, v116
	v_rcp_f32_e32 v116, v111
	v_add_f32_e32 v111, 1.0, v115
	v_rcp_f32_e32 v115, v111
	v_add_f32_e32 v111, 1.0, v117
	v_rcp_f32_e32 v117, v111
	v_mov_b32_e32 v118, v102
	v_mov_b32_e32 v119, v104
	v_mov_b32_e32 v104, v103
	v_pk_mul_f32 v[114:115], v[118:119], v[114:115]
	v_mov_b32_e32 v119, v100
	v_pk_mul_f32 v[102:103], v[104:105], v[116:117]
	v_mov_b32_e32 v100, v99
	v_mov_b32_e32 v118, v98
	v_pk_mul_f32 v[98:99], v[100:101], v[102:103]
	v_pk_mul_f32 v[114:115], v[118:119], v[114:115]
	v_and_b32_sdwa v102, v99, v177 dst_sel:DWORD dst_unused:UNUSED_PAD src0_sel:WORD_1 src1_sel:DWORD
	v_and_b32_sdwa v103, v98, v177 dst_sel:DWORD dst_unused:UNUSED_PAD src0_sel:WORD_1 src1_sel:DWORD
	v_and_b32_sdwa v100, v115, v177 dst_sel:DWORD dst_unused:UNUSED_PAD src0_sel:WORD_1 src1_sel:DWORD
	v_and_b32_sdwa v101, v114, v177 dst_sel:DWORD dst_unused:UNUSED_PAD src0_sel:WORD_1 src1_sel:DWORD
	v_add3_u32 v99, v99, v102, s28
	v_add3_u32 v98, v98, v103, s28
	v_add3_u32 v101, v114, v101, s28
	v_add3_u32 v100, v115, v100, s28
	v_and_b32_e32 v99, 0xffff0000, v99
	v_and_b32_e32 v98, 0xffff0000, v98
	v_or_b32_sdwa v99, v99, v100 dst_sel:DWORD dst_unused:UNUSED_PAD src0_sel:DWORD src1_sel:WORD_1
	v_or_b32_sdwa v98, v98, v101 dst_sel:DWORD dst_unused:UNUSED_PAD src0_sel:DWORD src1_sel:WORD_1
	global_store_dwordx2 v[112:113], v[98:99], off offset:96
	v_mul_f32_e32 v99, 0xbfb8aa3b, v94
	v_exp_f32_e32 v100, v99
	v_mul_f32_e32 v99, 0xbfb8aa3b, v95
	v_mul_f32_e32 v102, 0xbfb8aa3b, v96
	v_exp_f32_e32 v101, v99
	v_exp_f32_e32 v103, v102
	v_mul_f32_e32 v102, 0xbfb8aa3b, v97
	v_exp_f32_e32 v104, v102
	v_add_f32_e32 v101, 1.0, v101
	v_add_f32_e32 v100, 1.0, v100
	v_rcp_f32_e32 v102, v101
	v_add_f32_e32 v101, 1.0, v103
	v_add_f32_e32 v103, 1.0, v104
	v_rcp_f32_e32 v100, v100
	v_rcp_f32_e32 v101, v101
	v_rcp_f32_e32 v103, v103
	v_mov_b32_e32 v104, v94
	v_mov_b32_e32 v105, v96
	v_mov_b32_e32 v96, v95
	v_pk_mul_f32 v[100:101], v[104:105], v[100:101]
	v_mov_b32_e32 v105, v92
	v_pk_mul_f32 v[94:95], v[96:97], v[102:103]
	v_mov_b32_e32 v92, v91
	v_mov_b32_e32 v104, v90
	v_pk_mul_f32 v[90:91], v[92:93], v[94:95]
	v_pk_mul_f32 v[100:101], v[104:105], v[100:101]
	v_and_b32_sdwa v94, v91, v177 dst_sel:DWORD dst_unused:UNUSED_PAD src0_sel:WORD_1 src1_sel:DWORD
	v_and_b32_sdwa v92, v101, v177 dst_sel:DWORD dst_unused:UNUSED_PAD src0_sel:WORD_1 src1_sel:DWORD
	v_and_b32_sdwa v95, v90, v177 dst_sel:DWORD dst_unused:UNUSED_PAD src0_sel:WORD_1 src1_sel:DWORD
	v_add3_u32 v91, v91, v94, s28
	v_and_b32_sdwa v93, v100, v177 dst_sel:DWORD dst_unused:UNUSED_PAD src0_sel:WORD_1 src1_sel:DWORD
	v_add3_u32 v92, v101, v92, s28
	v_add3_u32 v90, v90, v95, s28
	v_and_b32_e32 v91, 0xffff0000, v91
	v_add3_u32 v93, v100, v93, s28
	v_and_b32_e32 v90, 0xffff0000, v90
	v_or_b32_sdwa v91, v91, v92 dst_sel:DWORD dst_unused:UNUSED_PAD src0_sel:DWORD src1_sel:WORD_1
	v_mul_f32_e32 v92, 0xbfb8aa3b, v86
	v_or_b32_sdwa v90, v90, v93 dst_sel:DWORD dst_unused:UNUSED_PAD src0_sel:DWORD src1_sel:WORD_1
	v_exp_f32_e32 v92, v92
	v_mul_f32_e32 v93, 0xbfb8aa3b, v87
	v_or_b32_e32 v98, 16, v110
	v_exp_f32_e32 v93, v93
	v_mad_i64_i32 v[98:99], s[6:7], v98, s52, v[106:107]
	v_lshl_add_u64 v[98:99], v[98:99], 0, v[108:109]
	global_store_dwordx2 v[98:99], v[90:91], off
	v_add_f32_e32 v90, 1.0, v92
	v_mul_f32_e32 v92, 0xbfb8aa3b, v88
	v_add_f32_e32 v91, 1.0, v93
	v_exp_f32_e32 v93, v92
	v_mul_f32_e32 v92, 0xbfb8aa3b, v89
	v_exp_f32_e32 v94, v92
	v_rcp_f32_e32 v92, v91
	v_add_f32_e32 v91, 1.0, v93
	v_rcp_f32_e32 v90, v90
	v_add_f32_e32 v93, 1.0, v94
	v_rcp_f32_e32 v91, v91
	v_rcp_f32_e32 v93, v93
	v_mov_b32_e32 v94, v86
	v_mov_b32_e32 v95, v88
	v_mov_b32_e32 v88, v87
	v_pk_mul_f32 v[90:91], v[94:95], v[90:91]
	v_mov_b32_e32 v95, v84
	v_pk_mul_f32 v[86:87], v[88:89], v[92:93]
	v_mov_b32_e32 v84, v83
	v_mov_b32_e32 v94, v82
	v_pk_mul_f32 v[82:83], v[84:85], v[86:87]
	v_pk_mul_f32 v[90:91], v[94:95], v[90:91]
	v_and_b32_sdwa v86, v83, v177 dst_sel:DWORD dst_unused:UNUSED_PAD src0_sel:WORD_1 src1_sel:DWORD
	v_and_b32_sdwa v84, v91, v177 dst_sel:DWORD dst_unused:UNUSED_PAD src0_sel:WORD_1 src1_sel:DWORD
	v_and_b32_sdwa v87, v82, v177 dst_sel:DWORD dst_unused:UNUSED_PAD src0_sel:WORD_1 src1_sel:DWORD
	v_add3_u32 v83, v83, v86, s28
	v_and_b32_sdwa v85, v90, v177 dst_sel:DWORD dst_unused:UNUSED_PAD src0_sel:WORD_1 src1_sel:DWORD
	v_add3_u32 v84, v91, v84, s28
	v_add3_u32 v82, v82, v87, s28
	v_and_b32_e32 v83, 0xffff0000, v83
	v_add3_u32 v85, v90, v85, s28
	v_and_b32_e32 v82, 0xffff0000, v82
	v_or_b32_sdwa v83, v83, v84 dst_sel:DWORD dst_unused:UNUSED_PAD src0_sel:DWORD src1_sel:WORD_1
	v_mul_f32_e32 v84, 0xbfb8aa3b, v78
	v_or_b32_sdwa v82, v82, v85 dst_sel:DWORD dst_unused:UNUSED_PAD src0_sel:DWORD src1_sel:WORD_1
	v_exp_f32_e32 v84, v84
	v_mul_f32_e32 v85, 0xbfb8aa3b, v79
	v_exp_f32_e32 v85, v85
	global_store_dwordx2 v[98:99], v[82:83], off offset:32
	v_add_f32_e32 v82, 1.0, v84
	v_mul_f32_e32 v84, 0xbfb8aa3b, v80
	v_add_f32_e32 v83, 1.0, v85
	v_exp_f32_e32 v85, v84
	v_mul_f32_e32 v84, 0xbfb8aa3b, v81
	v_exp_f32_e32 v86, v84
	v_rcp_f32_e32 v84, v83
	v_add_f32_e32 v83, 1.0, v85
	v_rcp_f32_e32 v82, v82
	v_add_f32_e32 v85, 1.0, v86
	v_rcp_f32_e32 v83, v83
	v_rcp_f32_e32 v85, v85
	v_mov_b32_e32 v86, v78
	v_mov_b32_e32 v87, v80
	v_mov_b32_e32 v80, v79
	v_pk_mul_f32 v[82:83], v[86:87], v[82:83]
	v_mov_b32_e32 v87, v76
	v_pk_mul_f32 v[78:79], v[80:81], v[84:85]
	v_mov_b32_e32 v76, v75
	v_mov_b32_e32 v86, v74
	v_pk_mul_f32 v[74:75], v[76:77], v[78:79]
	v_pk_mul_f32 v[82:83], v[86:87], v[82:83]
	v_and_b32_sdwa v78, v75, v177 dst_sel:DWORD dst_unused:UNUSED_PAD src0_sel:WORD_1 src1_sel:DWORD
	v_and_b32_sdwa v76, v83, v177 dst_sel:DWORD dst_unused:UNUSED_PAD src0_sel:WORD_1 src1_sel:DWORD
	v_and_b32_sdwa v79, v74, v177 dst_sel:DWORD dst_unused:UNUSED_PAD src0_sel:WORD_1 src1_sel:DWORD
	v_add3_u32 v75, v75, v78, s28
	v_and_b32_sdwa v77, v82, v177 dst_sel:DWORD dst_unused:UNUSED_PAD src0_sel:WORD_1 src1_sel:DWORD
	v_add3_u32 v76, v83, v76, s28
	v_add3_u32 v74, v74, v79, s28
	v_and_b32_e32 v75, 0xffff0000, v75
	v_add3_u32 v77, v82, v77, s28
	v_and_b32_e32 v74, 0xffff0000, v74
	v_or_b32_sdwa v75, v75, v76 dst_sel:DWORD dst_unused:UNUSED_PAD src0_sel:DWORD src1_sel:WORD_1
	v_mul_f32_e32 v76, 0xbfb8aa3b, v70
	v_or_b32_sdwa v74, v74, v77 dst_sel:DWORD dst_unused:UNUSED_PAD src0_sel:DWORD src1_sel:WORD_1
	v_exp_f32_e32 v76, v76
	v_mul_f32_e32 v77, 0xbfb8aa3b, v71
	v_exp_f32_e32 v77, v77
	global_store_dwordx2 v[98:99], v[74:75], off offset:64
	v_add_f32_e32 v74, 1.0, v76
	v_mul_f32_e32 v76, 0xbfb8aa3b, v72
	v_add_f32_e32 v75, 1.0, v77
	v_exp_f32_e32 v77, v76
	v_mul_f32_e32 v76, 0xbfb8aa3b, v73
	v_exp_f32_e32 v78, v76
	v_rcp_f32_e32 v76, v75
	v_add_f32_e32 v75, 1.0, v77
	v_rcp_f32_e32 v74, v74
	v_add_f32_e32 v77, 1.0, v78
	v_rcp_f32_e32 v75, v75
	v_rcp_f32_e32 v77, v77
	v_mov_b32_e32 v78, v70
	v_mov_b32_e32 v79, v72
	v_mov_b32_e32 v72, v71
	v_pk_mul_f32 v[74:75], v[78:79], v[74:75]
	v_mov_b32_e32 v79, v68
	v_pk_mul_f32 v[70:71], v[72:73], v[76:77]
	v_mov_b32_e32 v68, v67
	v_mov_b32_e32 v78, v66
	v_pk_mul_f32 v[66:67], v[68:69], v[70:71]
	v_pk_mul_f32 v[74:75], v[78:79], v[74:75]
	v_and_b32_sdwa v70, v67, v177 dst_sel:DWORD dst_unused:UNUSED_PAD src0_sel:WORD_1 src1_sel:DWORD
	v_and_b32_sdwa v71, v66, v177 dst_sel:DWORD dst_unused:UNUSED_PAD src0_sel:WORD_1 src1_sel:DWORD
	v_and_b32_sdwa v68, v75, v177 dst_sel:DWORD dst_unused:UNUSED_PAD src0_sel:WORD_1 src1_sel:DWORD
	v_and_b32_sdwa v69, v74, v177 dst_sel:DWORD dst_unused:UNUSED_PAD src0_sel:WORD_1 src1_sel:DWORD
	v_add3_u32 v67, v67, v70, s28
	v_add3_u32 v66, v66, v71, s28
	v_add3_u32 v69, v74, v69, s28
	v_add3_u32 v68, v75, v68, s28
	v_and_b32_e32 v67, 0xffff0000, v67
	v_and_b32_e32 v66, 0xffff0000, v66
	v_or_b32_sdwa v67, v67, v68 dst_sel:DWORD dst_unused:UNUSED_PAD src0_sel:DWORD src1_sel:WORD_1
	v_or_b32_sdwa v66, v66, v69 dst_sel:DWORD dst_unused:UNUSED_PAD src0_sel:DWORD src1_sel:WORD_1
	global_store_dwordx2 v[98:99], v[66:67], off offset:96
	v_mul_f32_e32 v67, 0xbfb8aa3b, v62
	v_exp_f32_e32 v68, v67
	v_mul_f32_e32 v67, 0xbfb8aa3b, v63
	v_mul_f32_e32 v70, 0xbfb8aa3b, v64
	v_exp_f32_e32 v69, v67
	v_exp_f32_e32 v71, v70
	v_mul_f32_e32 v70, 0xbfb8aa3b, v65
	v_exp_f32_e32 v72, v70
	v_add_f32_e32 v69, 1.0, v69
	v_add_f32_e32 v68, 1.0, v68
	v_rcp_f32_e32 v70, v69
	v_add_f32_e32 v69, 1.0, v71
	v_add_f32_e32 v71, 1.0, v72
	v_rcp_f32_e32 v68, v68
	v_rcp_f32_e32 v69, v69
	v_rcp_f32_e32 v71, v71
	v_mov_b32_e32 v72, v62
	v_mov_b32_e32 v73, v64
	v_mov_b32_e32 v64, v63
	v_pk_mul_f32 v[68:69], v[72:73], v[68:69]
	v_mov_b32_e32 v73, v60
	v_pk_mul_f32 v[62:63], v[64:65], v[70:71]
	v_mov_b32_e32 v60, v59
	v_mov_b32_e32 v72, v58
	v_pk_mul_f32 v[58:59], v[60:61], v[62:63]
	v_pk_mul_f32 v[68:69], v[72:73], v[68:69]
	v_and_b32_sdwa v62, v59, v177 dst_sel:DWORD dst_unused:UNUSED_PAD src0_sel:WORD_1 src1_sel:DWORD
	v_and_b32_sdwa v60, v69, v177 dst_sel:DWORD dst_unused:UNUSED_PAD src0_sel:WORD_1 src1_sel:DWORD
	v_and_b32_sdwa v63, v58, v177 dst_sel:DWORD dst_unused:UNUSED_PAD src0_sel:WORD_1 src1_sel:DWORD
	v_add3_u32 v59, v59, v62, s28
	v_and_b32_sdwa v61, v68, v177 dst_sel:DWORD dst_unused:UNUSED_PAD src0_sel:WORD_1 src1_sel:DWORD
	v_add3_u32 v60, v69, v60, s28
	v_add3_u32 v58, v58, v63, s28
	v_and_b32_e32 v59, 0xffff0000, v59
	v_add3_u32 v61, v68, v61, s28
	v_and_b32_e32 v58, 0xffff0000, v58
	v_or_b32_sdwa v59, v59, v60 dst_sel:DWORD dst_unused:UNUSED_PAD src0_sel:DWORD src1_sel:WORD_1
	v_mul_f32_e32 v60, 0xbfb8aa3b, v54
	v_or_b32_sdwa v58, v58, v61 dst_sel:DWORD dst_unused:UNUSED_PAD src0_sel:DWORD src1_sel:WORD_1
	v_exp_f32_e32 v60, v60
	v_mul_f32_e32 v61, 0xbfb8aa3b, v55
	v_or_b32_e32 v66, 32, v110
	v_exp_f32_e32 v61, v61
	v_mad_i64_i32 v[66:67], s[6:7], v66, s52, v[106:107]
	v_lshl_add_u64 v[66:67], v[66:67], 0, v[108:109]
	global_store_dwordx2 v[66:67], v[58:59], off
	v_add_f32_e32 v58, 1.0, v60
	v_mul_f32_e32 v60, 0xbfb8aa3b, v56
	v_add_f32_e32 v59, 1.0, v61
	v_exp_f32_e32 v61, v60
	v_mul_f32_e32 v60, 0xbfb8aa3b, v57
	v_exp_f32_e32 v62, v60
	v_rcp_f32_e32 v60, v59
	v_add_f32_e32 v59, 1.0, v61
	v_rcp_f32_e32 v58, v58
	v_add_f32_e32 v61, 1.0, v62
	v_rcp_f32_e32 v59, v59
	v_rcp_f32_e32 v61, v61
	v_mov_b32_e32 v62, v54
	v_mov_b32_e32 v63, v56
	v_mov_b32_e32 v56, v55
	v_pk_mul_f32 v[58:59], v[62:63], v[58:59]
	v_mov_b32_e32 v63, v52
	v_pk_mul_f32 v[54:55], v[56:57], v[60:61]
	v_mov_b32_e32 v52, v51
	v_mov_b32_e32 v62, v50
	v_pk_mul_f32 v[50:51], v[52:53], v[54:55]
	v_pk_mul_f32 v[58:59], v[62:63], v[58:59]
	v_and_b32_sdwa v54, v51, v177 dst_sel:DWORD dst_unused:UNUSED_PAD src0_sel:WORD_1 src1_sel:DWORD
	v_and_b32_sdwa v52, v59, v177 dst_sel:DWORD dst_unused:UNUSED_PAD src0_sel:WORD_1 src1_sel:DWORD
	v_and_b32_sdwa v55, v50, v177 dst_sel:DWORD dst_unused:UNUSED_PAD src0_sel:WORD_1 src1_sel:DWORD
	v_add3_u32 v51, v51, v54, s28
	v_and_b32_sdwa v53, v58, v177 dst_sel:DWORD dst_unused:UNUSED_PAD src0_sel:WORD_1 src1_sel:DWORD
	v_add3_u32 v52, v59, v52, s28
	v_add3_u32 v50, v50, v55, s28
	v_and_b32_e32 v51, 0xffff0000, v51
	v_add3_u32 v53, v58, v53, s28
	v_and_b32_e32 v50, 0xffff0000, v50
	v_or_b32_sdwa v51, v51, v52 dst_sel:DWORD dst_unused:UNUSED_PAD src0_sel:DWORD src1_sel:WORD_1
	v_mul_f32_e32 v52, 0xbfb8aa3b, v46
	v_or_b32_sdwa v50, v50, v53 dst_sel:DWORD dst_unused:UNUSED_PAD src0_sel:DWORD src1_sel:WORD_1
	v_exp_f32_e32 v52, v52
	v_mul_f32_e32 v53, 0xbfb8aa3b, v47
	v_exp_f32_e32 v53, v53
	global_store_dwordx2 v[66:67], v[50:51], off offset:32
	v_add_f32_e32 v50, 1.0, v52
	v_mul_f32_e32 v52, 0xbfb8aa3b, v48
	v_add_f32_e32 v51, 1.0, v53
	v_exp_f32_e32 v53, v52
	v_mul_f32_e32 v52, 0xbfb8aa3b, v49
	v_exp_f32_e32 v54, v52
	v_rcp_f32_e32 v52, v51
	v_add_f32_e32 v51, 1.0, v53
	v_rcp_f32_e32 v50, v50
	v_add_f32_e32 v53, 1.0, v54
	v_rcp_f32_e32 v51, v51
	v_rcp_f32_e32 v53, v53
	v_mov_b32_e32 v54, v46
	v_mov_b32_e32 v55, v48
	v_mov_b32_e32 v48, v47
	v_pk_mul_f32 v[50:51], v[54:55], v[50:51]
	v_mov_b32_e32 v55, v44
	v_pk_mul_f32 v[46:47], v[48:49], v[52:53]
	v_mov_b32_e32 v44, v43
	v_mov_b32_e32 v54, v42
	v_pk_mul_f32 v[42:43], v[44:45], v[46:47]
	v_pk_mul_f32 v[50:51], v[54:55], v[50:51]
	v_and_b32_sdwa v46, v43, v177 dst_sel:DWORD dst_unused:UNUSED_PAD src0_sel:WORD_1 src1_sel:DWORD
	v_and_b32_sdwa v44, v51, v177 dst_sel:DWORD dst_unused:UNUSED_PAD src0_sel:WORD_1 src1_sel:DWORD
	v_and_b32_sdwa v47, v42, v177 dst_sel:DWORD dst_unused:UNUSED_PAD src0_sel:WORD_1 src1_sel:DWORD
	v_add3_u32 v43, v43, v46, s28
	v_and_b32_sdwa v45, v50, v177 dst_sel:DWORD dst_unused:UNUSED_PAD src0_sel:WORD_1 src1_sel:DWORD
	v_add3_u32 v44, v51, v44, s28
	v_add3_u32 v42, v42, v47, s28
	v_and_b32_e32 v43, 0xffff0000, v43
	v_add3_u32 v45, v50, v45, s28
	v_and_b32_e32 v42, 0xffff0000, v42
	v_or_b32_sdwa v43, v43, v44 dst_sel:DWORD dst_unused:UNUSED_PAD src0_sel:DWORD src1_sel:WORD_1
	v_mul_f32_e32 v44, 0xbfb8aa3b, v38
	v_or_b32_sdwa v42, v42, v45 dst_sel:DWORD dst_unused:UNUSED_PAD src0_sel:DWORD src1_sel:WORD_1
	v_exp_f32_e32 v44, v44
	v_mul_f32_e32 v45, 0xbfb8aa3b, v39
	v_exp_f32_e32 v45, v45
	global_store_dwordx2 v[66:67], v[42:43], off offset:64
	v_add_f32_e32 v42, 1.0, v44
	v_mul_f32_e32 v44, 0xbfb8aa3b, v40
	v_add_f32_e32 v43, 1.0, v45
	v_exp_f32_e32 v45, v44
	v_mul_f32_e32 v44, 0xbfb8aa3b, v41
	v_exp_f32_e32 v46, v44
	v_rcp_f32_e32 v44, v43
	v_add_f32_e32 v43, 1.0, v45
	v_rcp_f32_e32 v42, v42
	v_add_f32_e32 v45, 1.0, v46
	v_rcp_f32_e32 v43, v43
	v_rcp_f32_e32 v45, v45
	v_mov_b32_e32 v46, v38
	v_mov_b32_e32 v47, v40
	v_mov_b32_e32 v40, v39
	v_pk_mul_f32 v[42:43], v[46:47], v[42:43]
	v_mov_b32_e32 v47, v36
	v_pk_mul_f32 v[38:39], v[40:41], v[44:45]
	v_mov_b32_e32 v36, v35
	v_mov_b32_e32 v46, v34
	v_pk_mul_f32 v[34:35], v[36:37], v[38:39]
	v_pk_mul_f32 v[42:43], v[46:47], v[42:43]
	v_and_b32_sdwa v38, v35, v177 dst_sel:DWORD dst_unused:UNUSED_PAD src0_sel:WORD_1 src1_sel:DWORD
	v_and_b32_sdwa v39, v34, v177 dst_sel:DWORD dst_unused:UNUSED_PAD src0_sel:WORD_1 src1_sel:DWORD
	v_and_b32_sdwa v36, v43, v177 dst_sel:DWORD dst_unused:UNUSED_PAD src0_sel:WORD_1 src1_sel:DWORD
	v_and_b32_sdwa v37, v42, v177 dst_sel:DWORD dst_unused:UNUSED_PAD src0_sel:WORD_1 src1_sel:DWORD
	v_add3_u32 v35, v35, v38, s28
	v_add3_u32 v34, v34, v39, s28
	v_add3_u32 v37, v42, v37, s28
	v_add3_u32 v36, v43, v36, s28
	v_and_b32_e32 v35, 0xffff0000, v35
	v_and_b32_e32 v34, 0xffff0000, v34
	v_or_b32_sdwa v35, v35, v36 dst_sel:DWORD dst_unused:UNUSED_PAD src0_sel:DWORD src1_sel:WORD_1
	v_or_b32_sdwa v34, v34, v37 dst_sel:DWORD dst_unused:UNUSED_PAD src0_sel:DWORD src1_sel:WORD_1
	global_store_dwordx2 v[66:67], v[34:35], off offset:96
	v_mul_f32_e32 v35, 0xbfb8aa3b, v30
	v_exp_f32_e32 v36, v35
	v_mul_f32_e32 v35, 0xbfb8aa3b, v31
	v_mul_f32_e32 v38, 0xbfb8aa3b, v32
	v_exp_f32_e32 v37, v35
	v_exp_f32_e32 v39, v38
	v_mul_f32_e32 v38, 0xbfb8aa3b, v33
	v_exp_f32_e32 v40, v38
	v_add_f32_e32 v37, 1.0, v37
	v_add_f32_e32 v36, 1.0, v36
	v_rcp_f32_e32 v38, v37
	v_add_f32_e32 v37, 1.0, v39
	v_add_f32_e32 v39, 1.0, v40
	v_rcp_f32_e32 v36, v36
	v_rcp_f32_e32 v37, v37
	v_rcp_f32_e32 v39, v39
	v_mov_b32_e32 v40, v30
	v_mov_b32_e32 v41, v32
	v_mov_b32_e32 v32, v31
	v_pk_mul_f32 v[36:37], v[40:41], v[36:37]
	v_mov_b32_e32 v41, v28
	v_pk_mul_f32 v[30:31], v[32:33], v[38:39]
	v_mov_b32_e32 v28, v27
	v_mov_b32_e32 v40, v26
	v_pk_mul_f32 v[26:27], v[28:29], v[30:31]
	v_pk_mul_f32 v[36:37], v[40:41], v[36:37]
	v_and_b32_sdwa v30, v27, v177 dst_sel:DWORD dst_unused:UNUSED_PAD src0_sel:WORD_1 src1_sel:DWORD
	v_and_b32_sdwa v28, v37, v177 dst_sel:DWORD dst_unused:UNUSED_PAD src0_sel:WORD_1 src1_sel:DWORD
	v_and_b32_sdwa v31, v26, v177 dst_sel:DWORD dst_unused:UNUSED_PAD src0_sel:WORD_1 src1_sel:DWORD
	v_add3_u32 v27, v27, v30, s28
	v_and_b32_sdwa v29, v36, v177 dst_sel:DWORD dst_unused:UNUSED_PAD src0_sel:WORD_1 src1_sel:DWORD
	v_add3_u32 v28, v37, v28, s28
	v_add3_u32 v26, v26, v31, s28
	v_and_b32_e32 v27, 0xffff0000, v27
	v_add3_u32 v29, v36, v29, s28
	v_and_b32_e32 v26, 0xffff0000, v26
	v_or_b32_sdwa v27, v27, v28 dst_sel:DWORD dst_unused:UNUSED_PAD src0_sel:DWORD src1_sel:WORD_1
	v_mul_f32_e32 v28, 0xbfb8aa3b, v22
	v_or_b32_sdwa v26, v26, v29 dst_sel:DWORD dst_unused:UNUSED_PAD src0_sel:DWORD src1_sel:WORD_1
	v_exp_f32_e32 v28, v28
	v_mul_f32_e32 v29, 0xbfb8aa3b, v23
	v_or_b32_e32 v34, 48, v110
	v_exp_f32_e32 v29, v29
	v_mad_i64_i32 v[34:35], s[6:7], v34, s52, v[106:107]
	v_lshl_add_u64 v[34:35], v[34:35], 0, v[108:109]
	global_store_dwordx2 v[34:35], v[26:27], off
	v_add_f32_e32 v26, 1.0, v28
	v_mul_f32_e32 v28, 0xbfb8aa3b, v24
	v_add_f32_e32 v27, 1.0, v29
	v_exp_f32_e32 v29, v28
	v_mul_f32_e32 v28, 0xbfb8aa3b, v25
	v_exp_f32_e32 v30, v28
	v_rcp_f32_e32 v28, v27
	v_add_f32_e32 v27, 1.0, v29
	v_rcp_f32_e32 v26, v26
	v_add_f32_e32 v29, 1.0, v30
	v_rcp_f32_e32 v27, v27
	v_rcp_f32_e32 v29, v29
	v_mov_b32_e32 v30, v22
	v_mov_b32_e32 v31, v24
	v_mov_b32_e32 v24, v23
	v_pk_mul_f32 v[26:27], v[30:31], v[26:27]
	v_mov_b32_e32 v31, v20
	v_pk_mul_f32 v[22:23], v[24:25], v[28:29]
	v_mov_b32_e32 v20, v19
	v_mov_b32_e32 v30, v18
	v_pk_mul_f32 v[18:19], v[20:21], v[22:23]
	v_pk_mul_f32 v[26:27], v[30:31], v[26:27]
	v_and_b32_sdwa v22, v19, v177 dst_sel:DWORD dst_unused:UNUSED_PAD src0_sel:WORD_1 src1_sel:DWORD
	v_and_b32_sdwa v20, v27, v177 dst_sel:DWORD dst_unused:UNUSED_PAD src0_sel:WORD_1 src1_sel:DWORD
	v_and_b32_sdwa v23, v18, v177 dst_sel:DWORD dst_unused:UNUSED_PAD src0_sel:WORD_1 src1_sel:DWORD
	v_add3_u32 v19, v19, v22, s28
	v_and_b32_sdwa v21, v26, v177 dst_sel:DWORD dst_unused:UNUSED_PAD src0_sel:WORD_1 src1_sel:DWORD
	v_add3_u32 v20, v27, v20, s28
	v_add3_u32 v18, v18, v23, s28
	v_and_b32_e32 v19, 0xffff0000, v19
	v_add3_u32 v21, v26, v21, s28
	v_and_b32_e32 v18, 0xffff0000, v18
	v_or_b32_sdwa v19, v19, v20 dst_sel:DWORD dst_unused:UNUSED_PAD src0_sel:DWORD src1_sel:WORD_1
	v_mul_f32_e32 v20, 0xbfb8aa3b, v14
	v_or_b32_sdwa v18, v18, v21 dst_sel:DWORD dst_unused:UNUSED_PAD src0_sel:DWORD src1_sel:WORD_1
	v_exp_f32_e32 v20, v20
	v_mul_f32_e32 v21, 0xbfb8aa3b, v15
	v_exp_f32_e32 v21, v21
	global_store_dwordx2 v[34:35], v[18:19], off offset:32
	v_add_f32_e32 v18, 1.0, v20
	v_mul_f32_e32 v20, 0xbfb8aa3b, v16
	v_add_f32_e32 v19, 1.0, v21
	v_exp_f32_e32 v21, v20
	v_mul_f32_e32 v20, 0xbfb8aa3b, v17
	v_exp_f32_e32 v22, v20
	v_rcp_f32_e32 v20, v19
	v_add_f32_e32 v19, 1.0, v21
	v_rcp_f32_e32 v18, v18
	v_add_f32_e32 v21, 1.0, v22
	v_rcp_f32_e32 v19, v19
	v_rcp_f32_e32 v21, v21
	v_mov_b32_e32 v22, v14
	v_mov_b32_e32 v23, v16
	v_mov_b32_e32 v16, v15
	v_pk_mul_f32 v[18:19], v[22:23], v[18:19]
	v_mov_b32_e32 v23, v12
	v_pk_mul_f32 v[14:15], v[16:17], v[20:21]
	v_mov_b32_e32 v12, v11
	v_mov_b32_e32 v22, v10
	v_pk_mul_f32 v[10:11], v[12:13], v[14:15]
	v_pk_mul_f32 v[18:19], v[22:23], v[18:19]
	v_and_b32_sdwa v14, v11, v177 dst_sel:DWORD dst_unused:UNUSED_PAD src0_sel:WORD_1 src1_sel:DWORD
	v_and_b32_sdwa v12, v19, v177 dst_sel:DWORD dst_unused:UNUSED_PAD src0_sel:WORD_1 src1_sel:DWORD
	v_and_b32_sdwa v15, v10, v177 dst_sel:DWORD dst_unused:UNUSED_PAD src0_sel:WORD_1 src1_sel:DWORD
	v_add3_u32 v11, v11, v14, s28
	v_and_b32_sdwa v13, v18, v177 dst_sel:DWORD dst_unused:UNUSED_PAD src0_sel:WORD_1 src1_sel:DWORD
	v_add3_u32 v12, v19, v12, s28
	v_add3_u32 v10, v10, v15, s28
	v_and_b32_e32 v11, 0xffff0000, v11
	v_add3_u32 v13, v18, v13, s28
	v_and_b32_e32 v10, 0xffff0000, v10
	v_or_b32_sdwa v11, v11, v12 dst_sel:DWORD dst_unused:UNUSED_PAD src0_sel:DWORD src1_sel:WORD_1
	v_mul_f32_e32 v12, 0xbfb8aa3b, v6
	v_or_b32_sdwa v10, v10, v13 dst_sel:DWORD dst_unused:UNUSED_PAD src0_sel:DWORD src1_sel:WORD_1
	v_exp_f32_e32 v12, v12
	v_mul_f32_e32 v13, 0xbfb8aa3b, v7
	v_exp_f32_e32 v13, v13
	global_store_dwordx2 v[34:35], v[10:11], off offset:64
	v_add_f32_e32 v10, 1.0, v12
	v_mul_f32_e32 v12, 0xbfb8aa3b, v8
	v_add_f32_e32 v11, 1.0, v13
	v_exp_f32_e32 v13, v12
	v_mul_f32_e32 v12, 0xbfb8aa3b, v9
	v_exp_f32_e32 v14, v12
	v_rcp_f32_e32 v12, v11
	v_add_f32_e32 v11, 1.0, v13
	v_rcp_f32_e32 v10, v10
	v_add_f32_e32 v13, 1.0, v14
	v_rcp_f32_e32 v11, v11
	v_rcp_f32_e32 v13, v13
	v_mov_b32_e32 v14, v6
	v_mov_b32_e32 v15, v8
	v_mov_b32_e32 v8, v7
	v_pk_mul_f32 v[10:11], v[14:15], v[10:11]
	v_mov_b32_e32 v15, v4
	v_pk_mul_f32 v[6:7], v[8:9], v[12:13]
	v_mov_b32_e32 v4, v3
	v_mov_b32_e32 v14, v2
	v_pk_mul_f32 v[2:3], v[4:5], v[6:7]
	v_pk_mul_f32 v[10:11], v[14:15], v[10:11]
	v_and_b32_sdwa v6, v3, v177 dst_sel:DWORD dst_unused:UNUSED_PAD src0_sel:WORD_1 src1_sel:DWORD
	v_and_b32_sdwa v7, v2, v177 dst_sel:DWORD dst_unused:UNUSED_PAD src0_sel:WORD_1 src1_sel:DWORD
	v_and_b32_sdwa v4, v11, v177 dst_sel:DWORD dst_unused:UNUSED_PAD src0_sel:WORD_1 src1_sel:DWORD
	v_and_b32_sdwa v5, v10, v177 dst_sel:DWORD dst_unused:UNUSED_PAD src0_sel:WORD_1 src1_sel:DWORD
	v_add3_u32 v3, v3, v6, s28
	v_add3_u32 v2, v2, v7, s28
	v_add3_u32 v5, v10, v5, s28
	v_add3_u32 v4, v11, v4, s28
	v_and_b32_e32 v3, 0xffff0000, v3
	v_and_b32_e32 v2, 0xffff0000, v2
	s_add_i32 s20, s20, s11
	v_or_b32_sdwa v3, v3, v4 dst_sel:DWORD dst_unused:UNUSED_PAD src0_sel:DWORD src1_sel:WORD_1
	v_or_b32_sdwa v2, v2, v5 dst_sel:DWORD dst_unused:UNUSED_PAD src0_sel:DWORD src1_sel:WORD_1
	s_cmpk_gt_i32 s20, 0x5ff
	global_store_dwordx2 v[34:35], v[2:3], off offset:96
	s_cbranch_scc0 .LBB0_465

.LBB0_662:
	s_or_b64 exec, exec, s[12:13]
	s_mov_b64 s[12:13], s[60:61]
	s_waitcnt lgkmcnt(0)
	v_mov_b32_e32 v2, v172
	s_mov_b32 s10, s42
	s_mov_b32 s11, s94
	s_barrier
	s_cmpk_lt_i32 s11, 0x3f0
	s_mov_b32 s42, 0xffff0000
	s_mov_b32 s94, 0x3f200000
	s_cbranch_scc0 .LBB0_667
	s_load_dwordx2 s[6:7], s[12:13], 0x130
	v_lshlrev_b32_e32 v0, 4, v2
	v_and_b32_e32 v0, 0x70, v0
	s_mov_b64 s[2:3], 0x3200000
	v_ashrrev_i32_e32 v204, 3, v2
	s_waitcnt lgkmcnt(0)
	s_add_u32 s12, s6, 0x6035800
	s_addc_u32 s13, s7, 0
	v_lshl_add_u64 v[4:5], s[6:7], 0, v[0:1]
	s_mov_b64 s[6:7], 0x2100000
	v_bfe_u32 v3, v2, 4, 2
	v_and_b32_e32 v6, 15, v2
	v_lshl_add_u64 v[162:163], v[4:5], 0, s[2:3]
	v_lshl_add_u64 v[164:165], v[4:5], 0, s[6:7]
	v_ashrrev_i32_e32 v4, 1, v2
	s_movk_i32 s2, 0xffc0
	v_lshlrev_b32_e32 v2, 1, v2
	v_and_or_b32 v205, v4, s2, v6
	v_and_b32_e32 v2, 0x80, v2
	s_movk_i32 s2, 0x90
	v_or_b32_e32 v4, v2, v6
	v_and_b32_e32 v100, 7, v204
	v_lshlrev_b32_e32 v100, 4, v100
	v_xor_b32_e32 v100, v100, v0
	v_lshl_add_u32 v166, v204, 7, v100
	v_and_b32_e32 v100, 7, v6
	v_xor_b32_e32 v100, v100, v3
	v_lshlrev_b32_e32 v206, 4, v100
	v_lshl_or_b32 v207, v3, 2, v2
	v_lshlrev_b32_e32 v0, 7, v205
	v_lshlrev_b32_e32 v167, 7, v4
	s_mov_b32 m0, s11
	s_mul_hi_i32 s101, m0, 0x38e38e39
	s_lshr_b32 vcc_lo, s101, 31
	s_ashr_i32 s101, s101, 4
	s_add_i32 s101, s101, vcc_lo
	s_mul_i32 vcc_lo, s101, 0x48
	s_sub_i32 m0, m0, vcc_lo
	s_lshl_b32 m0, m0, 19
	s_lshl_b32 s101, s101, 19
	v_readfirstlane_b32 vcc_lo, v162
	v_readfirstlane_b32 vcc_hi, v163
	v_and_b32_e32 v242, 7, v172
	v_lshlrev_b32_e32 v242, 4, v242
	v_lshl_add_u32 v242, v204, 11, v242
	s_add_u32 vcc_lo, vcc_lo, m0
	s_addc_u32 vcc_hi, vcc_hi, 0
	s_mov_b32 m0, s101
	v_readfirstlane_b32 s100, v164
	v_readfirstlane_b32 s101, v165
	s_nop 0
	s_add_u32 s100, s100, m0
	s_addc_u32 s101, s101, 0
	global_load_dwordx4 v[210:213], v242, vcc
	v_add_u32_e32 v214, s34, v242
	global_load_dwordx4 v[214:217], v214, vcc
	v_add_u32_e32 v218, s35, v242
	global_load_dwordx4 v[218:221], v218, vcc
	v_add_u32_e32 v222, s36, v242
	global_load_dwordx4 v[222:225], v222, vcc
	global_load_dwordx4 v[226:229], v242, s[100:101]
	v_add_u32_e32 v230, s34, v242
	global_load_dwordx4 v[230:233], v230, s[100:101]
	v_add_u32_e32 v234, s35, v242
	global_load_dwordx4 v[234:237], v234, s[100:101]
	v_add_u32_e32 v238, s36, v242
	global_load_dwordx4 v[238:241], v238, s[100:101]
.LBB0_664:
	s_mul_hi_i32 s4, s11, 0x38e38e39
	s_lshr_b32 s6, s4, 31
	s_ashr_i32 s4, s4, 4
	s_add_i32 s4, s4, s6
	s_mul_i32 s6, s4, 0x48
	s_sub_i32 s6, s11, s6
	s_lshl_b32 s6, s6, 8
	v_add_u32_e32 v2, s6, v204
	v_ashrrev_i32_e32 v3, 31, v2
	v_lshlrev_b64 v[2:3], 11, v[2:3]
	v_lshl_add_u64 v[168:169], v[162:163], 0, v[2:3]
	v_add_co_u32_e32 v56, vcc, s34, v168
	s_lshl_b32 s7, s4, 8
	s_nop 0
	v_addc_co_u32_e32 v57, vcc, 0, v169, vcc
	v_add_u32_e32 v2, s7, v204
	v_add_co_u32_e32 v58, vcc, s35, v168
	v_ashrrev_i32_e32 v3, 31, v2
	s_nop 0
	v_addc_co_u32_e32 v59, vcc, 0, v169, vcc
	v_lshlrev_b64 v[2:3], 11, v[2:3]
	v_add_co_u32_e32 v60, vcc, s36, v168
	v_lshl_add_u64 v[170:171], v[164:165], 0, v[2:3]
	s_nop 0
	v_addc_co_u32_e32 v61, vcc, 0, v169, vcc
	v_add_co_u32_e32 v62, vcc, s35, v170
	s_nop 1
	s_nop 1
	v_addc_co_u32_e32 v63, vcc, 0, v171, vcc
	v_add_co_u32_e32 v64, vcc, s36, v170
	s_nop 1
	s_nop 1
	v_addc_co_u32_e32 v65, vcc, 0, v171, vcc
	v_add_co_u32_e32 v66, vcc, s34, v170
	s_nop 1
	s_nop 1
	v_addc_co_u32_e32 v67, vcc, 0, v171, vcc
	s_nop 1
	s_nop 1
	s_barrier
	global_load_dwordx4 v[94:97], v[168:169], off offset:128
	global_load_dwordx4 v[86:89], v[56:57], off offset:128
	global_load_dwordx4 v[90:93], v[58:59], off offset:128
	global_load_dwordx4 v[106:109], v[60:61], off offset:128
	global_load_dwordx4 v[102:105], v[170:171], off offset:128
	global_load_dwordx4 v[98:101], v[66:67], off offset:128
	global_load_dwordx4 v[118:121], v[62:63], off offset:128
	global_load_dwordx4 v[110:113], v[64:65], off offset:128
	v_readfirstlane_b32 vcc_lo, v168
	v_readfirstlane_b32 vcc_hi, v169
	v_readfirstlane_b32 s100, v170
	v_readfirstlane_b32 s101, v171
	s_nop 1
	v_subrev_u32_e32 v168, vcc_lo, v168
	v_subrev_u32_e32 v170, s100, v170
	v_mov_b32_e32 v2, 0
	s_mov_b32 s4, 0
	v_mov_b32_e32 v3, v2
	v_mov_b32_e32 v4, v2
	v_mov_b32_e32 v5, v2
	v_mov_b32_e32 v6, v2
	v_mov_b32_e32 v7, v2
	v_mov_b32_e32 v8, v2
	v_mov_b32_e32 v9, v2
	v_mov_b32_e32 v10, v2
	v_mov_b32_e32 v11, v2
	v_mov_b32_e32 v12, v2
	v_mov_b32_e32 v13, v2
	v_mov_b32_e32 v14, v2
	v_mov_b32_e32 v15, v2
	v_mov_b32_e32 v16, v2
	v_mov_b32_e32 v17, v2
	v_mov_b32_e32 v18, v2
	v_mov_b32_e32 v19, v2
	v_mov_b32_e32 v20, v2
	v_mov_b32_e32 v21, v2
	v_mov_b32_e32 v22, v2
	v_mov_b32_e32 v23, v2
	v_mov_b32_e32 v56, v2
	v_mov_b32_e32 v57, v2
	v_mov_b32_e32 v58, v2
	v_mov_b32_e32 v59, v2
	v_mov_b32_e32 v60, v2
	v_mov_b32_e32 v61, v2
	v_mov_b32_e32 v66, v2
	v_mov_b32_e32 v67, v2
	v_mov_b32_e32 v68, v2
	v_mov_b32_e32 v69, v2
	v_mov_b32_e32 v62, v2
	v_mov_b32_e32 v63, v2
	v_mov_b32_e32 v64, v2
	v_mov_b32_e32 v65, v2
	v_mov_b32_e32 v70, v2
	v_mov_b32_e32 v71, v2
	v_mov_b32_e32 v72, v2
	v_mov_b32_e32 v73, v2
	v_mov_b32_e32 v74, v2
	v_mov_b32_e32 v75, v2
	v_mov_b32_e32 v76, v2
	v_mov_b32_e32 v77, v2
	v_mov_b32_e32 v78, v2
	v_mov_b32_e32 v79, v2
	v_mov_b32_e32 v80, v2
	v_mov_b32_e32 v81, v2
	v_mov_b32_e32 v82, v2
	v_mov_b32_e32 v83, v2
	v_mov_b32_e32 v84, v2
	v_mov_b32_e32 v85, v2
	s_waitcnt vmcnt(8)
	ds_write_b128 v166, v[234:237] offset:49152
	ds_write_b128 v166, v[238:241] offset:57344
	ds_write_b128 v166, v[210:213]
	ds_write_b128 v166, v[226:229] offset:32768
	ds_write_b128 v166, v[214:217] offset:8192
	ds_write_b128 v166, v[218:221] offset:16384
	ds_write_b128 v166, v[222:225] offset:24576
	ds_write_b128 v166, v[230:233] offset:40960
	v_mov_b32_e32 v24, v2
	v_mov_b32_e32 v25, v2
	v_mov_b32_e32 v26, v2
	v_mov_b32_e32 v27, v2
	v_mov_b32_e32 v28, v2
	v_mov_b32_e32 v29, v2
	v_mov_b32_e32 v34, v2
	v_mov_b32_e32 v35, v2
	v_mov_b32_e32 v36, v2
	v_mov_b32_e32 v37, v2
	v_mov_b32_e32 v30, v2
	v_mov_b32_e32 v31, v2
	v_mov_b32_e32 v32, v2
	v_mov_b32_e32 v33, v2
	v_mov_b32_e32 v38, v2
	v_mov_b32_e32 v39, v2
	v_mov_b32_e32 v40, v2
	v_mov_b32_e32 v41, v2
	v_mov_b32_e32 v42, v2
	v_mov_b32_e32 v43, v2
	v_mov_b32_e32 v44, v2
	v_mov_b32_e32 v45, v2
	v_mov_b32_e32 v46, v2
	v_mov_b32_e32 v47, v2
	v_mov_b32_e32 v48, v2
	v_mov_b32_e32 v49, v2
	v_mov_b32_e32 v50, v2
	v_mov_b32_e32 v51, v2
	v_mov_b32_e32 v52, v2
	v_mov_b32_e32 v53, v2
	v_mov_b32_e32 v54, v2
	v_mov_b32_e32 v55, v2
	v_mov_b32_e32 v114, v2
	v_mov_b32_e32 v115, v2
	v_mov_b32_e32 v116, v2
	v_mov_b32_e32 v117, v2
	v_mov_b32_e32 v122, v2
	v_mov_b32_e32 v123, v2
	v_mov_b32_e32 v124, v2
	v_mov_b32_e32 v125, v2
	v_mov_b32_e32 v130, v2
	v_mov_b32_e32 v131, v2
	v_mov_b32_e32 v132, v2
	v_mov_b32_e32 v133, v2
	v_mov_b32_e32 v126, v2
	v_mov_b32_e32 v127, v2
	v_mov_b32_e32 v128, v2
	v_mov_b32_e32 v129, v2
	v_mov_b32_e32 v134, v2
	v_mov_b32_e32 v135, v2
	v_mov_b32_e32 v136, v2
	v_mov_b32_e32 v137, v2
	v_mov_b32_e32 v138, v2
	v_mov_b32_e32 v139, v2
	v_mov_b32_e32 v140, v2
	v_mov_b32_e32 v141, v2
	v_mov_b32_e32 v142, v2
	v_mov_b32_e32 v143, v2
	v_mov_b32_e32 v144, v2
	v_mov_b32_e32 v145, v2
	v_mov_b32_e32 v146, v2
	v_mov_b32_e32 v147, v2
	v_mov_b32_e32 v148, v2
	v_mov_b32_e32 v149, v2
	v_mov_b32_e32 v150, v2
	v_mov_b32_e32 v151, v2
	v_mov_b32_e32 v152, v2
	v_mov_b32_e32 v153, v2
	v_mov_b32_e32 v154, v2
	v_mov_b32_e32 v155, v2
	v_mov_b32_e32 v156, v2
	v_mov_b32_e32 v157, v2
	v_mov_b32_e32 v158, v2
	v_mov_b32_e32 v159, v2
	v_mov_b32_e32 v160, v2
	v_mov_b32_e32 v161, v2
	s_waitcnt lgkmcnt(0)
	s_barrier
.LBB0_665:
	s_bitcmp1_b32 s4, 0
	s_cselect_b32 s15, 0x12000, 0
	v_or_b32_e32 v208, s15, v206
	v_add_u32_e32 v214, v208, v0
	v_add_u32_e32 v208, v208, v167
	ds_read_b128 v[184:187], v214
	ds_read_b128 v[218:221], v208 offset:32768
	ds_read_b128 v[198:201], v214 offset:2048
	ds_read_b128 v[210:213], v214 offset:4096
	ds_read_b128 v[214:217], v214 offset:6144
	ds_read_b128 v[222:225], v208 offset:34816
	ds_read_b128 v[226:229], v208 offset:36864
	ds_read_b128 v[230:233], v208 offset:38912
	ds_read_b128 v[234:237], v208 offset:40960
	ds_read_b128 v[238:241], v208 offset:43008
	ds_read_b128 v[242:245], v208 offset:45056
	ds_read_b128 v[246:249], v208 offset:47104
	s_add_i32 s14, s4, 1
	s_bitcmp1_b32 s14, 0
	s_cselect_b32 s16, 0x12000, 0
	v_add_u32_e32 v208, s16, v166
	v_add_u32_e32 v171, s16, v166
	v_xor_b32_e32 v169, 64, v206
	v_add3_u32 v169, s15, v167, v169
	s_waitcnt lgkmcnt(10)
	v_mfma_f32_16x16x32_bf16 v[158:161], v[218:221], v[184:187], v[158:161]
	s_waitcnt lgkmcnt(9)
	v_mfma_f32_16x16x32_bf16 v[130:133], v[218:221], v[198:201], v[130:133]
	s_waitcnt lgkmcnt(8)
	v_mfma_f32_16x16x32_bf16 v[66:69], v[218:221], v[210:213], v[66:69]
	s_waitcnt lgkmcnt(7)
	v_mfma_f32_16x16x32_bf16 v[34:37], v[218:221], v[214:217], v[34:37]
	ds_read_b128 v[218:221], v169 offset:32768
	s_waitcnt lgkmcnt(7)
	v_mfma_f32_16x16x32_bf16 v[154:157], v[222:225], v[184:187], v[154:157]
	v_mfma_f32_16x16x32_bf16 v[122:125], v[222:225], v[198:201], v[122:125]
	v_mfma_f32_16x16x32_bf16 v[58:61], v[222:225], v[210:213], v[58:61]
	v_mfma_f32_16x16x32_bf16 v[26:29], v[222:225], v[214:217], v[26:29]
	ds_read_b128 v[222:225], v169 offset:34816
	s_waitcnt lgkmcnt(7)
	v_mfma_f32_16x16x32_bf16 v[150:153], v[226:229], v[184:187], v[150:153]
	v_mfma_f32_16x16x32_bf16 v[114:117], v[226:229], v[198:201], v[114:117]
	v_mfma_f32_16x16x32_bf16 v[54:57], v[226:229], v[210:213], v[54:57]
	v_mfma_f32_16x16x32_bf16 v[22:25], v[226:229], v[214:217], v[22:25]
	ds_read_b128 v[226:229], v169 offset:36864
	s_waitcnt lgkmcnt(7)
	v_mfma_f32_16x16x32_bf16 v[146:149], v[230:233], v[184:187], v[146:149]
	v_mfma_f32_16x16x32_bf16 v[82:85], v[230:233], v[198:201], v[82:85]
	v_mfma_f32_16x16x32_bf16 v[50:53], v[230:233], v[210:213], v[50:53]
	v_mfma_f32_16x16x32_bf16 v[18:21], v[230:233], v[214:217], v[18:21]
	ds_read_b128 v[230:233], v169 offset:38912
	s_waitcnt lgkmcnt(7)
	v_mfma_f32_16x16x32_bf16 v[142:145], v[234:237], v[184:187], v[142:145]
	v_mfma_f32_16x16x32_bf16 v[78:81], v[234:237], v[198:201], v[78:81]
	v_mfma_f32_16x16x32_bf16 v[46:49], v[234:237], v[210:213], v[46:49]
	v_mfma_f32_16x16x32_bf16 v[14:17], v[234:237], v[214:217], v[14:17]
	ds_read_b128 v[234:237], v169 offset:40960
	s_waitcnt lgkmcnt(7)
	v_mfma_f32_16x16x32_bf16 v[138:141], v[238:241], v[184:187], v[138:141]
	v_mfma_f32_16x16x32_bf16 v[74:77], v[238:241], v[198:201], v[74:77]
	v_mfma_f32_16x16x32_bf16 v[42:45], v[238:241], v[210:213], v[42:45]
	v_mfma_f32_16x16x32_bf16 v[10:13], v[238:241], v[214:217], v[10:13]
	ds_read_b128 v[238:241], v169 offset:43008
	s_waitcnt lgkmcnt(7)
	v_mfma_f32_16x16x32_bf16 v[134:137], v[242:245], v[184:187], v[134:137]
	v_mfma_f32_16x16x32_bf16 v[70:73], v[242:245], v[198:201], v[70:73]
	v_mfma_f32_16x16x32_bf16 v[38:41], v[242:245], v[210:213], v[38:41]
	v_mfma_f32_16x16x32_bf16 v[6:9], v[242:245], v[214:217], v[6:9]
	ds_read_b128 v[242:245], v169 offset:45056
	s_waitcnt lgkmcnt(7)
	v_mfma_f32_16x16x32_bf16 v[126:129], v[246:249], v[184:187], v[126:129]
	v_mfma_f32_16x16x32_bf16 v[62:65], v[246:249], v[198:201], v[62:65]
	v_xor_b32_e32 v169, 64, v206
	v_add3_u32 v169, s15, v0, v169
	ds_read_b128 v[184:187], v169
	ds_read_b128 v[198:201], v169 offset:2048
	v_mfma_f32_16x16x32_bf16 v[30:33], v[246:249], v[210:213], v[30:33]
	ds_read_b128 v[210:213], v169 offset:4096
	v_mfma_f32_16x16x32_bf16 v[2:5], v[246:249], v[214:217], v[2:5]
	ds_read_b128 v[214:217], v169 offset:6144
	v_xor_b32_e32 v169, 64, v206
	v_add3_u32 v169, s15, v167, v169
	ds_read_b128 v[246:249], v169 offset:47104
	s_waitcnt lgkmcnt(4)
	v_mfma_f32_16x16x32_bf16 v[158:161], v[218:221], v[184:187], v[158:161]
	s_waitcnt lgkmcnt(3)
	v_mfma_f32_16x16x32_bf16 v[130:133], v[218:221], v[198:201], v[130:133]
	s_waitcnt lgkmcnt(2)
	v_mfma_f32_16x16x32_bf16 v[66:69], v[218:221], v[210:213], v[66:69]
	s_waitcnt lgkmcnt(1)
	v_mfma_f32_16x16x32_bf16 v[34:37], v[218:221], v[214:217], v[34:37]
	s_waitcnt vmcnt(7)
	ds_write_b128 v171, v[94:97]
	v_mfma_f32_16x16x32_bf16 v[154:157], v[222:225], v[184:187], v[154:157]
	v_mfma_f32_16x16x32_bf16 v[122:125], v[222:225], v[198:201], v[122:125]
	global_load_dwordx4 v[94:97], v168, vcc offset:256
	v_mfma_f32_16x16x32_bf16 v[58:61], v[222:225], v[210:213], v[58:61]
	v_mfma_f32_16x16x32_bf16 v[26:29], v[222:225], v[214:217], v[26:29]
	s_waitcnt vmcnt(7)
	ds_write_b128 v171, v[86:89] offset:8192
	v_mfma_f32_16x16x32_bf16 v[150:153], v[226:229], v[184:187], v[150:153]
	v_mfma_f32_16x16x32_bf16 v[114:117], v[226:229], v[198:201], v[114:117]
	v_add_u32_e32 v86, s34, v168
	global_load_dwordx4 v[86:89], v86, vcc offset:256
	v_mfma_f32_16x16x32_bf16 v[54:57], v[226:229], v[210:213], v[54:57]
	v_mfma_f32_16x16x32_bf16 v[22:25], v[226:229], v[214:217], v[22:25]
	s_waitcnt vmcnt(7)
	ds_write_b128 v171, v[90:93] offset:16384
	v_mfma_f32_16x16x32_bf16 v[146:149], v[230:233], v[184:187], v[146:149]
	v_mfma_f32_16x16x32_bf16 v[82:85], v[230:233], v[198:201], v[82:85]
	v_add_u32_e32 v90, s35, v168
	global_load_dwordx4 v[90:93], v90, vcc offset:256
	v_mfma_f32_16x16x32_bf16 v[50:53], v[230:233], v[210:213], v[50:53]
	v_mfma_f32_16x16x32_bf16 v[18:21], v[230:233], v[214:217], v[18:21]
	s_waitcnt vmcnt(7)
	ds_write_b128 v171, v[106:109] offset:24576
	v_mfma_f32_16x16x32_bf16 v[142:145], v[234:237], v[184:187], v[142:145]
	v_mfma_f32_16x16x32_bf16 v[78:81], v[234:237], v[198:201], v[78:81]
	v_add_u32_e32 v106, s36, v168
	global_load_dwordx4 v[106:109], v106, vcc offset:256
	v_mfma_f32_16x16x32_bf16 v[46:49], v[234:237], v[210:213], v[46:49]
	v_mfma_f32_16x16x32_bf16 v[14:17], v[234:237], v[214:217], v[14:17]
	s_waitcnt vmcnt(7)
	ds_write_b128 v171, v[102:105] offset:32768
	v_mfma_f32_16x16x32_bf16 v[138:141], v[238:241], v[184:187], v[138:141]
	v_mfma_f32_16x16x32_bf16 v[74:77], v[238:241], v[198:201], v[74:77]
	global_load_dwordx4 v[102:105], v170, s[100:101] offset:256
	v_mfma_f32_16x16x32_bf16 v[42:45], v[238:241], v[210:213], v[42:45]
	v_mfma_f32_16x16x32_bf16 v[10:13], v[238:241], v[214:217], v[10:13]
	s_waitcnt vmcnt(7)
	ds_write_b128 v171, v[98:101] offset:40960
	v_mfma_f32_16x16x32_bf16 v[134:137], v[242:245], v[184:187], v[134:137]
	v_mfma_f32_16x16x32_bf16 v[70:73], v[242:245], v[198:201], v[70:73]
	v_add_u32_e32 v98, s34, v170
	global_load_dwordx4 v[98:101], v98, s[100:101] offset:256
	v_mfma_f32_16x16x32_bf16 v[38:41], v[242:245], v[210:213], v[38:41]
	v_mfma_f32_16x16x32_bf16 v[6:9], v[242:245], v[214:217], v[6:9]
	s_waitcnt vmcnt(7)
	ds_write_b128 v171, v[118:121] offset:49152
	s_waitcnt lgkmcnt(7)
	v_mfma_f32_16x16x32_bf16 v[126:129], v[246:249], v[184:187], v[126:129]
	v_mfma_f32_16x16x32_bf16 v[62:65], v[246:249], v[198:201], v[62:65]
	v_add_u32_e32 v118, s35, v170
	global_load_dwordx4 v[118:121], v118, s[100:101] offset:256
	v_mfma_f32_16x16x32_bf16 v[30:33], v[246:249], v[210:213], v[30:33]
	v_mfma_f32_16x16x32_bf16 v[2:5], v[246:249], v[214:217], v[2:5]
	s_waitcnt vmcnt(7)
	ds_write_b128 v171, v[110:113] offset:57344
	v_add_u32_e32 v110, s36, v170
	global_load_dwordx4 v[110:113], v110, s[100:101] offset:256
	v_add_u32_e32 v168, 0x80, v168
	v_add_u32_e32 v170, 0x80, v170
	s_waitcnt lgkmcnt(0)
	s_barrier
	s_cmp_eq_u32 s14, 16
	s_mov_b32 s4, s14
	s_cbranch_scc0 .LBB0_665
	s_add_i32 m0, s11, s10
	s_cmpk_lt_i32 m0, 0x3f0
	s_cselect_b32 m0, m0, s11
	s_mul_hi_i32 s101, m0, 0x38e38e39
	s_lshr_b32 vcc_lo, s101, 31
	s_ashr_i32 s101, s101, 4
	s_add_i32 s101, s101, vcc_lo
	s_mul_i32 vcc_lo, s101, 0x48
	s_sub_i32 m0, m0, vcc_lo
	s_lshl_b32 m0, m0, 19
	s_lshl_b32 s101, s101, 19
	v_readfirstlane_b32 vcc_lo, v162
	v_readfirstlane_b32 vcc_hi, v163
	v_and_b32_e32 v242, 7, v172
	v_lshlrev_b32_e32 v242, 4, v242
	v_lshl_add_u32 v242, v204, 11, v242
	s_add_u32 vcc_lo, vcc_lo, m0
	s_addc_u32 vcc_hi, vcc_hi, 0
	s_mov_b32 m0, s101
	v_readfirstlane_b32 s100, v164
	v_readfirstlane_b32 s101, v165
	s_nop 0
	s_add_u32 s100, s100, m0
	s_addc_u32 s101, s101, 0
	global_load_dwordx4 v[210:213], v242, vcc
	v_add_u32_e32 v214, s34, v242
	global_load_dwordx4 v[214:217], v214, vcc
	v_add_u32_e32 v218, s35, v242
	global_load_dwordx4 v[218:221], v218, vcc
	v_add_u32_e32 v222, s36, v242
	global_load_dwordx4 v[222:225], v222, vcc
	global_load_dwordx4 v[226:229], v242, s[100:101]
	v_add_u32_e32 v230, s34, v242
	global_load_dwordx4 v[230:233], v230, s[100:101]
	v_add_u32_e32 v234, s35, v242
	global_load_dwordx4 v[234:237], v234, s[100:101]
	v_add_u32_e32 v238, s36, v242
	global_load_dwordx4 v[238:241], v238, s[100:101]
	s_waitcnt vmcnt(11)
	v_and_b32_sdwa v93, v158, v177 dst_sel:DWORD dst_unused:UNUSED_PAD src0_sel:WORD_1 src1_sel:DWORD
	v_or_b32_e32 v88, s7, v207
	v_add3_u32 v95, v158, v93, s28
	v_and_b32_sdwa v93, v161, v177 dst_sel:DWORD dst_unused:UNUSED_PAD src0_sel:WORD_1 src1_sel:DWORD
	v_and_b32_sdwa v96, v159, v177 dst_sel:DWORD dst_unused:UNUSED_PAD src0_sel:WORD_1 src1_sel:DWORD
	v_add_u32_e32 v94, s6, v205
	v_mov_b64_e32 v[86:87], s[12:13]
	v_ashrrev_i32_e32 v89, 31, v88
	v_and_b32_sdwa v92, v160, v177 dst_sel:DWORD dst_unused:UNUSED_PAD src0_sel:WORD_1 src1_sel:DWORD
	v_add3_u32 v93, v161, v93, s28
	v_add3_u32 v96, v159, v96, s28
	v_mad_i64_i32 v[90:91], s[6:7], v94, s8, v[86:87]
	v_lshlrev_b64 v[88:89], 1, v[88:89]
	v_add3_u32 v92, v160, v92, s28
	v_and_b32_e32 v93, 0xffff0000, v93
	v_and_b32_e32 v96, 0xffff0000, v96
	v_lshl_add_u64 v[90:91], v[90:91], 0, v[88:89]
	v_or_b32_sdwa v93, v93, v92 dst_sel:DWORD dst_unused:UNUSED_PAD src0_sel:DWORD src1_sel:WORD_1
	v_or_b32_sdwa v92, v96, v95 dst_sel:DWORD dst_unused:UNUSED_PAD src0_sel:DWORD src1_sel:WORD_1
	s_waitcnt vmcnt(8)
	global_store_dwordx2 v[90:91], v[92:93], off
	v_and_b32_sdwa v93, v154, v177 dst_sel:DWORD dst_unused:UNUSED_PAD src0_sel:WORD_1 src1_sel:DWORD
	v_add3_u32 v95, v154, v93, s28
	v_and_b32_sdwa v93, v157, v177 dst_sel:DWORD dst_unused:UNUSED_PAD src0_sel:WORD_1 src1_sel:DWORD
	v_and_b32_sdwa v96, v155, v177 dst_sel:DWORD dst_unused:UNUSED_PAD src0_sel:WORD_1 src1_sel:DWORD
	v_and_b32_sdwa v92, v156, v177 dst_sel:DWORD dst_unused:UNUSED_PAD src0_sel:WORD_1 src1_sel:DWORD
	v_add3_u32 v93, v157, v93, s28
	v_add3_u32 v96, v155, v96, s28
	v_add3_u32 v92, v156, v92, s28
	v_and_b32_e32 v93, 0xffff0000, v93
	v_and_b32_e32 v96, 0xffff0000, v96
	v_or_b32_sdwa v93, v93, v92 dst_sel:DWORD dst_unused:UNUSED_PAD src0_sel:DWORD src1_sel:WORD_1
	v_or_b32_sdwa v92, v96, v95 dst_sel:DWORD dst_unused:UNUSED_PAD src0_sel:DWORD src1_sel:WORD_1
	global_store_dwordx2 v[90:91], v[92:93], off offset:32
	v_and_b32_sdwa v93, v150, v177 dst_sel:DWORD dst_unused:UNUSED_PAD src0_sel:WORD_1 src1_sel:DWORD
	v_add3_u32 v95, v150, v93, s28
	v_and_b32_sdwa v93, v153, v177 dst_sel:DWORD dst_unused:UNUSED_PAD src0_sel:WORD_1 src1_sel:DWORD
	v_and_b32_sdwa v96, v151, v177 dst_sel:DWORD dst_unused:UNUSED_PAD src0_sel:WORD_1 src1_sel:DWORD
	v_and_b32_sdwa v92, v152, v177 dst_sel:DWORD dst_unused:UNUSED_PAD src0_sel:WORD_1 src1_sel:DWORD
	v_add3_u32 v93, v153, v93, s28
	v_add3_u32 v96, v151, v96, s28
	v_add3_u32 v92, v152, v92, s28
	v_and_b32_e32 v93, 0xffff0000, v93
	v_and_b32_e32 v96, 0xffff0000, v96
	v_or_b32_sdwa v93, v93, v92 dst_sel:DWORD dst_unused:UNUSED_PAD src0_sel:DWORD src1_sel:WORD_1
	v_or_b32_sdwa v92, v96, v95 dst_sel:DWORD dst_unused:UNUSED_PAD src0_sel:DWORD src1_sel:WORD_1
	global_store_dwordx2 v[90:91], v[92:93], off offset:64
	v_and_b32_sdwa v93, v146, v177 dst_sel:DWORD dst_unused:UNUSED_PAD src0_sel:WORD_1 src1_sel:DWORD
	v_add3_u32 v95, v146, v93, s28
	v_and_b32_sdwa v93, v149, v177 dst_sel:DWORD dst_unused:UNUSED_PAD src0_sel:WORD_1 src1_sel:DWORD
	v_and_b32_sdwa v96, v147, v177 dst_sel:DWORD dst_unused:UNUSED_PAD src0_sel:WORD_1 src1_sel:DWORD
	v_and_b32_sdwa v92, v148, v177 dst_sel:DWORD dst_unused:UNUSED_PAD src0_sel:WORD_1 src1_sel:DWORD
	v_add3_u32 v93, v149, v93, s28
	v_add3_u32 v96, v147, v96, s28
	v_add3_u32 v92, v148, v92, s28
	v_and_b32_e32 v93, 0xffff0000, v93
	v_and_b32_e32 v96, 0xffff0000, v96
	v_or_b32_sdwa v93, v93, v92 dst_sel:DWORD dst_unused:UNUSED_PAD src0_sel:DWORD src1_sel:WORD_1
	v_or_b32_sdwa v92, v96, v95 dst_sel:DWORD dst_unused:UNUSED_PAD src0_sel:DWORD src1_sel:WORD_1
	global_store_dwordx2 v[90:91], v[92:93], off offset:96
	v_and_b32_sdwa v93, v142, v177 dst_sel:DWORD dst_unused:UNUSED_PAD src0_sel:WORD_1 src1_sel:DWORD
	v_add3_u32 v95, v142, v93, s28
	v_and_b32_sdwa v93, v145, v177 dst_sel:DWORD dst_unused:UNUSED_PAD src0_sel:WORD_1 src1_sel:DWORD
	v_and_b32_sdwa v96, v143, v177 dst_sel:DWORD dst_unused:UNUSED_PAD src0_sel:WORD_1 src1_sel:DWORD
	v_and_b32_sdwa v92, v144, v177 dst_sel:DWORD dst_unused:UNUSED_PAD src0_sel:WORD_1 src1_sel:DWORD
	v_add3_u32 v93, v145, v93, s28
	v_add3_u32 v96, v143, v96, s28
	v_add3_u32 v92, v144, v92, s28
	v_and_b32_e32 v93, 0xffff0000, v93
	v_and_b32_e32 v96, 0xffff0000, v96
	v_or_b32_sdwa v93, v93, v92 dst_sel:DWORD dst_unused:UNUSED_PAD src0_sel:DWORD src1_sel:WORD_1
	v_or_b32_sdwa v92, v96, v95 dst_sel:DWORD dst_unused:UNUSED_PAD src0_sel:DWORD src1_sel:WORD_1
	global_store_dwordx2 v[90:91], v[92:93], off offset:128
	v_and_b32_sdwa v93, v138, v177 dst_sel:DWORD dst_unused:UNUSED_PAD src0_sel:WORD_1 src1_sel:DWORD
	v_add3_u32 v95, v138, v93, s28
	v_and_b32_sdwa v93, v141, v177 dst_sel:DWORD dst_unused:UNUSED_PAD src0_sel:WORD_1 src1_sel:DWORD
	v_and_b32_sdwa v96, v139, v177 dst_sel:DWORD dst_unused:UNUSED_PAD src0_sel:WORD_1 src1_sel:DWORD
	v_and_b32_sdwa v92, v140, v177 dst_sel:DWORD dst_unused:UNUSED_PAD src0_sel:WORD_1 src1_sel:DWORD
	v_add3_u32 v93, v141, v93, s28
	v_add3_u32 v96, v139, v96, s28
	v_add3_u32 v92, v140, v92, s28
	v_and_b32_e32 v93, 0xffff0000, v93
	v_and_b32_e32 v96, 0xffff0000, v96
	v_or_b32_sdwa v93, v93, v92 dst_sel:DWORD dst_unused:UNUSED_PAD src0_sel:DWORD src1_sel:WORD_1
	v_or_b32_sdwa v92, v96, v95 dst_sel:DWORD dst_unused:UNUSED_PAD src0_sel:DWORD src1_sel:WORD_1
	global_store_dwordx2 v[90:91], v[92:93], off offset:160
	v_and_b32_sdwa v93, v134, v177 dst_sel:DWORD dst_unused:UNUSED_PAD src0_sel:WORD_1 src1_sel:DWORD
	v_add3_u32 v95, v134, v93, s28
	v_and_b32_sdwa v93, v137, v177 dst_sel:DWORD dst_unused:UNUSED_PAD src0_sel:WORD_1 src1_sel:DWORD
	v_and_b32_sdwa v96, v135, v177 dst_sel:DWORD dst_unused:UNUSED_PAD src0_sel:WORD_1 src1_sel:DWORD
	v_and_b32_sdwa v92, v136, v177 dst_sel:DWORD dst_unused:UNUSED_PAD src0_sel:WORD_1 src1_sel:DWORD
	v_add3_u32 v93, v137, v93, s28
	v_add3_u32 v96, v135, v96, s28
	v_add3_u32 v92, v136, v92, s28
	v_and_b32_e32 v93, 0xffff0000, v93
	v_and_b32_e32 v96, 0xffff0000, v96
	v_or_b32_sdwa v93, v93, v92 dst_sel:DWORD dst_unused:UNUSED_PAD src0_sel:DWORD src1_sel:WORD_1
	v_or_b32_sdwa v92, v96, v95 dst_sel:DWORD dst_unused:UNUSED_PAD src0_sel:DWORD src1_sel:WORD_1
	global_store_dwordx2 v[90:91], v[92:93], off offset:192
	v_and_b32_sdwa v93, v126, v177 dst_sel:DWORD dst_unused:UNUSED_PAD src0_sel:WORD_1 src1_sel:DWORD
	v_add3_u32 v95, v126, v93, s28
	v_and_b32_sdwa v93, v129, v177 dst_sel:DWORD dst_unused:UNUSED_PAD src0_sel:WORD_1 src1_sel:DWORD
	v_and_b32_sdwa v96, v127, v177 dst_sel:DWORD dst_unused:UNUSED_PAD src0_sel:WORD_1 src1_sel:DWORD
	v_and_b32_sdwa v92, v128, v177 dst_sel:DWORD dst_unused:UNUSED_PAD src0_sel:WORD_1 src1_sel:DWORD
	v_add3_u32 v93, v129, v93, s28
	v_add3_u32 v96, v127, v96, s28
	v_add3_u32 v92, v128, v92, s28
	v_and_b32_e32 v93, 0xffff0000, v93
	v_and_b32_e32 v96, 0xffff0000, v96
	v_or_b32_sdwa v93, v93, v92 dst_sel:DWORD dst_unused:UNUSED_PAD src0_sel:DWORD src1_sel:WORD_1
	v_or_b32_sdwa v92, v96, v95 dst_sel:DWORD dst_unused:UNUSED_PAD src0_sel:DWORD src1_sel:WORD_1
	global_store_dwordx2 v[90:91], v[92:93], off offset:224
	v_and_b32_sdwa v93, v130, v177 dst_sel:DWORD dst_unused:UNUSED_PAD src0_sel:WORD_1 src1_sel:DWORD
	v_add3_u32 v95, v130, v93, s28
	v_and_b32_sdwa v93, v133, v177 dst_sel:DWORD dst_unused:UNUSED_PAD src0_sel:WORD_1 src1_sel:DWORD
	v_and_b32_sdwa v96, v131, v177 dst_sel:DWORD dst_unused:UNUSED_PAD src0_sel:WORD_1 src1_sel:DWORD
	v_or_b32_e32 v90, 16, v94
	v_and_b32_sdwa v92, v132, v177 dst_sel:DWORD dst_unused:UNUSED_PAD src0_sel:WORD_1 src1_sel:DWORD
	v_add3_u32 v93, v133, v93, s28
	v_add3_u32 v96, v131, v96, s28
	v_mad_i64_i32 v[90:91], s[6:7], v90, s8, v[86:87]
	v_add3_u32 v92, v132, v92, s28
	v_and_b32_e32 v93, 0xffff0000, v93
	v_and_b32_e32 v96, 0xffff0000, v96
	v_lshl_add_u64 v[90:91], v[90:91], 0, v[88:89]
	v_or_b32_sdwa v93, v93, v92 dst_sel:DWORD dst_unused:UNUSED_PAD src0_sel:DWORD src1_sel:WORD_1
	v_or_b32_sdwa v92, v96, v95 dst_sel:DWORD dst_unused:UNUSED_PAD src0_sel:DWORD src1_sel:WORD_1
	global_store_dwordx2 v[90:91], v[92:93], off
	v_and_b32_sdwa v93, v122, v177 dst_sel:DWORD dst_unused:UNUSED_PAD src0_sel:WORD_1 src1_sel:DWORD
	v_add3_u32 v95, v122, v93, s28
	v_and_b32_sdwa v93, v125, v177 dst_sel:DWORD dst_unused:UNUSED_PAD src0_sel:WORD_1 src1_sel:DWORD
	v_and_b32_sdwa v96, v123, v177 dst_sel:DWORD dst_unused:UNUSED_PAD src0_sel:WORD_1 src1_sel:DWORD
	v_and_b32_sdwa v92, v124, v177 dst_sel:DWORD dst_unused:UNUSED_PAD src0_sel:WORD_1 src1_sel:DWORD
	v_add3_u32 v93, v125, v93, s28
	v_add3_u32 v96, v123, v96, s28
	v_add3_u32 v92, v124, v92, s28
	v_and_b32_e32 v93, 0xffff0000, v93
	v_and_b32_e32 v96, 0xffff0000, v96
	v_or_b32_sdwa v93, v93, v92 dst_sel:DWORD dst_unused:UNUSED_PAD src0_sel:DWORD src1_sel:WORD_1
	v_or_b32_sdwa v92, v96, v95 dst_sel:DWORD dst_unused:UNUSED_PAD src0_sel:DWORD src1_sel:WORD_1
	global_store_dwordx2 v[90:91], v[92:93], off offset:32
	v_and_b32_sdwa v93, v114, v177 dst_sel:DWORD dst_unused:UNUSED_PAD src0_sel:WORD_1 src1_sel:DWORD
	v_add3_u32 v95, v114, v93, s28
	v_and_b32_sdwa v93, v117, v177 dst_sel:DWORD dst_unused:UNUSED_PAD src0_sel:WORD_1 src1_sel:DWORD
	v_and_b32_sdwa v96, v115, v177 dst_sel:DWORD dst_unused:UNUSED_PAD src0_sel:WORD_1 src1_sel:DWORD
	v_and_b32_sdwa v92, v116, v177 dst_sel:DWORD dst_unused:UNUSED_PAD src0_sel:WORD_1 src1_sel:DWORD
	v_add3_u32 v93, v117, v93, s28
	v_add3_u32 v96, v115, v96, s28
	v_add3_u32 v92, v116, v92, s28
	v_and_b32_e32 v93, 0xffff0000, v93
	v_and_b32_e32 v96, 0xffff0000, v96
	v_or_b32_sdwa v93, v93, v92 dst_sel:DWORD dst_unused:UNUSED_PAD src0_sel:DWORD src1_sel:WORD_1
	v_or_b32_sdwa v92, v96, v95 dst_sel:DWORD dst_unused:UNUSED_PAD src0_sel:DWORD src1_sel:WORD_1
	global_store_dwordx2 v[90:91], v[92:93], off offset:64
	v_and_b32_sdwa v92, v84, v177 dst_sel:DWORD dst_unused:UNUSED_PAD src0_sel:WORD_1 src1_sel:DWORD
	v_and_b32_sdwa v93, v82, v177 dst_sel:DWORD dst_unused:UNUSED_PAD src0_sel:WORD_1 src1_sel:DWORD
	v_add3_u32 v82, v82, v93, s28
	v_add3_u32 v84, v84, v92, s28
	v_and_b32_sdwa v92, v85, v177 dst_sel:DWORD dst_unused:UNUSED_PAD src0_sel:WORD_1 src1_sel:DWORD
	v_and_b32_sdwa v93, v83, v177 dst_sel:DWORD dst_unused:UNUSED_PAD src0_sel:WORD_1 src1_sel:DWORD
	v_add3_u32 v85, v85, v92, s28
	v_add3_u32 v83, v83, v93, s28
	v_and_b32_e32 v85, 0xffff0000, v85
	v_and_b32_e32 v92, 0xffff0000, v83
	v_or_b32_sdwa v83, v85, v84 dst_sel:DWORD dst_unused:UNUSED_PAD src0_sel:DWORD src1_sel:WORD_1
	v_or_b32_sdwa v82, v92, v82 dst_sel:DWORD dst_unused:UNUSED_PAD src0_sel:DWORD src1_sel:WORD_1
	global_store_dwordx2 v[90:91], v[82:83], off offset:96
	v_and_b32_sdwa v82, v80, v177 dst_sel:DWORD dst_unused:UNUSED_PAD src0_sel:WORD_1 src1_sel:DWORD
	v_and_b32_sdwa v83, v78, v177 dst_sel:DWORD dst_unused:UNUSED_PAD src0_sel:WORD_1 src1_sel:DWORD
	v_add3_u32 v78, v78, v83, s28
	v_add3_u32 v80, v80, v82, s28
	v_and_b32_sdwa v82, v81, v177 dst_sel:DWORD dst_unused:UNUSED_PAD src0_sel:WORD_1 src1_sel:DWORD
	v_and_b32_sdwa v83, v79, v177 dst_sel:DWORD dst_unused:UNUSED_PAD src0_sel:WORD_1 src1_sel:DWORD
	v_add3_u32 v81, v81, v82, s28
	v_add3_u32 v79, v79, v83, s28
	v_and_b32_e32 v81, 0xffff0000, v81
	v_and_b32_e32 v82, 0xffff0000, v79
	v_or_b32_sdwa v79, v81, v80 dst_sel:DWORD dst_unused:UNUSED_PAD src0_sel:DWORD src1_sel:WORD_1
	v_or_b32_sdwa v78, v82, v78 dst_sel:DWORD dst_unused:UNUSED_PAD src0_sel:DWORD src1_sel:WORD_1
	global_store_dwordx2 v[90:91], v[78:79], off offset:128
	v_and_b32_sdwa v78, v76, v177 dst_sel:DWORD dst_unused:UNUSED_PAD src0_sel:WORD_1 src1_sel:DWORD
	v_and_b32_sdwa v79, v74, v177 dst_sel:DWORD dst_unused:UNUSED_PAD src0_sel:WORD_1 src1_sel:DWORD
	v_add3_u32 v74, v74, v79, s28
	v_add3_u32 v76, v76, v78, s28
	v_and_b32_sdwa v78, v77, v177 dst_sel:DWORD dst_unused:UNUSED_PAD src0_sel:WORD_1 src1_sel:DWORD
	v_and_b32_sdwa v79, v75, v177 dst_sel:DWORD dst_unused:UNUSED_PAD src0_sel:WORD_1 src1_sel:DWORD
	v_add3_u32 v77, v77, v78, s28
	v_add3_u32 v75, v75, v79, s28
	v_and_b32_e32 v77, 0xffff0000, v77
	v_and_b32_e32 v78, 0xffff0000, v75
	v_or_b32_sdwa v75, v77, v76 dst_sel:DWORD dst_unused:UNUSED_PAD src0_sel:DWORD src1_sel:WORD_1
	v_or_b32_sdwa v74, v78, v74 dst_sel:DWORD dst_unused:UNUSED_PAD src0_sel:DWORD src1_sel:WORD_1
	global_store_dwordx2 v[90:91], v[74:75], off offset:160
	v_and_b32_sdwa v74, v72, v177 dst_sel:DWORD dst_unused:UNUSED_PAD src0_sel:WORD_1 src1_sel:DWORD
	v_and_b32_sdwa v75, v70, v177 dst_sel:DWORD dst_unused:UNUSED_PAD src0_sel:WORD_1 src1_sel:DWORD
	v_add3_u32 v70, v70, v75, s28
	v_add3_u32 v72, v72, v74, s28
	v_and_b32_sdwa v74, v73, v177 dst_sel:DWORD dst_unused:UNUSED_PAD src0_sel:WORD_1 src1_sel:DWORD
	v_and_b32_sdwa v75, v71, v177 dst_sel:DWORD dst_unused:UNUSED_PAD src0_sel:WORD_1 src1_sel:DWORD
	v_add3_u32 v73, v73, v74, s28
	v_add3_u32 v71, v71, v75, s28
	v_and_b32_e32 v73, 0xffff0000, v73
	v_and_b32_e32 v74, 0xffff0000, v71
	v_or_b32_sdwa v71, v73, v72 dst_sel:DWORD dst_unused:UNUSED_PAD src0_sel:DWORD src1_sel:WORD_1
	v_or_b32_sdwa v70, v74, v70 dst_sel:DWORD dst_unused:UNUSED_PAD src0_sel:DWORD src1_sel:WORD_1
	global_store_dwordx2 v[90:91], v[70:71], off offset:192
	v_and_b32_sdwa v70, v64, v177 dst_sel:DWORD dst_unused:UNUSED_PAD src0_sel:WORD_1 src1_sel:DWORD
	v_and_b32_sdwa v71, v62, v177 dst_sel:DWORD dst_unused:UNUSED_PAD src0_sel:WORD_1 src1_sel:DWORD
	v_add3_u32 v64, v64, v70, s28
	v_and_b32_sdwa v70, v65, v177 dst_sel:DWORD dst_unused:UNUSED_PAD src0_sel:WORD_1 src1_sel:DWORD
	v_add3_u32 v62, v62, v71, s28
	v_and_b32_sdwa v71, v63, v177 dst_sel:DWORD dst_unused:UNUSED_PAD src0_sel:WORD_1 src1_sel:DWORD
	v_add3_u32 v65, v65, v70, s28
	v_add3_u32 v63, v63, v71, s28
	v_and_b32_e32 v65, 0xffff0000, v65
	v_and_b32_e32 v70, 0xffff0000, v63
	v_or_b32_sdwa v63, v65, v64 dst_sel:DWORD dst_unused:UNUSED_PAD src0_sel:DWORD src1_sel:WORD_1
	v_and_b32_sdwa v64, v68, v177 dst_sel:DWORD dst_unused:UNUSED_PAD src0_sel:WORD_1 src1_sel:DWORD
	v_and_b32_sdwa v65, v66, v177 dst_sel:DWORD dst_unused:UNUSED_PAD src0_sel:WORD_1 src1_sel:DWORD
	v_or_b32_sdwa v62, v70, v62 dst_sel:DWORD dst_unused:UNUSED_PAD src0_sel:DWORD src1_sel:WORD_1
	v_add3_u32 v66, v66, v65, s28
	v_add3_u32 v64, v68, v64, s28
	v_and_b32_sdwa v65, v69, v177 dst_sel:DWORD dst_unused:UNUSED_PAD src0_sel:WORD_1 src1_sel:DWORD
	v_and_b32_sdwa v68, v67, v177 dst_sel:DWORD dst_unused:UNUSED_PAD src0_sel:WORD_1 src1_sel:DWORD
	global_store_dwordx2 v[90:91], v[62:63], off offset:224
	v_or_b32_e32 v62, 32, v94
	v_add3_u32 v65, v69, v65, s28
	v_add3_u32 v67, v67, v68, s28
	v_mad_i64_i32 v[62:63], s[6:7], v62, s8, v[86:87]
	v_and_b32_e32 v65, 0xffff0000, v65
	v_and_b32_e32 v67, 0xffff0000, v67
	v_lshl_add_u64 v[62:63], v[62:63], 0, v[88:89]
	v_or_b32_sdwa v65, v65, v64 dst_sel:DWORD dst_unused:UNUSED_PAD src0_sel:DWORD src1_sel:WORD_1
	v_or_b32_sdwa v64, v67, v66 dst_sel:DWORD dst_unused:UNUSED_PAD src0_sel:DWORD src1_sel:WORD_1
	global_store_dwordx2 v[62:63], v[64:65], off
	v_and_b32_sdwa v64, v60, v177 dst_sel:DWORD dst_unused:UNUSED_PAD src0_sel:WORD_1 src1_sel:DWORD
	v_and_b32_sdwa v65, v58, v177 dst_sel:DWORD dst_unused:UNUSED_PAD src0_sel:WORD_1 src1_sel:DWORD
	v_add3_u32 v58, v58, v65, s28
	v_add3_u32 v60, v60, v64, s28
	v_and_b32_sdwa v64, v61, v177 dst_sel:DWORD dst_unused:UNUSED_PAD src0_sel:WORD_1 src1_sel:DWORD
	v_and_b32_sdwa v65, v59, v177 dst_sel:DWORD dst_unused:UNUSED_PAD src0_sel:WORD_1 src1_sel:DWORD
	v_add3_u32 v61, v61, v64, s28
	v_add3_u32 v59, v59, v65, s28
	v_and_b32_e32 v61, 0xffff0000, v61
	v_and_b32_e32 v64, 0xffff0000, v59
	v_or_b32_sdwa v59, v61, v60 dst_sel:DWORD dst_unused:UNUSED_PAD src0_sel:DWORD src1_sel:WORD_1
	v_or_b32_sdwa v58, v64, v58 dst_sel:DWORD dst_unused:UNUSED_PAD src0_sel:DWORD src1_sel:WORD_1
	global_store_dwordx2 v[62:63], v[58:59], off offset:32
	v_and_b32_sdwa v58, v56, v177 dst_sel:DWORD dst_unused:UNUSED_PAD src0_sel:WORD_1 src1_sel:DWORD
	v_and_b32_sdwa v59, v54, v177 dst_sel:DWORD dst_unused:UNUSED_PAD src0_sel:WORD_1 src1_sel:DWORD
	v_add3_u32 v54, v54, v59, s28
	v_add3_u32 v56, v56, v58, s28
	v_and_b32_sdwa v58, v57, v177 dst_sel:DWORD dst_unused:UNUSED_PAD src0_sel:WORD_1 src1_sel:DWORD
	v_and_b32_sdwa v59, v55, v177 dst_sel:DWORD dst_unused:UNUSED_PAD src0_sel:WORD_1 src1_sel:DWORD
	v_add3_u32 v57, v57, v58, s28
	v_add3_u32 v55, v55, v59, s28
	v_and_b32_e32 v57, 0xffff0000, v57
	v_and_b32_e32 v58, 0xffff0000, v55
	v_or_b32_sdwa v55, v57, v56 dst_sel:DWORD dst_unused:UNUSED_PAD src0_sel:DWORD src1_sel:WORD_1
	v_or_b32_sdwa v54, v58, v54 dst_sel:DWORD dst_unused:UNUSED_PAD src0_sel:DWORD src1_sel:WORD_1
	global_store_dwordx2 v[62:63], v[54:55], off offset:64
	v_and_b32_sdwa v54, v52, v177 dst_sel:DWORD dst_unused:UNUSED_PAD src0_sel:WORD_1 src1_sel:DWORD
	v_and_b32_sdwa v55, v50, v177 dst_sel:DWORD dst_unused:UNUSED_PAD src0_sel:WORD_1 src1_sel:DWORD
	v_add3_u32 v50, v50, v55, s28
	v_add3_u32 v52, v52, v54, s28
	v_and_b32_sdwa v54, v53, v177 dst_sel:DWORD dst_unused:UNUSED_PAD src0_sel:WORD_1 src1_sel:DWORD
	v_and_b32_sdwa v55, v51, v177 dst_sel:DWORD dst_unused:UNUSED_PAD src0_sel:WORD_1 src1_sel:DWORD
	v_add3_u32 v53, v53, v54, s28
	v_add3_u32 v51, v51, v55, s28
	v_and_b32_e32 v53, 0xffff0000, v53
	v_and_b32_e32 v54, 0xffff0000, v51
	v_or_b32_sdwa v51, v53, v52 dst_sel:DWORD dst_unused:UNUSED_PAD src0_sel:DWORD src1_sel:WORD_1
	v_or_b32_sdwa v50, v54, v50 dst_sel:DWORD dst_unused:UNUSED_PAD src0_sel:DWORD src1_sel:WORD_1
	global_store_dwordx2 v[62:63], v[50:51], off offset:96
	v_and_b32_sdwa v50, v48, v177 dst_sel:DWORD dst_unused:UNUSED_PAD src0_sel:WORD_1 src1_sel:DWORD
	v_and_b32_sdwa v51, v46, v177 dst_sel:DWORD dst_unused:UNUSED_PAD src0_sel:WORD_1 src1_sel:DWORD
	v_add3_u32 v46, v46, v51, s28
	v_add3_u32 v48, v48, v50, s28
	v_and_b32_sdwa v50, v49, v177 dst_sel:DWORD dst_unused:UNUSED_PAD src0_sel:WORD_1 src1_sel:DWORD
	v_and_b32_sdwa v51, v47, v177 dst_sel:DWORD dst_unused:UNUSED_PAD src0_sel:WORD_1 src1_sel:DWORD
	v_add3_u32 v49, v49, v50, s28
	v_add3_u32 v47, v47, v51, s28
	v_and_b32_e32 v49, 0xffff0000, v49
	v_and_b32_e32 v50, 0xffff0000, v47
	v_or_b32_sdwa v47, v49, v48 dst_sel:DWORD dst_unused:UNUSED_PAD src0_sel:DWORD src1_sel:WORD_1
	v_or_b32_sdwa v46, v50, v46 dst_sel:DWORD dst_unused:UNUSED_PAD src0_sel:DWORD src1_sel:WORD_1
	global_store_dwordx2 v[62:63], v[46:47], off offset:128
	v_and_b32_sdwa v46, v44, v177 dst_sel:DWORD dst_unused:UNUSED_PAD src0_sel:WORD_1 src1_sel:DWORD
	v_and_b32_sdwa v47, v42, v177 dst_sel:DWORD dst_unused:UNUSED_PAD src0_sel:WORD_1 src1_sel:DWORD
	v_add3_u32 v42, v42, v47, s28
	v_add3_u32 v44, v44, v46, s28
	v_and_b32_sdwa v46, v45, v177 dst_sel:DWORD dst_unused:UNUSED_PAD src0_sel:WORD_1 src1_sel:DWORD
	v_and_b32_sdwa v47, v43, v177 dst_sel:DWORD dst_unused:UNUSED_PAD src0_sel:WORD_1 src1_sel:DWORD
	v_add3_u32 v45, v45, v46, s28
	v_add3_u32 v43, v43, v47, s28
	v_and_b32_e32 v45, 0xffff0000, v45
	v_and_b32_e32 v46, 0xffff0000, v43
	v_or_b32_sdwa v43, v45, v44 dst_sel:DWORD dst_unused:UNUSED_PAD src0_sel:DWORD src1_sel:WORD_1
	v_or_b32_sdwa v42, v46, v42 dst_sel:DWORD dst_unused:UNUSED_PAD src0_sel:DWORD src1_sel:WORD_1
	global_store_dwordx2 v[62:63], v[42:43], off offset:160
	v_and_b32_sdwa v42, v40, v177 dst_sel:DWORD dst_unused:UNUSED_PAD src0_sel:WORD_1 src1_sel:DWORD
	v_and_b32_sdwa v43, v38, v177 dst_sel:DWORD dst_unused:UNUSED_PAD src0_sel:WORD_1 src1_sel:DWORD
	v_add3_u32 v38, v38, v43, s28
	v_add3_u32 v40, v40, v42, s28
	v_and_b32_sdwa v42, v41, v177 dst_sel:DWORD dst_unused:UNUSED_PAD src0_sel:WORD_1 src1_sel:DWORD
	v_and_b32_sdwa v43, v39, v177 dst_sel:DWORD dst_unused:UNUSED_PAD src0_sel:WORD_1 src1_sel:DWORD
	v_add3_u32 v41, v41, v42, s28
	v_add3_u32 v39, v39, v43, s28
	v_and_b32_e32 v41, 0xffff0000, v41
	v_and_b32_e32 v42, 0xffff0000, v39
	v_or_b32_sdwa v39, v41, v40 dst_sel:DWORD dst_unused:UNUSED_PAD src0_sel:DWORD src1_sel:WORD_1
	v_or_b32_sdwa v38, v42, v38 dst_sel:DWORD dst_unused:UNUSED_PAD src0_sel:DWORD src1_sel:WORD_1
	global_store_dwordx2 v[62:63], v[38:39], off offset:192
	v_and_b32_sdwa v38, v32, v177 dst_sel:DWORD dst_unused:UNUSED_PAD src0_sel:WORD_1 src1_sel:DWORD
	v_and_b32_sdwa v39, v30, v177 dst_sel:DWORD dst_unused:UNUSED_PAD src0_sel:WORD_1 src1_sel:DWORD
	v_add3_u32 v32, v32, v38, s28
	v_and_b32_sdwa v38, v33, v177 dst_sel:DWORD dst_unused:UNUSED_PAD src0_sel:WORD_1 src1_sel:DWORD
	v_add3_u32 v30, v30, v39, s28
	v_and_b32_sdwa v39, v31, v177 dst_sel:DWORD dst_unused:UNUSED_PAD src0_sel:WORD_1 src1_sel:DWORD
	v_add3_u32 v33, v33, v38, s28
	v_add3_u32 v31, v31, v39, s28
	v_and_b32_e32 v33, 0xffff0000, v33
	v_and_b32_e32 v38, 0xffff0000, v31
	v_or_b32_sdwa v31, v33, v32 dst_sel:DWORD dst_unused:UNUSED_PAD src0_sel:DWORD src1_sel:WORD_1
	v_and_b32_sdwa v32, v36, v177 dst_sel:DWORD dst_unused:UNUSED_PAD src0_sel:WORD_1 src1_sel:DWORD
	v_and_b32_sdwa v33, v34, v177 dst_sel:DWORD dst_unused:UNUSED_PAD src0_sel:WORD_1 src1_sel:DWORD
	v_or_b32_sdwa v30, v38, v30 dst_sel:DWORD dst_unused:UNUSED_PAD src0_sel:DWORD src1_sel:WORD_1
	v_add3_u32 v34, v34, v33, s28
	v_add3_u32 v32, v36, v32, s28
	v_and_b32_sdwa v33, v37, v177 dst_sel:DWORD dst_unused:UNUSED_PAD src0_sel:WORD_1 src1_sel:DWORD
	v_and_b32_sdwa v36, v35, v177 dst_sel:DWORD dst_unused:UNUSED_PAD src0_sel:WORD_1 src1_sel:DWORD
	global_store_dwordx2 v[62:63], v[30:31], off offset:224
	v_or_b32_e32 v30, 48, v94
	v_add3_u32 v33, v37, v33, s28
	v_add3_u32 v35, v35, v36, s28
	v_mad_i64_i32 v[30:31], s[6:7], v30, s8, v[86:87]
	v_and_b32_e32 v33, 0xffff0000, v33
	v_and_b32_e32 v35, 0xffff0000, v35
	v_lshl_add_u64 v[30:31], v[30:31], 0, v[88:89]
	v_or_b32_sdwa v33, v33, v32 dst_sel:DWORD dst_unused:UNUSED_PAD src0_sel:DWORD src1_sel:WORD_1
	v_or_b32_sdwa v32, v35, v34 dst_sel:DWORD dst_unused:UNUSED_PAD src0_sel:DWORD src1_sel:WORD_1
	global_store_dwordx2 v[30:31], v[32:33], off
	v_and_b32_sdwa v32, v28, v177 dst_sel:DWORD dst_unused:UNUSED_PAD src0_sel:WORD_1 src1_sel:DWORD
	v_and_b32_sdwa v33, v26, v177 dst_sel:DWORD dst_unused:UNUSED_PAD src0_sel:WORD_1 src1_sel:DWORD
	v_add3_u32 v26, v26, v33, s28
	v_add3_u32 v28, v28, v32, s28
	v_and_b32_sdwa v32, v29, v177 dst_sel:DWORD dst_unused:UNUSED_PAD src0_sel:WORD_1 src1_sel:DWORD
	v_and_b32_sdwa v33, v27, v177 dst_sel:DWORD dst_unused:UNUSED_PAD src0_sel:WORD_1 src1_sel:DWORD
	v_add3_u32 v29, v29, v32, s28
	v_add3_u32 v27, v27, v33, s28
	v_and_b32_e32 v29, 0xffff0000, v29
	v_and_b32_e32 v32, 0xffff0000, v27
	v_or_b32_sdwa v27, v29, v28 dst_sel:DWORD dst_unused:UNUSED_PAD src0_sel:DWORD src1_sel:WORD_1
	v_or_b32_sdwa v26, v32, v26 dst_sel:DWORD dst_unused:UNUSED_PAD src0_sel:DWORD src1_sel:WORD_1
	global_store_dwordx2 v[30:31], v[26:27], off offset:32
	v_and_b32_sdwa v26, v24, v177 dst_sel:DWORD dst_unused:UNUSED_PAD src0_sel:WORD_1 src1_sel:DWORD
	v_and_b32_sdwa v27, v22, v177 dst_sel:DWORD dst_unused:UNUSED_PAD src0_sel:WORD_1 src1_sel:DWORD
	v_add3_u32 v22, v22, v27, s28
	v_add3_u32 v24, v24, v26, s28
	v_and_b32_sdwa v26, v25, v177 dst_sel:DWORD dst_unused:UNUSED_PAD src0_sel:WORD_1 src1_sel:DWORD
	v_and_b32_sdwa v27, v23, v177 dst_sel:DWORD dst_unused:UNUSED_PAD src0_sel:WORD_1 src1_sel:DWORD
	v_add3_u32 v25, v25, v26, s28
	v_add3_u32 v23, v23, v27, s28
	v_and_b32_e32 v25, 0xffff0000, v25
	v_and_b32_e32 v26, 0xffff0000, v23
	v_or_b32_sdwa v23, v25, v24 dst_sel:DWORD dst_unused:UNUSED_PAD src0_sel:DWORD src1_sel:WORD_1
	v_or_b32_sdwa v22, v26, v22 dst_sel:DWORD dst_unused:UNUSED_PAD src0_sel:DWORD src1_sel:WORD_1
	global_store_dwordx2 v[30:31], v[22:23], off offset:64
	v_and_b32_sdwa v22, v20, v177 dst_sel:DWORD dst_unused:UNUSED_PAD src0_sel:WORD_1 src1_sel:DWORD
	v_and_b32_sdwa v23, v18, v177 dst_sel:DWORD dst_unused:UNUSED_PAD src0_sel:WORD_1 src1_sel:DWORD
	v_add3_u32 v18, v18, v23, s28
	v_add3_u32 v20, v20, v22, s28
	v_and_b32_sdwa v22, v21, v177 dst_sel:DWORD dst_unused:UNUSED_PAD src0_sel:WORD_1 src1_sel:DWORD
	v_and_b32_sdwa v23, v19, v177 dst_sel:DWORD dst_unused:UNUSED_PAD src0_sel:WORD_1 src1_sel:DWORD
	v_add3_u32 v21, v21, v22, s28
	v_add3_u32 v19, v19, v23, s28
	v_and_b32_e32 v21, 0xffff0000, v21
	v_and_b32_e32 v22, 0xffff0000, v19
	v_or_b32_sdwa v19, v21, v20 dst_sel:DWORD dst_unused:UNUSED_PAD src0_sel:DWORD src1_sel:WORD_1
	v_or_b32_sdwa v18, v22, v18 dst_sel:DWORD dst_unused:UNUSED_PAD src0_sel:DWORD src1_sel:WORD_1
	global_store_dwordx2 v[30:31], v[18:19], off offset:96
	v_and_b32_sdwa v18, v16, v177 dst_sel:DWORD dst_unused:UNUSED_PAD src0_sel:WORD_1 src1_sel:DWORD
	v_and_b32_sdwa v19, v14, v177 dst_sel:DWORD dst_unused:UNUSED_PAD src0_sel:WORD_1 src1_sel:DWORD
	v_add3_u32 v14, v14, v19, s28
	v_add3_u32 v16, v16, v18, s28
	v_and_b32_sdwa v18, v17, v177 dst_sel:DWORD dst_unused:UNUSED_PAD src0_sel:WORD_1 src1_sel:DWORD
	v_and_b32_sdwa v19, v15, v177 dst_sel:DWORD dst_unused:UNUSED_PAD src0_sel:WORD_1 src1_sel:DWORD
	v_add3_u32 v17, v17, v18, s28
	v_add3_u32 v15, v15, v19, s28
	v_and_b32_e32 v17, 0xffff0000, v17
	v_and_b32_e32 v18, 0xffff0000, v15
	v_or_b32_sdwa v15, v17, v16 dst_sel:DWORD dst_unused:UNUSED_PAD src0_sel:DWORD src1_sel:WORD_1
	v_or_b32_sdwa v14, v18, v14 dst_sel:DWORD dst_unused:UNUSED_PAD src0_sel:DWORD src1_sel:WORD_1
	global_store_dwordx2 v[30:31], v[14:15], off offset:128
	v_and_b32_sdwa v14, v12, v177 dst_sel:DWORD dst_unused:UNUSED_PAD src0_sel:WORD_1 src1_sel:DWORD
	v_and_b32_sdwa v15, v10, v177 dst_sel:DWORD dst_unused:UNUSED_PAD src0_sel:WORD_1 src1_sel:DWORD
	v_add3_u32 v10, v10, v15, s28
	v_add3_u32 v12, v12, v14, s28
	v_and_b32_sdwa v14, v13, v177 dst_sel:DWORD dst_unused:UNUSED_PAD src0_sel:WORD_1 src1_sel:DWORD
	v_and_b32_sdwa v15, v11, v177 dst_sel:DWORD dst_unused:UNUSED_PAD src0_sel:WORD_1 src1_sel:DWORD
	v_add3_u32 v13, v13, v14, s28
	v_add3_u32 v11, v11, v15, s28
	v_and_b32_e32 v13, 0xffff0000, v13
	v_and_b32_e32 v14, 0xffff0000, v11
	v_or_b32_sdwa v11, v13, v12 dst_sel:DWORD dst_unused:UNUSED_PAD src0_sel:DWORD src1_sel:WORD_1
	v_or_b32_sdwa v10, v14, v10 dst_sel:DWORD dst_unused:UNUSED_PAD src0_sel:DWORD src1_sel:WORD_1
	global_store_dwordx2 v[30:31], v[10:11], off offset:160
	v_and_b32_sdwa v10, v8, v177 dst_sel:DWORD dst_unused:UNUSED_PAD src0_sel:WORD_1 src1_sel:DWORD
	v_and_b32_sdwa v11, v6, v177 dst_sel:DWORD dst_unused:UNUSED_PAD src0_sel:WORD_1 src1_sel:DWORD
	v_add3_u32 v6, v6, v11, s28
	v_add3_u32 v8, v8, v10, s28
	v_and_b32_sdwa v10, v9, v177 dst_sel:DWORD dst_unused:UNUSED_PAD src0_sel:WORD_1 src1_sel:DWORD
	v_and_b32_sdwa v11, v7, v177 dst_sel:DWORD dst_unused:UNUSED_PAD src0_sel:WORD_1 src1_sel:DWORD
	v_add3_u32 v9, v9, v10, s28
	v_add3_u32 v7, v7, v11, s28
	v_and_b32_e32 v9, 0xffff0000, v9
	v_and_b32_e32 v10, 0xffff0000, v7
	v_or_b32_sdwa v7, v9, v8 dst_sel:DWORD dst_unused:UNUSED_PAD src0_sel:DWORD src1_sel:WORD_1
	v_or_b32_sdwa v6, v10, v6 dst_sel:DWORD dst_unused:UNUSED_PAD src0_sel:DWORD src1_sel:WORD_1
	global_store_dwordx2 v[30:31], v[6:7], off offset:192
	v_and_b32_sdwa v6, v4, v177 dst_sel:DWORD dst_unused:UNUSED_PAD src0_sel:WORD_1 src1_sel:DWORD
	v_and_b32_sdwa v7, v2, v177 dst_sel:DWORD dst_unused:UNUSED_PAD src0_sel:WORD_1 src1_sel:DWORD
	v_add3_u32 v2, v2, v7, s28
	v_add3_u32 v4, v4, v6, s28
	v_and_b32_sdwa v6, v5, v177 dst_sel:DWORD dst_unused:UNUSED_PAD src0_sel:WORD_1 src1_sel:DWORD
	v_and_b32_sdwa v7, v3, v177 dst_sel:DWORD dst_unused:UNUSED_PAD src0_sel:WORD_1 src1_sel:DWORD
	v_add3_u32 v5, v5, v6, s28
	v_add3_u32 v3, v3, v7, s28
	v_and_b32_e32 v5, 0xffff0000, v5
	v_and_b32_e32 v6, 0xffff0000, v3
	s_add_i32 s11, s11, s10
	v_or_b32_sdwa v3, v5, v4 dst_sel:DWORD dst_unused:UNUSED_PAD src0_sel:DWORD src1_sel:WORD_1
	v_or_b32_sdwa v2, v6, v2 dst_sel:DWORD dst_unused:UNUSED_PAD src0_sel:DWORD src1_sel:WORD_1
	s_cmpk_gt_i32 s11, 0x3ef
	global_store_dwordx2 v[30:31], v[2:3], off offset:224
	s_cbranch_scc0 .LBB0_664

.LBB0_1437:
	s_or_b64 exec, exec, s[12:13]
	s_mov_b64 s[6:7], s[60:61]
	s_waitcnt lgkmcnt(0)
	s_barrier
	s_load_dwordx2 s[6:7], s[6:7], 0x130
	v_readlane_b32 s2, v255, 44
	v_readlane_b32 s3, v255, 45
	s_mov_b64 s[14:15], -1
	s_waitcnt lgkmcnt(0)
	s_add_u32 s12, s6, 0x6035800
	s_addc_u32 s13, s7, 0
	s_add_u32 s44, s6, 0xb00000
	s_addc_u32 s45, s7, 0
	s_add_u32 s46, s6, 0x3200000
	s_addc_u32 s47, s7, 0
	s_and_b64 vcc, exec, s[2:3]
	s_cbranch_vccz .LBB0_1458
	v_mov_b32_e32 v2, v172
	s_mov_b32 s11, s42
	s_mov_b32 s14, s94
	s_cmpk_gt_i32 s14, 0x4ff
	s_cbranch_scc1 .LBB0_1443
	v_ashrrev_i32_e32 v204, 3, v2
	v_bfe_u32 v3, v2, 4, 2
	v_and_b32_e32 v4, 15, v2
	v_lshlrev_b32_e32 v0, 4, v2
	v_ashrrev_i32_e32 v5, 1, v2
	s_movk_i32 s2, 0xffc0
	v_lshlrev_b32_e32 v2, 1, v2
	v_and_b32_e32 v0, 0x70, v0
	v_and_or_b32 v205, v5, s2, v4
	v_and_b32_e32 v207, 0x80, v2
	s_movk_i32 s2, 0x90
	v_or_b32_e32 v2, v207, v4
	v_and_b32_e32 v100, 7, v204
	v_lshlrev_b32_e32 v100, 4, v100
	v_xor_b32_e32 v100, v100, v0
	v_lshl_add_u32 v166, v204, 7, v100
	v_lshl_add_u64 v[162:163], s[46:47], 0, v[0:1]
	v_lshl_add_u64 v[164:165], s[44:45], 0, v[0:1]
	v_and_b32_e32 v100, 7, v4
	v_xor_b32_e32 v100, v100, v3
	v_lshlrev_b32_e32 v206, 4, v100
	v_lshlrev_b32_e32 v208, 2, v3
	v_lshlrev_b32_e32 v0, 7, v205
	v_lshlrev_b32_e32 v167, 7, v2
	s_mov_b32 m0, s14
	s_lshr_b32 s101, m0, 6
	s_and_b32 m0, m0, 63
	s_lshl_b32 m0, m0, 19
	s_lshl_b32 s101, s101, 19
	v_readfirstlane_b32 vcc_lo, v162
	v_readfirstlane_b32 vcc_hi, v163
	v_and_b32_e32 v242, 7, v172
	v_lshlrev_b32_e32 v242, 4, v242
	v_lshl_add_u32 v242, v204, 11, v242
	s_add_u32 vcc_lo, vcc_lo, m0
	s_addc_u32 vcc_hi, vcc_hi, 0
	s_mov_b32 m0, s101
	v_readfirstlane_b32 s100, v164
	v_readfirstlane_b32 s101, v165
	s_nop 0
	s_add_u32 s100, s100, m0
	s_addc_u32 s101, s101, 0
	global_load_dwordx4 v[210:213], v242, vcc
	v_add_u32_e32 v214, s34, v242
	global_load_dwordx4 v[214:217], v214, vcc
	v_add_u32_e32 v218, s35, v242
	global_load_dwordx4 v[218:221], v218, vcc
	v_add_u32_e32 v222, s36, v242
	global_load_dwordx4 v[222:225], v222, vcc
	global_load_dwordx4 v[226:229], v242, s[100:101]
	v_add_u32_e32 v230, s34, v242
	global_load_dwordx4 v[230:233], v230, s[100:101]
	v_add_u32_e32 v234, s35, v242
	global_load_dwordx4 v[234:237], v234, s[100:101]
	v_add_u32_e32 v238, s36, v242
	global_load_dwordx4 v[238:241], v238, s[100:101]
.LBB0_1440:
	s_ashr_i32 s2, s14, 31
	s_lshr_b32 s2, s2, 26
	s_add_i32 s2, s14, s2
	s_and_b32 s3, s2, 0xffffc0
	s_sub_i32 s3, s14, s3
	s_lshl_b32 s6, s3, 8
	v_add_u32_e32 v2, s6, v204
	v_ashrrev_i32_e32 v3, 31, v2
	v_lshlrev_b64 v[2:3], 11, v[2:3]
	v_lshl_add_u64 v[168:169], v[162:163], 0, v[2:3]
	s_lshl_b32 s2, s2, 2
	v_add_co_u32_e32 v56, vcc, s34, v168
	s_and_b32 s7, s2, 0xffffff00
	s_nop 0
	v_addc_co_u32_e32 v57, vcc, 0, v169, vcc
	v_add_u32_e32 v2, s7, v204
	v_add_co_u32_e32 v58, vcc, s35, v168
	v_ashrrev_i32_e32 v3, 31, v2
	s_nop 0
	v_addc_co_u32_e32 v59, vcc, 0, v169, vcc
	v_lshlrev_b64 v[2:3], 11, v[2:3]
	v_add_co_u32_e32 v60, vcc, s36, v168
	v_lshl_add_u64 v[170:171], v[164:165], 0, v[2:3]
	s_nop 0
	v_addc_co_u32_e32 v61, vcc, 0, v169, vcc
	v_add_co_u32_e32 v62, vcc, s35, v170
	s_nop 1
	s_nop 1
	v_addc_co_u32_e32 v63, vcc, 0, v171, vcc
	v_add_co_u32_e32 v64, vcc, s36, v170
	s_nop 1
	s_nop 1
	v_addc_co_u32_e32 v65, vcc, 0, v171, vcc
	v_add_co_u32_e32 v66, vcc, s34, v170
	s_nop 1
	s_nop 1
	v_addc_co_u32_e32 v67, vcc, 0, v171, vcc
	s_nop 1
	s_nop 1
	s_barrier
	global_load_dwordx4 v[114:117], v[168:169], off offset:128
	global_load_dwordx4 v[106:109], v[56:57], off offset:128
	global_load_dwordx4 v[110:113], v[58:59], off offset:128
	global_load_dwordx4 v[126:129], v[60:61], off offset:128
	global_load_dwordx4 v[122:125], v[170:171], off offset:128
	global_load_dwordx4 v[118:121], v[66:67], off offset:128
	global_load_dwordx4 v[134:137], v[62:63], off offset:128
	global_load_dwordx4 v[130:133], v[64:65], off offset:128
	v_readfirstlane_b32 vcc_lo, v168
	v_readfirstlane_b32 vcc_hi, v169
	v_readfirstlane_b32 s100, v170
	v_readfirstlane_b32 s101, v171
	s_nop 1
	v_subrev_u32_e32 v168, vcc_lo, v168
	v_subrev_u32_e32 v170, s100, v170
	v_mov_b32_e32 v2, 0
	s_mov_b32 s4, 0
	v_mov_b32_e32 v3, v2
	v_mov_b32_e32 v4, v2
	v_mov_b32_e32 v5, v2
	v_mov_b32_e32 v6, v2
	v_mov_b32_e32 v7, v2
	v_mov_b32_e32 v8, v2
	v_mov_b32_e32 v9, v2
	v_mov_b32_e32 v10, v2
	v_mov_b32_e32 v11, v2
	v_mov_b32_e32 v12, v2
	v_mov_b32_e32 v13, v2
	v_mov_b32_e32 v14, v2
	v_mov_b32_e32 v15, v2
	v_mov_b32_e32 v16, v2
	v_mov_b32_e32 v17, v2
	v_mov_b32_e32 v18, v2
	v_mov_b32_e32 v19, v2
	v_mov_b32_e32 v20, v2
	v_mov_b32_e32 v21, v2
	v_mov_b32_e32 v22, v2
	v_mov_b32_e32 v23, v2
	v_mov_b32_e32 v56, v2
	v_mov_b32_e32 v57, v2
	v_mov_b32_e32 v58, v2
	v_mov_b32_e32 v59, v2
	v_mov_b32_e32 v60, v2
	v_mov_b32_e32 v61, v2
	v_mov_b32_e32 v62, v2
	v_mov_b32_e32 v63, v2
	v_mov_b32_e32 v64, v2
	v_mov_b32_e32 v65, v2
	v_mov_b32_e32 v66, v2
	v_mov_b32_e32 v67, v2
	v_mov_b32_e32 v68, v2
	v_mov_b32_e32 v69, v2
	v_mov_b32_e32 v70, v2
	v_mov_b32_e32 v71, v2
	v_mov_b32_e32 v72, v2
	v_mov_b32_e32 v73, v2
	v_mov_b32_e32 v74, v2
	v_mov_b32_e32 v75, v2
	v_mov_b32_e32 v76, v2
	v_mov_b32_e32 v77, v2
	v_mov_b32_e32 v78, v2
	v_mov_b32_e32 v79, v2
	v_mov_b32_e32 v80, v2
	v_mov_b32_e32 v81, v2
	v_mov_b32_e32 v82, v2
	v_mov_b32_e32 v83, v2
	v_mov_b32_e32 v84, v2
	v_mov_b32_e32 v85, v2
	s_waitcnt vmcnt(13)
	s_waitcnt vmcnt(8)
	ds_write_b128 v166, v[210:213]
	s_waitcnt vmcnt(12)
	ds_write_b128 v166, v[226:229] offset:32768
	ds_write_b128 v166, v[234:237] offset:49152
	ds_write_b128 v166, v[238:241] offset:57344
	ds_write_b128 v166, v[214:217] offset:8192
	ds_write_b128 v166, v[218:221] offset:16384
	ds_write_b128 v166, v[222:225] offset:24576
	ds_write_b128 v166, v[230:233] offset:40960
	v_mov_b32_e32 v24, v2
	v_mov_b32_e32 v25, v2
	v_mov_b32_e32 v26, v2
	v_mov_b32_e32 v27, v2
	v_mov_b32_e32 v28, v2
	v_mov_b32_e32 v29, v2
	v_mov_b32_e32 v30, v2
	v_mov_b32_e32 v31, v2
	v_mov_b32_e32 v32, v2
	v_mov_b32_e32 v33, v2
	v_mov_b32_e32 v34, v2
	v_mov_b32_e32 v35, v2
	v_mov_b32_e32 v36, v2
	v_mov_b32_e32 v37, v2
	v_mov_b32_e32 v38, v2
	v_mov_b32_e32 v39, v2
	v_mov_b32_e32 v40, v2
	v_mov_b32_e32 v41, v2
	v_mov_b32_e32 v42, v2
	v_mov_b32_e32 v43, v2
	v_mov_b32_e32 v44, v2
	v_mov_b32_e32 v45, v2
	v_mov_b32_e32 v46, v2
	v_mov_b32_e32 v47, v2
	v_mov_b32_e32 v48, v2
	v_mov_b32_e32 v49, v2
	v_mov_b32_e32 v50, v2
	v_mov_b32_e32 v51, v2
	v_mov_b32_e32 v52, v2
	v_mov_b32_e32 v53, v2
	v_mov_b32_e32 v54, v2
	v_mov_b32_e32 v55, v2
	v_mov_b32_e32 v86, v2
	v_mov_b32_e32 v87, v2
	v_mov_b32_e32 v88, v2
	v_mov_b32_e32 v89, v2
	v_mov_b32_e32 v90, v2
	v_mov_b32_e32 v91, v2
	v_mov_b32_e32 v92, v2
	v_mov_b32_e32 v93, v2
	v_mov_b32_e32 v94, v2
	v_mov_b32_e32 v95, v2
	v_mov_b32_e32 v96, v2
	v_mov_b32_e32 v97, v2
	v_mov_b32_e32 v98, v2
	v_mov_b32_e32 v99, v2
	v_mov_b32_e32 v100, v2
	v_mov_b32_e32 v101, v2
	v_mov_b32_e32 v102, v2
	v_mov_b32_e32 v103, v2
	v_mov_b32_e32 v104, v2
	v_mov_b32_e32 v105, v2
	v_mov_b32_e32 v138, v2
	v_mov_b32_e32 v139, v2
	v_mov_b32_e32 v140, v2
	v_mov_b32_e32 v141, v2
	v_mov_b32_e32 v142, v2
	v_mov_b32_e32 v143, v2
	v_mov_b32_e32 v144, v2
	v_mov_b32_e32 v145, v2
	v_mov_b32_e32 v146, v2
	v_mov_b32_e32 v147, v2
	v_mov_b32_e32 v148, v2
	v_mov_b32_e32 v149, v2
	v_mov_b32_e32 v150, v2
	v_mov_b32_e32 v151, v2
	v_mov_b32_e32 v152, v2
	v_mov_b32_e32 v153, v2
	v_mov_b32_e32 v154, v2
	v_mov_b32_e32 v155, v2
	v_mov_b32_e32 v156, v2
	v_mov_b32_e32 v157, v2
	v_mov_b32_e32 v158, v2
	v_mov_b32_e32 v159, v2
	v_mov_b32_e32 v160, v2
	v_mov_b32_e32 v161, v2
	s_waitcnt lgkmcnt(0)
	s_barrier
.LBB0_1441:
	s_bitcmp1_b32 s4, 0
	s_cselect_b32 s2, 0x12000, 0
	v_or_b32_e32 v218, s2, v206
	v_add_u32_e32 v214, v218, v0
	v_add_u32_e32 v246, v218, v167
	ds_read_b128 v[184:187], v214
	ds_read_b128 v[218:221], v246 offset:32768
	ds_read_b128 v[198:201], v214 offset:2048
	ds_read_b128 v[210:213], v214 offset:4096
	ds_read_b128 v[214:217], v214 offset:6144
	ds_read_b128 v[222:225], v246 offset:34816
	ds_read_b128 v[226:229], v246 offset:36864
	ds_read_b128 v[230:233], v246 offset:38912
	ds_read_b128 v[234:237], v246 offset:40960
	ds_read_b128 v[238:241], v246 offset:43008
	ds_read_b128 v[242:245], v246 offset:45056
	ds_read_b128 v[246:249], v246 offset:47104
	s_add_i32 s10, s4, 1
	s_bitcmp1_b32 s10, 0
	s_cselect_b32 s3, 0x12000, 0
	v_add_u32_e32 v171, s3, v166
	v_xor_b32_e32 v169, 64, v206
	v_add3_u32 v169, s2, v167, v169
	s_waitcnt lgkmcnt(10)
	v_mfma_f32_16x16x32_bf16 v[158:161], v[218:221], v[184:187], v[158:161]
	s_waitcnt lgkmcnt(9)
	v_mfma_f32_16x16x32_bf16 v[94:97], v[218:221], v[198:201], v[94:97]
	s_waitcnt lgkmcnt(8)
	v_mfma_f32_16x16x32_bf16 v[62:65], v[218:221], v[210:213], v[62:65]
	s_waitcnt lgkmcnt(7)
	v_mfma_f32_16x16x32_bf16 v[30:33], v[218:221], v[214:217], v[30:33]
	ds_read_b128 v[218:221], v169 offset:32768
	s_waitcnt lgkmcnt(7)
	v_mfma_f32_16x16x32_bf16 v[154:157], v[222:225], v[184:187], v[154:157]
	v_mfma_f32_16x16x32_bf16 v[90:93], v[222:225], v[198:201], v[90:93]
	v_mfma_f32_16x16x32_bf16 v[58:61], v[222:225], v[210:213], v[58:61]
	v_mfma_f32_16x16x32_bf16 v[26:29], v[222:225], v[214:217], v[26:29]
	ds_read_b128 v[222:225], v169 offset:34816
	s_waitcnt lgkmcnt(7)
	v_mfma_f32_16x16x32_bf16 v[150:153], v[226:229], v[184:187], v[150:153]
	v_mfma_f32_16x16x32_bf16 v[86:89], v[226:229], v[198:201], v[86:89]
	v_mfma_f32_16x16x32_bf16 v[54:57], v[226:229], v[210:213], v[54:57]
	v_mfma_f32_16x16x32_bf16 v[22:25], v[226:229], v[214:217], v[22:25]
	ds_read_b128 v[226:229], v169 offset:36864
	s_waitcnt lgkmcnt(7)
	v_mfma_f32_16x16x32_bf16 v[146:149], v[230:233], v[184:187], v[146:149]
	v_mfma_f32_16x16x32_bf16 v[82:85], v[230:233], v[198:201], v[82:85]
	v_mfma_f32_16x16x32_bf16 v[50:53], v[230:233], v[210:213], v[50:53]
	v_mfma_f32_16x16x32_bf16 v[18:21], v[230:233], v[214:217], v[18:21]
	ds_read_b128 v[230:233], v169 offset:38912
	s_waitcnt lgkmcnt(7)
	v_mfma_f32_16x16x32_bf16 v[142:145], v[234:237], v[184:187], v[142:145]
	v_mfma_f32_16x16x32_bf16 v[78:81], v[234:237], v[198:201], v[78:81]
	v_mfma_f32_16x16x32_bf16 v[46:49], v[234:237], v[210:213], v[46:49]
	v_mfma_f32_16x16x32_bf16 v[14:17], v[234:237], v[214:217], v[14:17]
	ds_read_b128 v[234:237], v169 offset:40960
	s_waitcnt lgkmcnt(7)
	v_mfma_f32_16x16x32_bf16 v[138:141], v[238:241], v[184:187], v[138:141]
	v_mfma_f32_16x16x32_bf16 v[74:77], v[238:241], v[198:201], v[74:77]
	v_mfma_f32_16x16x32_bf16 v[42:45], v[238:241], v[210:213], v[42:45]
	v_mfma_f32_16x16x32_bf16 v[10:13], v[238:241], v[214:217], v[10:13]
	ds_read_b128 v[238:241], v169 offset:43008
	s_waitcnt lgkmcnt(7)
	v_mfma_f32_16x16x32_bf16 v[102:105], v[242:245], v[184:187], v[102:105]
	v_mfma_f32_16x16x32_bf16 v[70:73], v[242:245], v[198:201], v[70:73]
	v_mfma_f32_16x16x32_bf16 v[38:41], v[242:245], v[210:213], v[38:41]
	v_mfma_f32_16x16x32_bf16 v[6:9], v[242:245], v[214:217], v[6:9]
	ds_read_b128 v[242:245], v169 offset:45056
	s_waitcnt lgkmcnt(7)
	v_mfma_f32_16x16x32_bf16 v[98:101], v[246:249], v[184:187], v[98:101]
	v_mfma_f32_16x16x32_bf16 v[66:69], v[246:249], v[198:201], v[66:69]
	v_xor_b32_e32 v169, 64, v206
	v_add3_u32 v169, s2, v0, v169
	ds_read_b128 v[184:187], v169
	ds_read_b128 v[198:201], v169 offset:2048
	v_mfma_f32_16x16x32_bf16 v[34:37], v[246:249], v[210:213], v[34:37]
	ds_read_b128 v[210:213], v169 offset:4096
	v_mfma_f32_16x16x32_bf16 v[2:5], v[246:249], v[214:217], v[2:5]
	ds_read_b128 v[214:217], v169 offset:6144
	v_xor_b32_e32 v169, 64, v206
	v_add3_u32 v169, s2, v167, v169
	ds_read_b128 v[246:249], v169 offset:47104
	s_waitcnt lgkmcnt(4)
	v_mfma_f32_16x16x32_bf16 v[158:161], v[218:221], v[184:187], v[158:161]
	s_waitcnt lgkmcnt(3)
	v_mfma_f32_16x16x32_bf16 v[94:97], v[218:221], v[198:201], v[94:97]
	s_waitcnt lgkmcnt(2)
	v_mfma_f32_16x16x32_bf16 v[62:65], v[218:221], v[210:213], v[62:65]
	s_waitcnt lgkmcnt(1)
	v_mfma_f32_16x16x32_bf16 v[30:33], v[218:221], v[214:217], v[30:33]
	s_waitcnt vmcnt(7)
	ds_write_b128 v171, v[114:117]
	v_mfma_f32_16x16x32_bf16 v[154:157], v[222:225], v[184:187], v[154:157]
	v_mfma_f32_16x16x32_bf16 v[90:93], v[222:225], v[198:201], v[90:93]
	global_load_dwordx4 v[114:117], v168, vcc offset:256
	v_mfma_f32_16x16x32_bf16 v[58:61], v[222:225], v[210:213], v[58:61]
	v_mfma_f32_16x16x32_bf16 v[26:29], v[222:225], v[214:217], v[26:29]
	s_waitcnt vmcnt(7)
	ds_write_b128 v171, v[106:109] offset:8192
	v_mfma_f32_16x16x32_bf16 v[150:153], v[226:229], v[184:187], v[150:153]
	v_mfma_f32_16x16x32_bf16 v[86:89], v[226:229], v[198:201], v[86:89]
	v_add_u32_e32 v106, s34, v168
	global_load_dwordx4 v[106:109], v106, vcc offset:256
	v_mfma_f32_16x16x32_bf16 v[54:57], v[226:229], v[210:213], v[54:57]
	v_mfma_f32_16x16x32_bf16 v[22:25], v[226:229], v[214:217], v[22:25]
	s_waitcnt vmcnt(7)
	ds_write_b128 v171, v[110:113] offset:16384
	v_mfma_f32_16x16x32_bf16 v[146:149], v[230:233], v[184:187], v[146:149]
	v_mfma_f32_16x16x32_bf16 v[82:85], v[230:233], v[198:201], v[82:85]
	v_add_u32_e32 v110, s35, v168
	global_load_dwordx4 v[110:113], v110, vcc offset:256
	v_mfma_f32_16x16x32_bf16 v[50:53], v[230:233], v[210:213], v[50:53]
	v_mfma_f32_16x16x32_bf16 v[18:21], v[230:233], v[214:217], v[18:21]
	s_waitcnt vmcnt(7)
	ds_write_b128 v171, v[126:129] offset:24576
	v_mfma_f32_16x16x32_bf16 v[142:145], v[234:237], v[184:187], v[142:145]
	v_mfma_f32_16x16x32_bf16 v[78:81], v[234:237], v[198:201], v[78:81]
	v_add_u32_e32 v126, s36, v168
	global_load_dwordx4 v[126:129], v126, vcc offset:256
	v_mfma_f32_16x16x32_bf16 v[46:49], v[234:237], v[210:213], v[46:49]
	v_mfma_f32_16x16x32_bf16 v[14:17], v[234:237], v[214:217], v[14:17]
	s_waitcnt vmcnt(7)
	ds_write_b128 v171, v[122:125] offset:32768
	v_mfma_f32_16x16x32_bf16 v[138:141], v[238:241], v[184:187], v[138:141]
	v_mfma_f32_16x16x32_bf16 v[74:77], v[238:241], v[198:201], v[74:77]
	global_load_dwordx4 v[122:125], v170, s[100:101] offset:256
	v_mfma_f32_16x16x32_bf16 v[42:45], v[238:241], v[210:213], v[42:45]
	v_mfma_f32_16x16x32_bf16 v[10:13], v[238:241], v[214:217], v[10:13]
	s_waitcnt vmcnt(7)
	ds_write_b128 v171, v[118:121] offset:40960
	v_mfma_f32_16x16x32_bf16 v[102:105], v[242:245], v[184:187], v[102:105]
	v_mfma_f32_16x16x32_bf16 v[70:73], v[242:245], v[198:201], v[70:73]
	v_add_u32_e32 v118, s34, v170
	global_load_dwordx4 v[118:121], v118, s[100:101] offset:256
	v_mfma_f32_16x16x32_bf16 v[38:41], v[242:245], v[210:213], v[38:41]
	v_mfma_f32_16x16x32_bf16 v[6:9], v[242:245], v[214:217], v[6:9]
	s_waitcnt vmcnt(7)
	ds_write_b128 v171, v[134:137] offset:49152
	s_waitcnt lgkmcnt(7)
	v_mfma_f32_16x16x32_bf16 v[98:101], v[246:249], v[184:187], v[98:101]
	v_mfma_f32_16x16x32_bf16 v[66:69], v[246:249], v[198:201], v[66:69]
	v_add_u32_e32 v134, s35, v170
	global_load_dwordx4 v[134:137], v134, s[100:101] offset:256
	v_mfma_f32_16x16x32_bf16 v[34:37], v[246:249], v[210:213], v[34:37]
	v_mfma_f32_16x16x32_bf16 v[2:5], v[246:249], v[214:217], v[2:5]
	s_waitcnt vmcnt(7)
	ds_write_b128 v171, v[130:133] offset:57344
	v_add_u32_e32 v130, s36, v170
	global_load_dwordx4 v[130:133], v130, s[100:101] offset:256
	v_add_u32_e32 v168, 0x80, v168
	v_add_u32_e32 v170, 0x80, v170
	s_waitcnt lgkmcnt(0)
	s_barrier
	s_cmp_eq_u32 s10, 16
	s_mov_b32 s4, s10
	s_cbranch_scc0 .LBB0_1441
	s_add_i32 m0, s14, s11
	s_cmpk_lt_i32 m0, 0x500
	s_cselect_b32 m0, m0, s14
	s_lshr_b32 s101, m0, 6
	s_and_b32 m0, m0, 63
	s_lshl_b32 m0, m0, 19
	s_lshl_b32 s101, s101, 19
	v_readfirstlane_b32 vcc_lo, v162
	v_readfirstlane_b32 vcc_hi, v163
	v_and_b32_e32 v242, 7, v172
	v_lshlrev_b32_e32 v242, 4, v242
	v_lshl_add_u32 v242, v204, 11, v242
	s_add_u32 vcc_lo, vcc_lo, m0
	s_addc_u32 vcc_hi, vcc_hi, 0
	s_mov_b32 m0, s101
	v_readfirstlane_b32 s100, v164
	v_readfirstlane_b32 s101, v165
	s_nop 0
	s_add_u32 s100, s100, m0
	s_addc_u32 s101, s101, 0
	global_load_dwordx4 v[210:213], v242, vcc
	v_add_u32_e32 v214, s34, v242
	global_load_dwordx4 v[214:217], v214, vcc
	v_add_u32_e32 v218, s35, v242
	global_load_dwordx4 v[218:221], v218, vcc
	v_add_u32_e32 v222, s36, v242
	global_load_dwordx4 v[222:225], v222, vcc
	global_load_dwordx4 v[226:229], v242, s[100:101]
	v_add_u32_e32 v230, s34, v242
	global_load_dwordx4 v[230:233], v230, s[100:101]
	v_add_u32_e32 v234, s35, v242
	global_load_dwordx4 v[234:237], v234, s[100:101]
	v_add_u32_e32 v238, s36, v242
	global_load_dwordx4 v[238:241], v238, s[100:101]
	s_waitcnt vmcnt(12)
	v_mul_f32_e32 v109, 0xbfb8aa3b, v158
	v_exp_f32_e32 v109, v109
	s_waitcnt vmcnt(11)
	v_mul_f32_e32 v111, 0xbfb8aa3b, v159
	v_exp_f32_e32 v111, v111
	v_mul_f32_e32 v115, 0xbfb8aa3b, v161
	v_add_f32_e32 v109, 1.0, v109
	v_rcp_f32_e32 v114, v109
	v_add_f32_e32 v109, 1.0, v111
	v_mul_f32_e32 v111, 0xbfb8aa3b, v160
	v_exp_f32_e32 v111, v111
	v_exp_f32_e32 v117, v115
	v_rcp_f32_e32 v116, v109
	s_waitcnt vmcnt(10)
	v_mov_b32_e32 v118, v158
	v_add_f32_e32 v109, 1.0, v111
	v_rcp_f32_e32 v115, v109
	v_add_f32_e32 v109, 1.0, v117
	v_rcp_f32_e32 v117, v109
	v_mov_b32_e32 v119, v160
	v_pk_mul_f32 v[114:115], v[118:119], v[114:115]
	v_mov_b32_e32 v118, v154
	v_mov_b32_e32 v119, v156
	v_mov_b32_e32 v160, v159
	v_pk_mul_f32 v[114:115], v[118:119], v[114:115]
	v_pk_mul_f32 v[116:117], v[160:161], v[116:117]
	v_mov_b32_e32 v156, v155
	v_pk_mul_f32 v[116:117], v[156:157], v[116:117]
	v_and_b32_sdwa v111, v115, v177 dst_sel:DWORD dst_unused:UNUSED_PAD src0_sel:WORD_1 src1_sel:DWORD
	v_and_b32_sdwa v118, v114, v177 dst_sel:DWORD dst_unused:UNUSED_PAD src0_sel:WORD_1 src1_sel:DWORD
	v_add3_u32 v111, v115, v111, s28
	v_and_b32_sdwa v115, v117, v177 dst_sel:DWORD dst_unused:UNUSED_PAD src0_sel:WORD_1 src1_sel:DWORD
	v_add3_u32 v114, v114, v118, s28
	v_and_b32_sdwa v118, v116, v177 dst_sel:DWORD dst_unused:UNUSED_PAD src0_sel:WORD_1 src1_sel:DWORD
	v_add3_u32 v115, v117, v115, s28
	v_or_b32_e32 v106, s7, v207
	v_add3_u32 v116, v116, v118, s28
	v_and_b32_e32 v115, 0xffff0000, v115
	v_ashrrev_i32_e32 v106, 1, v106
	v_and_b32_e32 v116, 0xffff0000, v116
	v_or_b32_sdwa v115, v115, v111 dst_sel:DWORD dst_unused:UNUSED_PAD src0_sel:DWORD src1_sel:WORD_1
	v_mul_f32_e32 v111, 0xbfb8aa3b, v150
	v_or_b32_e32 v108, v106, v208
	v_or_b32_sdwa v114, v116, v114 dst_sel:DWORD dst_unused:UNUSED_PAD src0_sel:DWORD src1_sel:WORD_1
	v_exp_f32_e32 v111, v111
	v_mul_f32_e32 v116, 0xbfb8aa3b, v151
	v_add_u32_e32 v110, s6, v205
	v_mov_b64_e32 v[106:107], s[12:13]
	v_ashrrev_i32_e32 v109, 31, v108
	v_exp_f32_e32 v116, v116
	v_mad_i64_i32 v[112:113], s[6:7], v110, s52, v[106:107]
	v_lshlrev_b64 v[108:109], 1, v[108:109]
	v_lshl_add_u64 v[112:113], v[112:113], 0, v[108:109]
	s_waitcnt vmcnt(8)
	global_store_dwordx2 v[112:113], v[114:115], off
	v_add_f32_e32 v111, 1.0, v111
	v_mul_f32_e32 v115, 0xbfb8aa3b, v152
	v_rcp_f32_e32 v114, v111
	v_add_f32_e32 v111, 1.0, v116
	v_exp_f32_e32 v115, v115
	v_mul_f32_e32 v116, 0xbfb8aa3b, v153
	v_exp_f32_e32 v117, v116
	v_rcp_f32_e32 v116, v111
	v_add_f32_e32 v111, 1.0, v115
	v_rcp_f32_e32 v115, v111
	v_add_f32_e32 v111, 1.0, v117
	v_rcp_f32_e32 v117, v111
	v_mov_b32_e32 v118, v150
	v_mov_b32_e32 v119, v152
	v_pk_mul_f32 v[114:115], v[118:119], v[114:115]
	v_mov_b32_e32 v118, v146
	v_mov_b32_e32 v119, v148
	v_mov_b32_e32 v152, v151
	v_pk_mul_f32 v[114:115], v[118:119], v[114:115]
	v_pk_mul_f32 v[116:117], v[152:153], v[116:117]
	v_mov_b32_e32 v148, v147
	v_pk_mul_f32 v[116:117], v[148:149], v[116:117]
	v_and_b32_sdwa v111, v115, v177 dst_sel:DWORD dst_unused:UNUSED_PAD src0_sel:WORD_1 src1_sel:DWORD
	v_and_b32_sdwa v118, v114, v177 dst_sel:DWORD dst_unused:UNUSED_PAD src0_sel:WORD_1 src1_sel:DWORD
	v_add3_u32 v111, v115, v111, s28
	v_and_b32_sdwa v115, v117, v177 dst_sel:DWORD dst_unused:UNUSED_PAD src0_sel:WORD_1 src1_sel:DWORD
	v_add3_u32 v114, v114, v118, s28
	v_and_b32_sdwa v118, v116, v177 dst_sel:DWORD dst_unused:UNUSED_PAD src0_sel:WORD_1 src1_sel:DWORD
	v_add3_u32 v115, v117, v115, s28
	v_add3_u32 v116, v116, v118, s28
	v_and_b32_e32 v115, 0xffff0000, v115
	v_and_b32_e32 v116, 0xffff0000, v116
	v_or_b32_sdwa v115, v115, v111 dst_sel:DWORD dst_unused:UNUSED_PAD src0_sel:DWORD src1_sel:WORD_1
	v_mul_f32_e32 v111, 0xbfb8aa3b, v142
	v_or_b32_sdwa v114, v116, v114 dst_sel:DWORD dst_unused:UNUSED_PAD src0_sel:DWORD src1_sel:WORD_1
	v_exp_f32_e32 v111, v111
	v_mul_f32_e32 v116, 0xbfb8aa3b, v143
	v_exp_f32_e32 v116, v116
	global_store_dwordx2 v[112:113], v[114:115], off offset:32
	v_add_f32_e32 v111, 1.0, v111
	v_mul_f32_e32 v115, 0xbfb8aa3b, v144
	v_rcp_f32_e32 v114, v111
	v_add_f32_e32 v111, 1.0, v116
	v_exp_f32_e32 v115, v115
	v_mul_f32_e32 v116, 0xbfb8aa3b, v145
	v_exp_f32_e32 v117, v116
	v_rcp_f32_e32 v116, v111
	v_add_f32_e32 v111, 1.0, v115
	v_rcp_f32_e32 v115, v111
	v_add_f32_e32 v111, 1.0, v117
	v_rcp_f32_e32 v117, v111
	v_mov_b32_e32 v118, v142
	v_mov_b32_e32 v119, v144
	v_pk_mul_f32 v[114:115], v[118:119], v[114:115]
	v_mov_b32_e32 v118, v138
	v_mov_b32_e32 v119, v140
	v_mov_b32_e32 v144, v143
	v_pk_mul_f32 v[114:115], v[118:119], v[114:115]
	v_pk_mul_f32 v[116:117], v[144:145], v[116:117]
	v_mov_b32_e32 v140, v139
	v_pk_mul_f32 v[116:117], v[140:141], v[116:117]
	v_and_b32_sdwa v111, v115, v177 dst_sel:DWORD dst_unused:UNUSED_PAD src0_sel:WORD_1 src1_sel:DWORD
	v_and_b32_sdwa v118, v114, v177 dst_sel:DWORD dst_unused:UNUSED_PAD src0_sel:WORD_1 src1_sel:DWORD
	v_add3_u32 v111, v115, v111, s28
	v_and_b32_sdwa v115, v117, v177 dst_sel:DWORD dst_unused:UNUSED_PAD src0_sel:WORD_1 src1_sel:DWORD
	v_add3_u32 v114, v114, v118, s28
	v_and_b32_sdwa v118, v116, v177 dst_sel:DWORD dst_unused:UNUSED_PAD src0_sel:WORD_1 src1_sel:DWORD
	v_add3_u32 v115, v117, v115, s28
	v_add3_u32 v116, v116, v118, s28
	v_and_b32_e32 v115, 0xffff0000, v115
	v_and_b32_e32 v116, 0xffff0000, v116
	v_or_b32_sdwa v115, v115, v111 dst_sel:DWORD dst_unused:UNUSED_PAD src0_sel:DWORD src1_sel:WORD_1
	v_mul_f32_e32 v111, 0xbfb8aa3b, v102
	v_or_b32_sdwa v114, v116, v114 dst_sel:DWORD dst_unused:UNUSED_PAD src0_sel:DWORD src1_sel:WORD_1
	v_exp_f32_e32 v111, v111
	v_mul_f32_e32 v116, 0xbfb8aa3b, v103
	v_exp_f32_e32 v116, v116
	global_store_dwordx2 v[112:113], v[114:115], off offset:64
	v_add_f32_e32 v111, 1.0, v111
	v_mul_f32_e32 v115, 0xbfb8aa3b, v104
	v_rcp_f32_e32 v114, v111
	v_add_f32_e32 v111, 1.0, v116
	v_exp_f32_e32 v115, v115
	v_mul_f32_e32 v116, 0xbfb8aa3b, v105
	v_exp_f32_e32 v117, v116
	v_rcp_f32_e32 v116, v111
	v_add_f32_e32 v111, 1.0, v115
	v_rcp_f32_e32 v115, v111
	v_add_f32_e32 v111, 1.0, v117
	v_rcp_f32_e32 v117, v111
	v_mov_b32_e32 v118, v102
	v_mov_b32_e32 v119, v104
	v_mov_b32_e32 v104, v103
	v_pk_mul_f32 v[114:115], v[118:119], v[114:115]
	v_mov_b32_e32 v119, v100
	v_pk_mul_f32 v[102:103], v[104:105], v[116:117]
	v_mov_b32_e32 v100, v99
	v_mov_b32_e32 v118, v98
	v_pk_mul_f32 v[98:99], v[100:101], v[102:103]
	v_pk_mul_f32 v[114:115], v[118:119], v[114:115]
	v_and_b32_sdwa v102, v99, v177 dst_sel:DWORD dst_unused:UNUSED_PAD src0_sel:WORD_1 src1_sel:DWORD
	v_and_b32_sdwa v103, v98, v177 dst_sel:DWORD dst_unused:UNUSED_PAD src0_sel:WORD_1 src1_sel:DWORD
	v_and_b32_sdwa v100, v115, v177 dst_sel:DWORD dst_unused:UNUSED_PAD src0_sel:WORD_1 src1_sel:DWORD
	v_and_b32_sdwa v101, v114, v177 dst_sel:DWORD dst_unused:UNUSED_PAD src0_sel:WORD_1 src1_sel:DWORD
	v_add3_u32 v99, v99, v102, s28
	v_add3_u32 v98, v98, v103, s28
	v_add3_u32 v101, v114, v101, s28
	v_add3_u32 v100, v115, v100, s28
	v_and_b32_e32 v99, 0xffff0000, v99
	v_and_b32_e32 v98, 0xffff0000, v98
	v_or_b32_sdwa v99, v99, v100 dst_sel:DWORD dst_unused:UNUSED_PAD src0_sel:DWORD src1_sel:WORD_1
	v_or_b32_sdwa v98, v98, v101 dst_sel:DWORD dst_unused:UNUSED_PAD src0_sel:DWORD src1_sel:WORD_1
	global_store_dwordx2 v[112:113], v[98:99], off offset:96
	v_mul_f32_e32 v99, 0xbfb8aa3b, v94
	v_exp_f32_e32 v100, v99
	v_mul_f32_e32 v99, 0xbfb8aa3b, v95
	v_mul_f32_e32 v102, 0xbfb8aa3b, v96
	v_exp_f32_e32 v101, v99
	v_exp_f32_e32 v103, v102
	v_mul_f32_e32 v102, 0xbfb8aa3b, v97
	v_exp_f32_e32 v104, v102
	v_add_f32_e32 v101, 1.0, v101
	v_add_f32_e32 v100, 1.0, v100
	v_rcp_f32_e32 v102, v101
	v_add_f32_e32 v101, 1.0, v103
	v_add_f32_e32 v103, 1.0, v104
	v_rcp_f32_e32 v100, v100
	v_rcp_f32_e32 v101, v101
	v_rcp_f32_e32 v103, v103
	v_mov_b32_e32 v104, v94
	v_mov_b32_e32 v105, v96
	v_mov_b32_e32 v96, v95
	v_pk_mul_f32 v[100:101], v[104:105], v[100:101]
	v_mov_b32_e32 v105, v92
	v_pk_mul_f32 v[94:95], v[96:97], v[102:103]
	v_mov_b32_e32 v92, v91
	v_mov_b32_e32 v104, v90
	v_pk_mul_f32 v[90:91], v[92:93], v[94:95]
	v_pk_mul_f32 v[100:101], v[104:105], v[100:101]
	v_and_b32_sdwa v94, v91, v177 dst_sel:DWORD dst_unused:UNUSED_PAD src0_sel:WORD_1 src1_sel:DWORD
	v_and_b32_sdwa v92, v101, v177 dst_sel:DWORD dst_unused:UNUSED_PAD src0_sel:WORD_1 src1_sel:DWORD
	v_and_b32_sdwa v95, v90, v177 dst_sel:DWORD dst_unused:UNUSED_PAD src0_sel:WORD_1 src1_sel:DWORD
	v_add3_u32 v91, v91, v94, s28
	v_and_b32_sdwa v93, v100, v177 dst_sel:DWORD dst_unused:UNUSED_PAD src0_sel:WORD_1 src1_sel:DWORD
	v_add3_u32 v92, v101, v92, s28
	v_add3_u32 v90, v90, v95, s28
	v_and_b32_e32 v91, 0xffff0000, v91
	v_add3_u32 v93, v100, v93, s28
	v_and_b32_e32 v90, 0xffff0000, v90
	v_or_b32_sdwa v91, v91, v92 dst_sel:DWORD dst_unused:UNUSED_PAD src0_sel:DWORD src1_sel:WORD_1
	v_mul_f32_e32 v92, 0xbfb8aa3b, v86
	v_or_b32_sdwa v90, v90, v93 dst_sel:DWORD dst_unused:UNUSED_PAD src0_sel:DWORD src1_sel:WORD_1
	v_exp_f32_e32 v92, v92
	v_mul_f32_e32 v93, 0xbfb8aa3b, v87
	v_or_b32_e32 v98, 16, v110
	v_exp_f32_e32 v93, v93
	v_mad_i64_i32 v[98:99], s[6:7], v98, s52, v[106:107]
	v_lshl_add_u64 v[98:99], v[98:99], 0, v[108:109]
	global_store_dwordx2 v[98:99], v[90:91], off
	v_add_f32_e32 v90, 1.0, v92
	v_mul_f32_e32 v92, 0xbfb8aa3b, v88
	v_add_f32_e32 v91, 1.0, v93
	v_exp_f32_e32 v93, v92
	v_mul_f32_e32 v92, 0xbfb8aa3b, v89
	v_exp_f32_e32 v94, v92
	v_rcp_f32_e32 v92, v91
	v_add_f32_e32 v91, 1.0, v93
	v_rcp_f32_e32 v90, v90
	v_add_f32_e32 v93, 1.0, v94
	v_rcp_f32_e32 v91, v91
	v_rcp_f32_e32 v93, v93
	v_mov_b32_e32 v94, v86
	v_mov_b32_e32 v95, v88
	v_mov_b32_e32 v88, v87
	v_pk_mul_f32 v[90:91], v[94:95], v[90:91]
	v_mov_b32_e32 v95, v84
	v_pk_mul_f32 v[86:87], v[88:89], v[92:93]
	v_mov_b32_e32 v84, v83
	v_mov_b32_e32 v94, v82
	v_pk_mul_f32 v[82:83], v[84:85], v[86:87]
	v_pk_mul_f32 v[90:91], v[94:95], v[90:91]
	v_and_b32_sdwa v86, v83, v177 dst_sel:DWORD dst_unused:UNUSED_PAD src0_sel:WORD_1 src1_sel:DWORD
	v_and_b32_sdwa v84, v91, v177 dst_sel:DWORD dst_unused:UNUSED_PAD src0_sel:WORD_1 src1_sel:DWORD
	v_and_b32_sdwa v87, v82, v177 dst_sel:DWORD dst_unused:UNUSED_PAD src0_sel:WORD_1 src1_sel:DWORD
	v_add3_u32 v83, v83, v86, s28
	v_and_b32_sdwa v85, v90, v177 dst_sel:DWORD dst_unused:UNUSED_PAD src0_sel:WORD_1 src1_sel:DWORD
	v_add3_u32 v84, v91, v84, s28
	v_add3_u32 v82, v82, v87, s28
	v_and_b32_e32 v83, 0xffff0000, v83
	v_add3_u32 v85, v90, v85, s28
	v_and_b32_e32 v82, 0xffff0000, v82
	v_or_b32_sdwa v83, v83, v84 dst_sel:DWORD dst_unused:UNUSED_PAD src0_sel:DWORD src1_sel:WORD_1
	v_mul_f32_e32 v84, 0xbfb8aa3b, v78
	v_or_b32_sdwa v82, v82, v85 dst_sel:DWORD dst_unused:UNUSED_PAD src0_sel:DWORD src1_sel:WORD_1
	v_exp_f32_e32 v84, v84
	v_mul_f32_e32 v85, 0xbfb8aa3b, v79
	v_exp_f32_e32 v85, v85
	global_store_dwordx2 v[98:99], v[82:83], off offset:32
	v_add_f32_e32 v82, 1.0, v84
	v_mul_f32_e32 v84, 0xbfb8aa3b, v80
	v_add_f32_e32 v83, 1.0, v85
	v_exp_f32_e32 v85, v84
	v_mul_f32_e32 v84, 0xbfb8aa3b, v81
	v_exp_f32_e32 v86, v84
	v_rcp_f32_e32 v84, v83
	v_add_f32_e32 v83, 1.0, v85
	v_rcp_f32_e32 v82, v82
	v_add_f32_e32 v85, 1.0, v86
	v_rcp_f32_e32 v83, v83
	v_rcp_f32_e32 v85, v85
	v_mov_b32_e32 v86, v78
	v_mov_b32_e32 v87, v80
	v_mov_b32_e32 v80, v79
	v_pk_mul_f32 v[82:83], v[86:87], v[82:83]
	v_mov_b32_e32 v87, v76
	v_pk_mul_f32 v[78:79], v[80:81], v[84:85]
	v_mov_b32_e32 v76, v75
	v_mov_b32_e32 v86, v74
	v_pk_mul_f32 v[74:75], v[76:77], v[78:79]
	v_pk_mul_f32 v[82:83], v[86:87], v[82:83]
	v_and_b32_sdwa v78, v75, v177 dst_sel:DWORD dst_unused:UNUSED_PAD src0_sel:WORD_1 src1_sel:DWORD
	v_and_b32_sdwa v76, v83, v177 dst_sel:DWORD dst_unused:UNUSED_PAD src0_sel:WORD_1 src1_sel:DWORD
	v_and_b32_sdwa v79, v74, v177 dst_sel:DWORD dst_unused:UNUSED_PAD src0_sel:WORD_1 src1_sel:DWORD
	v_add3_u32 v75, v75, v78, s28
	v_and_b32_sdwa v77, v82, v177 dst_sel:DWORD dst_unused:UNUSED_PAD src0_sel:WORD_1 src1_sel:DWORD
	v_add3_u32 v76, v83, v76, s28
	v_add3_u32 v74, v74, v79, s28
	v_and_b32_e32 v75, 0xffff0000, v75
	v_add3_u32 v77, v82, v77, s28
	v_and_b32_e32 v74, 0xffff0000, v74
	v_or_b32_sdwa v75, v75, v76 dst_sel:DWORD dst_unused:UNUSED_PAD src0_sel:DWORD src1_sel:WORD_1
	v_mul_f32_e32 v76, 0xbfb8aa3b, v70
	v_or_b32_sdwa v74, v74, v77 dst_sel:DWORD dst_unused:UNUSED_PAD src0_sel:DWORD src1_sel:WORD_1
	v_exp_f32_e32 v76, v76
	v_mul_f32_e32 v77, 0xbfb8aa3b, v71
	v_exp_f32_e32 v77, v77
	global_store_dwordx2 v[98:99], v[74:75], off offset:64
	v_add_f32_e32 v74, 1.0, v76
	v_mul_f32_e32 v76, 0xbfb8aa3b, v72
	v_add_f32_e32 v75, 1.0, v77
	v_exp_f32_e32 v77, v76
	v_mul_f32_e32 v76, 0xbfb8aa3b, v73
	v_exp_f32_e32 v78, v76
	v_rcp_f32_e32 v76, v75
	v_add_f32_e32 v75, 1.0, v77
	v_rcp_f32_e32 v74, v74
	v_add_f32_e32 v77, 1.0, v78
	v_rcp_f32_e32 v75, v75
	v_rcp_f32_e32 v77, v77
	v_mov_b32_e32 v78, v70
	v_mov_b32_e32 v79, v72
	v_mov_b32_e32 v72, v71
	v_pk_mul_f32 v[74:75], v[78:79], v[74:75]
	v_mov_b32_e32 v79, v68
	v_pk_mul_f32 v[70:71], v[72:73], v[76:77]
	v_mov_b32_e32 v68, v67
	v_mov_b32_e32 v78, v66
	v_pk_mul_f32 v[66:67], v[68:69], v[70:71]
	v_pk_mul_f32 v[74:75], v[78:79], v[74:75]
	v_and_b32_sdwa v70, v67, v177 dst_sel:DWORD dst_unused:UNUSED_PAD src0_sel:WORD_1 src1_sel:DWORD
	v_and_b32_sdwa v71, v66, v177 dst_sel:DWORD dst_unused:UNUSED_PAD src0_sel:WORD_1 src1_sel:DWORD
	v_and_b32_sdwa v68, v75, v177 dst_sel:DWORD dst_unused:UNUSED_PAD src0_sel:WORD_1 src1_sel:DWORD
	v_and_b32_sdwa v69, v74, v177 dst_sel:DWORD dst_unused:UNUSED_PAD src0_sel:WORD_1 src1_sel:DWORD
	v_add3_u32 v67, v67, v70, s28
	v_add3_u32 v66, v66, v71, s28
	v_add3_u32 v69, v74, v69, s28
	v_add3_u32 v68, v75, v68, s28
	v_and_b32_e32 v67, 0xffff0000, v67
	v_and_b32_e32 v66, 0xffff0000, v66
	v_or_b32_sdwa v67, v67, v68 dst_sel:DWORD dst_unused:UNUSED_PAD src0_sel:DWORD src1_sel:WORD_1
	v_or_b32_sdwa v66, v66, v69 dst_sel:DWORD dst_unused:UNUSED_PAD src0_sel:DWORD src1_sel:WORD_1
	global_store_dwordx2 v[98:99], v[66:67], off offset:96
	v_mul_f32_e32 v67, 0xbfb8aa3b, v62
	v_exp_f32_e32 v68, v67
	v_mul_f32_e32 v67, 0xbfb8aa3b, v63
	v_mul_f32_e32 v70, 0xbfb8aa3b, v64
	v_exp_f32_e32 v69, v67
	v_exp_f32_e32 v71, v70
	v_mul_f32_e32 v70, 0xbfb8aa3b, v65
	v_exp_f32_e32 v72, v70
	v_add_f32_e32 v69, 1.0, v69
	v_add_f32_e32 v68, 1.0, v68
	v_rcp_f32_e32 v70, v69
	v_add_f32_e32 v69, 1.0, v71
	v_add_f32_e32 v71, 1.0, v72
	v_rcp_f32_e32 v68, v68
	v_rcp_f32_e32 v69, v69
	v_rcp_f32_e32 v71, v71
	v_mov_b32_e32 v72, v62
	v_mov_b32_e32 v73, v64
	v_mov_b32_e32 v64, v63
	v_pk_mul_f32 v[68:69], v[72:73], v[68:69]
	v_mov_b32_e32 v73, v60
	v_pk_mul_f32 v[62:63], v[64:65], v[70:71]
	v_mov_b32_e32 v60, v59
	v_mov_b32_e32 v72, v58
	v_pk_mul_f32 v[58:59], v[60:61], v[62:63]
	v_pk_mul_f32 v[68:69], v[72:73], v[68:69]
	v_and_b32_sdwa v62, v59, v177 dst_sel:DWORD dst_unused:UNUSED_PAD src0_sel:WORD_1 src1_sel:DWORD
	v_and_b32_sdwa v60, v69, v177 dst_sel:DWORD dst_unused:UNUSED_PAD src0_sel:WORD_1 src1_sel:DWORD
	v_and_b32_sdwa v63, v58, v177 dst_sel:DWORD dst_unused:UNUSED_PAD src0_sel:WORD_1 src1_sel:DWORD
	v_add3_u32 v59, v59, v62, s28
	v_and_b32_sdwa v61, v68, v177 dst_sel:DWORD dst_unused:UNUSED_PAD src0_sel:WORD_1 src1_sel:DWORD
	v_add3_u32 v60, v69, v60, s28
	v_add3_u32 v58, v58, v63, s28
	v_and_b32_e32 v59, 0xffff0000, v59
	v_add3_u32 v61, v68, v61, s28
	v_and_b32_e32 v58, 0xffff0000, v58
	v_or_b32_sdwa v59, v59, v60 dst_sel:DWORD dst_unused:UNUSED_PAD src0_sel:DWORD src1_sel:WORD_1
	v_mul_f32_e32 v60, 0xbfb8aa3b, v54
	v_or_b32_sdwa v58, v58, v61 dst_sel:DWORD dst_unused:UNUSED_PAD src0_sel:DWORD src1_sel:WORD_1
	v_exp_f32_e32 v60, v60
	v_mul_f32_e32 v61, 0xbfb8aa3b, v55
	v_or_b32_e32 v66, 32, v110
	v_exp_f32_e32 v61, v61
	v_mad_i64_i32 v[66:67], s[6:7], v66, s52, v[106:107]
	v_lshl_add_u64 v[66:67], v[66:67], 0, v[108:109]
	global_store_dwordx2 v[66:67], v[58:59], off
	v_add_f32_e32 v58, 1.0, v60
	v_mul_f32_e32 v60, 0xbfb8aa3b, v56
	v_add_f32_e32 v59, 1.0, v61
	v_exp_f32_e32 v61, v60
	v_mul_f32_e32 v60, 0xbfb8aa3b, v57
	v_exp_f32_e32 v62, v60
	v_rcp_f32_e32 v60, v59
	v_add_f32_e32 v59, 1.0, v61
	v_rcp_f32_e32 v58, v58
	v_add_f32_e32 v61, 1.0, v62
	v_rcp_f32_e32 v59, v59
	v_rcp_f32_e32 v61, v61
	v_mov_b32_e32 v62, v54
	v_mov_b32_e32 v63, v56
	v_mov_b32_e32 v56, v55
	v_pk_mul_f32 v[58:59], v[62:63], v[58:59]
	v_mov_b32_e32 v63, v52
	v_pk_mul_f32 v[54:55], v[56:57], v[60:61]
	v_mov_b32_e32 v52, v51
	v_mov_b32_e32 v62, v50
	v_pk_mul_f32 v[50:51], v[52:53], v[54:55]
	v_pk_mul_f32 v[58:59], v[62:63], v[58:59]
	v_and_b32_sdwa v54, v51, v177 dst_sel:DWORD dst_unused:UNUSED_PAD src0_sel:WORD_1 src1_sel:DWORD
	v_and_b32_sdwa v52, v59, v177 dst_sel:DWORD dst_unused:UNUSED_PAD src0_sel:WORD_1 src1_sel:DWORD
	v_and_b32_sdwa v55, v50, v177 dst_sel:DWORD dst_unused:UNUSED_PAD src0_sel:WORD_1 src1_sel:DWORD
	v_add3_u32 v51, v51, v54, s28
	v_and_b32_sdwa v53, v58, v177 dst_sel:DWORD dst_unused:UNUSED_PAD src0_sel:WORD_1 src1_sel:DWORD
	v_add3_u32 v52, v59, v52, s28
	v_add3_u32 v50, v50, v55, s28
	v_and_b32_e32 v51, 0xffff0000, v51
	v_add3_u32 v53, v58, v53, s28
	v_and_b32_e32 v50, 0xffff0000, v50
	v_or_b32_sdwa v51, v51, v52 dst_sel:DWORD dst_unused:UNUSED_PAD src0_sel:DWORD src1_sel:WORD_1
	v_mul_f32_e32 v52, 0xbfb8aa3b, v46
	v_or_b32_sdwa v50, v50, v53 dst_sel:DWORD dst_unused:UNUSED_PAD src0_sel:DWORD src1_sel:WORD_1
	v_exp_f32_e32 v52, v52
	v_mul_f32_e32 v53, 0xbfb8aa3b, v47
	v_exp_f32_e32 v53, v53
	global_store_dwordx2 v[66:67], v[50:51], off offset:32
	v_add_f32_e32 v50, 1.0, v52
	v_mul_f32_e32 v52, 0xbfb8aa3b, v48
	v_add_f32_e32 v51, 1.0, v53
	v_exp_f32_e32 v53, v52
	v_mul_f32_e32 v52, 0xbfb8aa3b, v49
	v_exp_f32_e32 v54, v52
	v_rcp_f32_e32 v52, v51
	v_add_f32_e32 v51, 1.0, v53
	v_rcp_f32_e32 v50, v50
	v_add_f32_e32 v53, 1.0, v54
	v_rcp_f32_e32 v51, v51
	v_rcp_f32_e32 v53, v53
	v_mov_b32_e32 v54, v46
	v_mov_b32_e32 v55, v48
	v_mov_b32_e32 v48, v47
	v_pk_mul_f32 v[50:51], v[54:55], v[50:51]
	v_mov_b32_e32 v55, v44
	v_pk_mul_f32 v[46:47], v[48:49], v[52:53]
	v_mov_b32_e32 v44, v43
	v_mov_b32_e32 v54, v42
	v_pk_mul_f32 v[42:43], v[44:45], v[46:47]
	v_pk_mul_f32 v[50:51], v[54:55], v[50:51]
	v_and_b32_sdwa v46, v43, v177 dst_sel:DWORD dst_unused:UNUSED_PAD src0_sel:WORD_1 src1_sel:DWORD
	v_and_b32_sdwa v44, v51, v177 dst_sel:DWORD dst_unused:UNUSED_PAD src0_sel:WORD_1 src1_sel:DWORD
	v_and_b32_sdwa v47, v42, v177 dst_sel:DWORD dst_unused:UNUSED_PAD src0_sel:WORD_1 src1_sel:DWORD
	v_add3_u32 v43, v43, v46, s28
	v_and_b32_sdwa v45, v50, v177 dst_sel:DWORD dst_unused:UNUSED_PAD src0_sel:WORD_1 src1_sel:DWORD
	v_add3_u32 v44, v51, v44, s28
	v_add3_u32 v42, v42, v47, s28
	v_and_b32_e32 v43, 0xffff0000, v43
	v_add3_u32 v45, v50, v45, s28
	v_and_b32_e32 v42, 0xffff0000, v42
	v_or_b32_sdwa v43, v43, v44 dst_sel:DWORD dst_unused:UNUSED_PAD src0_sel:DWORD src1_sel:WORD_1
	v_mul_f32_e32 v44, 0xbfb8aa3b, v38
	v_or_b32_sdwa v42, v42, v45 dst_sel:DWORD dst_unused:UNUSED_PAD src0_sel:DWORD src1_sel:WORD_1
	v_exp_f32_e32 v44, v44
	v_mul_f32_e32 v45, 0xbfb8aa3b, v39
	v_exp_f32_e32 v45, v45
	global_store_dwordx2 v[66:67], v[42:43], off offset:64
	v_add_f32_e32 v42, 1.0, v44
	v_mul_f32_e32 v44, 0xbfb8aa3b, v40
	v_add_f32_e32 v43, 1.0, v45
	v_exp_f32_e32 v45, v44
	v_mul_f32_e32 v44, 0xbfb8aa3b, v41
	v_exp_f32_e32 v46, v44
	v_rcp_f32_e32 v44, v43
	v_add_f32_e32 v43, 1.0, v45
	v_rcp_f32_e32 v42, v42
	v_add_f32_e32 v45, 1.0, v46
	v_rcp_f32_e32 v43, v43
	v_rcp_f32_e32 v45, v45
	v_mov_b32_e32 v46, v38
	v_mov_b32_e32 v47, v40
	v_mov_b32_e32 v40, v39
	v_pk_mul_f32 v[42:43], v[46:47], v[42:43]
	v_mov_b32_e32 v47, v36
	v_pk_mul_f32 v[38:39], v[40:41], v[44:45]
	v_mov_b32_e32 v36, v35
	v_mov_b32_e32 v46, v34
	v_pk_mul_f32 v[34:35], v[36:37], v[38:39]
	v_pk_mul_f32 v[42:43], v[46:47], v[42:43]
	v_and_b32_sdwa v38, v35, v177 dst_sel:DWORD dst_unused:UNUSED_PAD src0_sel:WORD_1 src1_sel:DWORD
	v_and_b32_sdwa v39, v34, v177 dst_sel:DWORD dst_unused:UNUSED_PAD src0_sel:WORD_1 src1_sel:DWORD
	v_and_b32_sdwa v36, v43, v177 dst_sel:DWORD dst_unused:UNUSED_PAD src0_sel:WORD_1 src1_sel:DWORD
	v_and_b32_sdwa v37, v42, v177 dst_sel:DWORD dst_unused:UNUSED_PAD src0_sel:WORD_1 src1_sel:DWORD
	v_add3_u32 v35, v35, v38, s28
	v_add3_u32 v34, v34, v39, s28
	v_add3_u32 v37, v42, v37, s28
	v_add3_u32 v36, v43, v36, s28
	v_and_b32_e32 v35, 0xffff0000, v35
	v_and_b32_e32 v34, 0xffff0000, v34
	v_or_b32_sdwa v35, v35, v36 dst_sel:DWORD dst_unused:UNUSED_PAD src0_sel:DWORD src1_sel:WORD_1
	v_or_b32_sdwa v34, v34, v37 dst_sel:DWORD dst_unused:UNUSED_PAD src0_sel:DWORD src1_sel:WORD_1
	global_store_dwordx2 v[66:67], v[34:35], off offset:96
	v_mul_f32_e32 v35, 0xbfb8aa3b, v30
	v_exp_f32_e32 v36, v35
	v_mul_f32_e32 v35, 0xbfb8aa3b, v31
	v_mul_f32_e32 v38, 0xbfb8aa3b, v32
	v_exp_f32_e32 v37, v35
	v_exp_f32_e32 v39, v38
	v_mul_f32_e32 v38, 0xbfb8aa3b, v33
	v_exp_f32_e32 v40, v38
	v_add_f32_e32 v37, 1.0, v37
	v_add_f32_e32 v36, 1.0, v36
	v_rcp_f32_e32 v38, v37
	v_add_f32_e32 v37, 1.0, v39
	v_add_f32_e32 v39, 1.0, v40
	v_rcp_f32_e32 v36, v36
	v_rcp_f32_e32 v37, v37
	v_rcp_f32_e32 v39, v39
	v_mov_b32_e32 v40, v30
	v_mov_b32_e32 v41, v32
	v_mov_b32_e32 v32, v31
	v_pk_mul_f32 v[36:37], v[40:41], v[36:37]
	v_mov_b32_e32 v41, v28
	v_pk_mul_f32 v[30:31], v[32:33], v[38:39]
	v_mov_b32_e32 v28, v27
	v_mov_b32_e32 v40, v26
	v_pk_mul_f32 v[26:27], v[28:29], v[30:31]
	v_pk_mul_f32 v[36:37], v[40:41], v[36:37]
	v_and_b32_sdwa v30, v27, v177 dst_sel:DWORD dst_unused:UNUSED_PAD src0_sel:WORD_1 src1_sel:DWORD
	v_and_b32_sdwa v28, v37, v177 dst_sel:DWORD dst_unused:UNUSED_PAD src0_sel:WORD_1 src1_sel:DWORD
	v_and_b32_sdwa v31, v26, v177 dst_sel:DWORD dst_unused:UNUSED_PAD src0_sel:WORD_1 src1_sel:DWORD
	v_add3_u32 v27, v27, v30, s28
	v_and_b32_sdwa v29, v36, v177 dst_sel:DWORD dst_unused:UNUSED_PAD src0_sel:WORD_1 src1_sel:DWORD
	v_add3_u32 v28, v37, v28, s28
	v_add3_u32 v26, v26, v31, s28
	v_and_b32_e32 v27, 0xffff0000, v27
	v_add3_u32 v29, v36, v29, s28
	v_and_b32_e32 v26, 0xffff0000, v26
	v_or_b32_sdwa v27, v27, v28 dst_sel:DWORD dst_unused:UNUSED_PAD src0_sel:DWORD src1_sel:WORD_1
	v_mul_f32_e32 v28, 0xbfb8aa3b, v22
	v_or_b32_sdwa v26, v26, v29 dst_sel:DWORD dst_unused:UNUSED_PAD src0_sel:DWORD src1_sel:WORD_1
	v_exp_f32_e32 v28, v28
	v_mul_f32_e32 v29, 0xbfb8aa3b, v23
	v_or_b32_e32 v34, 48, v110
	v_exp_f32_e32 v29, v29
	v_mad_i64_i32 v[34:35], s[6:7], v34, s52, v[106:107]
	v_lshl_add_u64 v[34:35], v[34:35], 0, v[108:109]
	global_store_dwordx2 v[34:35], v[26:27], off
	v_add_f32_e32 v26, 1.0, v28
	v_mul_f32_e32 v28, 0xbfb8aa3b, v24
	v_add_f32_e32 v27, 1.0, v29
	v_exp_f32_e32 v29, v28
	v_mul_f32_e32 v28, 0xbfb8aa3b, v25
	v_exp_f32_e32 v30, v28
	v_rcp_f32_e32 v28, v27
	v_add_f32_e32 v27, 1.0, v29
	v_rcp_f32_e32 v26, v26
	v_add_f32_e32 v29, 1.0, v30
	v_rcp_f32_e32 v27, v27
	v_rcp_f32_e32 v29, v29
	v_mov_b32_e32 v30, v22
	v_mov_b32_e32 v31, v24
	v_mov_b32_e32 v24, v23
	v_pk_mul_f32 v[26:27], v[30:31], v[26:27]
	v_mov_b32_e32 v31, v20
	v_pk_mul_f32 v[22:23], v[24:25], v[28:29]
	v_mov_b32_e32 v20, v19
	v_mov_b32_e32 v30, v18
	v_pk_mul_f32 v[18:19], v[20:21], v[22:23]
	v_pk_mul_f32 v[26:27], v[30:31], v[26:27]
	v_and_b32_sdwa v22, v19, v177 dst_sel:DWORD dst_unused:UNUSED_PAD src0_sel:WORD_1 src1_sel:DWORD
	v_and_b32_sdwa v20, v27, v177 dst_sel:DWORD dst_unused:UNUSED_PAD src0_sel:WORD_1 src1_sel:DWORD
	v_and_b32_sdwa v23, v18, v177 dst_sel:DWORD dst_unused:UNUSED_PAD src0_sel:WORD_1 src1_sel:DWORD
	v_add3_u32 v19, v19, v22, s28
	v_and_b32_sdwa v21, v26, v177 dst_sel:DWORD dst_unused:UNUSED_PAD src0_sel:WORD_1 src1_sel:DWORD
	v_add3_u32 v20, v27, v20, s28
	v_add3_u32 v18, v18, v23, s28
	v_and_b32_e32 v19, 0xffff0000, v19
	v_add3_u32 v21, v26, v21, s28
	v_and_b32_e32 v18, 0xffff0000, v18
	v_or_b32_sdwa v19, v19, v20 dst_sel:DWORD dst_unused:UNUSED_PAD src0_sel:DWORD src1_sel:WORD_1
	v_mul_f32_e32 v20, 0xbfb8aa3b, v14
	v_or_b32_sdwa v18, v18, v21 dst_sel:DWORD dst_unused:UNUSED_PAD src0_sel:DWORD src1_sel:WORD_1
	v_exp_f32_e32 v20, v20
	v_mul_f32_e32 v21, 0xbfb8aa3b, v15
	v_exp_f32_e32 v21, v21
	global_store_dwordx2 v[34:35], v[18:19], off offset:32
	v_add_f32_e32 v18, 1.0, v20
	v_mul_f32_e32 v20, 0xbfb8aa3b, v16
	v_add_f32_e32 v19, 1.0, v21
	v_exp_f32_e32 v21, v20
	v_mul_f32_e32 v20, 0xbfb8aa3b, v17
	v_exp_f32_e32 v22, v20
	v_rcp_f32_e32 v20, v19
	v_add_f32_e32 v19, 1.0, v21
	v_rcp_f32_e32 v18, v18
	v_add_f32_e32 v21, 1.0, v22
	v_rcp_f32_e32 v19, v19
	v_rcp_f32_e32 v21, v21
	v_mov_b32_e32 v22, v14
	v_mov_b32_e32 v23, v16
	v_mov_b32_e32 v16, v15
	v_pk_mul_f32 v[18:19], v[22:23], v[18:19]
	v_mov_b32_e32 v23, v12
	v_pk_mul_f32 v[14:15], v[16:17], v[20:21]
	v_mov_b32_e32 v12, v11
	v_mov_b32_e32 v22, v10
	v_pk_mul_f32 v[10:11], v[12:13], v[14:15]
	v_pk_mul_f32 v[18:19], v[22:23], v[18:19]
	v_and_b32_sdwa v14, v11, v177 dst_sel:DWORD dst_unused:UNUSED_PAD src0_sel:WORD_1 src1_sel:DWORD
	v_and_b32_sdwa v12, v19, v177 dst_sel:DWORD dst_unused:UNUSED_PAD src0_sel:WORD_1 src1_sel:DWORD
	v_and_b32_sdwa v15, v10, v177 dst_sel:DWORD dst_unused:UNUSED_PAD src0_sel:WORD_1 src1_sel:DWORD
	v_add3_u32 v11, v11, v14, s28
	v_and_b32_sdwa v13, v18, v177 dst_sel:DWORD dst_unused:UNUSED_PAD src0_sel:WORD_1 src1_sel:DWORD
	v_add3_u32 v12, v19, v12, s28
	v_add3_u32 v10, v10, v15, s28
	v_and_b32_e32 v11, 0xffff0000, v11
	v_add3_u32 v13, v18, v13, s28
	v_and_b32_e32 v10, 0xffff0000, v10
	v_or_b32_sdwa v11, v11, v12 dst_sel:DWORD dst_unused:UNUSED_PAD src0_sel:DWORD src1_sel:WORD_1
	v_mul_f32_e32 v12, 0xbfb8aa3b, v6
	v_or_b32_sdwa v10, v10, v13 dst_sel:DWORD dst_unused:UNUSED_PAD src0_sel:DWORD src1_sel:WORD_1
	v_exp_f32_e32 v12, v12
	v_mul_f32_e32 v13, 0xbfb8aa3b, v7
	v_exp_f32_e32 v13, v13
	global_store_dwordx2 v[34:35], v[10:11], off offset:64
	v_add_f32_e32 v10, 1.0, v12
	v_mul_f32_e32 v12, 0xbfb8aa3b, v8
	v_add_f32_e32 v11, 1.0, v13
	v_exp_f32_e32 v13, v12
	v_mul_f32_e32 v12, 0xbfb8aa3b, v9
	v_exp_f32_e32 v14, v12
	v_rcp_f32_e32 v12, v11
	v_add_f32_e32 v11, 1.0, v13
	v_rcp_f32_e32 v10, v10
	v_add_f32_e32 v13, 1.0, v14
	v_rcp_f32_e32 v11, v11
	v_rcp_f32_e32 v13, v13
	v_mov_b32_e32 v14, v6
	v_mov_b32_e32 v15, v8
	v_mov_b32_e32 v8, v7
	v_pk_mul_f32 v[10:11], v[14:15], v[10:11]
	v_mov_b32_e32 v15, v4
	v_pk_mul_f32 v[6:7], v[8:9], v[12:13]
	v_mov_b32_e32 v4, v3
	v_mov_b32_e32 v14, v2
	v_pk_mul_f32 v[2:3], v[4:5], v[6:7]
	v_pk_mul_f32 v[10:11], v[14:15], v[10:11]
	v_and_b32_sdwa v6, v3, v177 dst_sel:DWORD dst_unused:UNUSED_PAD src0_sel:WORD_1 src1_sel:DWORD
	v_and_b32_sdwa v7, v2, v177 dst_sel:DWORD dst_unused:UNUSED_PAD src0_sel:WORD_1 src1_sel:DWORD
	v_and_b32_sdwa v4, v11, v177 dst_sel:DWORD dst_unused:UNUSED_PAD src0_sel:WORD_1 src1_sel:DWORD
	v_and_b32_sdwa v5, v10, v177 dst_sel:DWORD dst_unused:UNUSED_PAD src0_sel:WORD_1 src1_sel:DWORD
	v_add3_u32 v3, v3, v6, s28
	v_add3_u32 v2, v2, v7, s28
	v_add3_u32 v5, v10, v5, s28
	v_add3_u32 v4, v11, v4, s28
	v_and_b32_e32 v3, 0xffff0000, v3
	v_and_b32_e32 v2, 0xffff0000, v2
	s_add_i32 s14, s14, s11
	v_or_b32_sdwa v3, v3, v4 dst_sel:DWORD dst_unused:UNUSED_PAD src0_sel:DWORD src1_sel:WORD_1
	v_or_b32_sdwa v2, v2, v5 dst_sel:DWORD dst_unused:UNUSED_PAD src0_sel:DWORD src1_sel:WORD_1
	s_cmpk_gt_i32 s14, 0x4ff
	global_store_dwordx2 v[34:35], v[2:3], off offset:96
	s_cbranch_scc0 .LBB0_1440

.LBB0_1458:
	s_and_b64 vcc, exec, s[14:15]
	s_cbranch_vccz .LBB0_1472
	v_mov_b32_e32 v2, v172
	s_mov_b32 s11, s42
	s_mov_b32 s14, s94
	s_cmpk_gt_i32 s14, 0x5ff
	s_cbranch_scc1 .LBB0_1464
	v_ashrrev_i32_e32 v204, 3, v2
	v_bfe_u32 v3, v2, 4, 2
	v_and_b32_e32 v4, 15, v2
	v_lshlrev_b32_e32 v0, 4, v2
	v_ashrrev_i32_e32 v5, 1, v2
	s_movk_i32 s2, 0xffc0
	v_lshlrev_b32_e32 v2, 1, v2
	v_and_b32_e32 v0, 0x70, v0
	v_and_or_b32 v205, v5, s2, v4
	v_and_b32_e32 v207, 0x80, v2
	s_movk_i32 s2, 0x90
	v_or_b32_e32 v2, v207, v4
	v_and_b32_e32 v100, 7, v204
	v_lshlrev_b32_e32 v100, 4, v100
	v_xor_b32_e32 v100, v100, v0
	v_lshl_add_u32 v166, v204, 7, v100
	v_lshl_add_u64 v[162:163], s[46:47], 0, v[0:1]
	v_lshl_add_u64 v[164:165], s[44:45], 0, v[0:1]
	v_and_b32_e32 v100, 7, v4
	v_xor_b32_e32 v100, v100, v3
	v_lshlrev_b32_e32 v206, 4, v100
	v_lshlrev_b32_e32 v208, 2, v3
	v_lshlrev_b32_e32 v0, 7, v205
	v_lshlrev_b32_e32 v167, 7, v2
	s_mov_b32 m0, s14
	s_mul_hi_i32 s101, m0, 0x38e38e39
	s_lshr_b32 vcc_lo, s101, 31
	s_ashr_i32 s101, s101, 4
	s_add_i32 s101, s101, vcc_lo
	s_mul_i32 vcc_lo, s101, 0x48
	s_sub_i32 m0, m0, vcc_lo
	s_lshl_b32 m0, m0, 19
	s_lshl_b32 s101, s101, 19
	v_readfirstlane_b32 vcc_lo, v162
	v_readfirstlane_b32 vcc_hi, v163
	v_and_b32_e32 v242, 7, v172
	v_lshlrev_b32_e32 v242, 4, v242
	v_lshl_add_u32 v242, v204, 11, v242
	s_add_u32 vcc_lo, vcc_lo, m0
	s_addc_u32 vcc_hi, vcc_hi, 0
	s_mov_b32 m0, s101
	v_readfirstlane_b32 s100, v164
	v_readfirstlane_b32 s101, v165
	s_nop 0
	s_add_u32 s100, s100, m0
	s_addc_u32 s101, s101, 0
	global_load_dwordx4 v[210:213], v242, vcc
	v_add_u32_e32 v214, s34, v242
	global_load_dwordx4 v[214:217], v214, vcc
	v_add_u32_e32 v218, s35, v242
	global_load_dwordx4 v[218:221], v218, vcc
	v_add_u32_e32 v222, s36, v242
	global_load_dwordx4 v[222:225], v222, vcc
	global_load_dwordx4 v[226:229], v242, s[100:101]
	v_add_u32_e32 v230, s34, v242
	global_load_dwordx4 v[230:233], v230, s[100:101]
	v_add_u32_e32 v234, s35, v242
	global_load_dwordx4 v[234:237], v234, s[100:101]
	v_add_u32_e32 v238, s36, v242
	global_load_dwordx4 v[238:241], v238, s[100:101]
.LBB0_1461:
	s_mul_hi_i32 s2, s14, 0x38e38e39
	s_lshr_b32 s3, s2, 31
	s_ashr_i32 s2, s2, 4
	s_add_i32 s2, s2, s3
	s_mul_i32 s3, s2, 0x48
	s_sub_i32 s3, s14, s3
	s_lshl_b32 s6, s3, 8
	v_add_u32_e32 v2, s6, v204
	v_ashrrev_i32_e32 v3, 31, v2
	v_lshlrev_b64 v[2:3], 11, v[2:3]
	v_lshl_add_u64 v[168:169], v[162:163], 0, v[2:3]
	v_add_co_u32_e32 v56, vcc, s34, v168
	s_lshl_b32 s7, s2, 8
	s_nop 0
	v_addc_co_u32_e32 v57, vcc, 0, v169, vcc
	v_add_u32_e32 v2, s7, v204
	s_waitcnt vmcnt(9)
	v_add_co_u32_e32 v58, vcc, s35, v168
	v_ashrrev_i32_e32 v3, 31, v2
	s_nop 0
	v_addc_co_u32_e32 v59, vcc, 0, v169, vcc
	v_lshlrev_b64 v[2:3], 11, v[2:3]
	v_add_co_u32_e32 v60, vcc, s36, v168
	v_lshl_add_u64 v[170:171], v[164:165], 0, v[2:3]
	s_nop 0
	v_addc_co_u32_e32 v61, vcc, 0, v169, vcc
	s_waitcnt vmcnt(8)
	v_add_co_u32_e32 v62, vcc, s35, v170
	s_nop 1
	s_nop 1
	v_addc_co_u32_e32 v63, vcc, 0, v171, vcc
	v_add_co_u32_e32 v64, vcc, s36, v170
	s_nop 1
	s_nop 1
	v_addc_co_u32_e32 v65, vcc, 0, v171, vcc
	v_add_co_u32_e32 v66, vcc, s34, v170
	s_nop 1
	s_nop 1
	v_addc_co_u32_e32 v67, vcc, 0, v171, vcc
	s_nop 1
	s_nop 1
	s_waitcnt lgkmcnt(0)
	s_barrier
	global_load_dwordx4 v[114:117], v[168:169], off offset:128
	global_load_dwordx4 v[106:109], v[56:57], off offset:128
	global_load_dwordx4 v[110:113], v[58:59], off offset:128
	global_load_dwordx4 v[126:129], v[60:61], off offset:128
	global_load_dwordx4 v[122:125], v[170:171], off offset:128
	global_load_dwordx4 v[118:121], v[66:67], off offset:128
	global_load_dwordx4 v[134:137], v[62:63], off offset:128
	global_load_dwordx4 v[130:133], v[64:65], off offset:128
	v_readfirstlane_b32 vcc_lo, v168
	v_readfirstlane_b32 vcc_hi, v169
	v_readfirstlane_b32 s100, v170
	v_readfirstlane_b32 s101, v171
	s_nop 1
	v_subrev_u32_e32 v168, vcc_lo, v168
	v_subrev_u32_e32 v170, s100, v170
	v_mov_b32_e32 v2, 0
	s_mov_b32 s4, 0
	v_mov_b32_e32 v3, v2
	v_mov_b32_e32 v4, v2
	v_mov_b32_e32 v5, v2
	v_mov_b32_e32 v6, v2
	v_mov_b32_e32 v7, v2
	v_mov_b32_e32 v8, v2
	v_mov_b32_e32 v9, v2
	v_mov_b32_e32 v10, v2
	v_mov_b32_e32 v11, v2
	v_mov_b32_e32 v12, v2
	v_mov_b32_e32 v13, v2
	v_mov_b32_e32 v14, v2
	v_mov_b32_e32 v15, v2
	v_mov_b32_e32 v16, v2
	v_mov_b32_e32 v17, v2
	v_mov_b32_e32 v18, v2
	v_mov_b32_e32 v19, v2
	v_mov_b32_e32 v20, v2
	v_mov_b32_e32 v21, v2
	v_mov_b32_e32 v22, v2
	v_mov_b32_e32 v23, v2
	v_mov_b32_e32 v56, v2
	v_mov_b32_e32 v57, v2
	v_mov_b32_e32 v58, v2
	v_mov_b32_e32 v59, v2
	v_mov_b32_e32 v60, v2
	v_mov_b32_e32 v61, v2
	v_mov_b32_e32 v62, v2
	v_mov_b32_e32 v63, v2
	v_mov_b32_e32 v64, v2
	v_mov_b32_e32 v65, v2
	v_mov_b32_e32 v66, v2
	v_mov_b32_e32 v67, v2
	v_mov_b32_e32 v68, v2
	v_mov_b32_e32 v69, v2
	v_mov_b32_e32 v70, v2
	v_mov_b32_e32 v71, v2
	v_mov_b32_e32 v72, v2
	v_mov_b32_e32 v73, v2
	v_mov_b32_e32 v74, v2
	v_mov_b32_e32 v75, v2
	v_mov_b32_e32 v76, v2
	v_mov_b32_e32 v77, v2
	v_mov_b32_e32 v78, v2
	v_mov_b32_e32 v79, v2
	v_mov_b32_e32 v80, v2
	v_mov_b32_e32 v81, v2
	v_mov_b32_e32 v82, v2
	v_mov_b32_e32 v83, v2
	v_mov_b32_e32 v84, v2
	v_mov_b32_e32 v85, v2
	s_waitcnt vmcnt(8)
	ds_write_b128 v166, v[234:237] offset:49152
	ds_write_b128 v166, v[238:241] offset:57344
	ds_write_b128 v166, v[210:213]
	ds_write_b128 v166, v[226:229] offset:32768
	ds_write_b128 v166, v[214:217] offset:8192
	ds_write_b128 v166, v[218:221] offset:16384
	ds_write_b128 v166, v[222:225] offset:24576
	ds_write_b128 v166, v[230:233] offset:40960
	v_mov_b32_e32 v24, v2
	v_mov_b32_e32 v25, v2
	v_mov_b32_e32 v26, v2
	v_mov_b32_e32 v27, v2
	v_mov_b32_e32 v28, v2
	v_mov_b32_e32 v29, v2
	v_mov_b32_e32 v30, v2
	v_mov_b32_e32 v31, v2
	v_mov_b32_e32 v32, v2
	v_mov_b32_e32 v33, v2
	v_mov_b32_e32 v34, v2
	v_mov_b32_e32 v35, v2
	v_mov_b32_e32 v36, v2
	v_mov_b32_e32 v37, v2
	v_mov_b32_e32 v38, v2
	v_mov_b32_e32 v39, v2
	v_mov_b32_e32 v40, v2
	v_mov_b32_e32 v41, v2
	v_mov_b32_e32 v42, v2
	v_mov_b32_e32 v43, v2
	v_mov_b32_e32 v44, v2
	v_mov_b32_e32 v45, v2
	v_mov_b32_e32 v46, v2
	v_mov_b32_e32 v47, v2
	v_mov_b32_e32 v48, v2
	v_mov_b32_e32 v49, v2
	v_mov_b32_e32 v50, v2
	v_mov_b32_e32 v51, v2
	v_mov_b32_e32 v52, v2
	v_mov_b32_e32 v53, v2
	v_mov_b32_e32 v54, v2
	v_mov_b32_e32 v55, v2
	v_mov_b32_e32 v86, v2
	v_mov_b32_e32 v87, v2
	v_mov_b32_e32 v88, v2
	v_mov_b32_e32 v89, v2
	v_mov_b32_e32 v90, v2
	v_mov_b32_e32 v91, v2
	v_mov_b32_e32 v92, v2
	v_mov_b32_e32 v93, v2
	v_mov_b32_e32 v94, v2
	v_mov_b32_e32 v95, v2
	v_mov_b32_e32 v96, v2
	v_mov_b32_e32 v97, v2
	v_mov_b32_e32 v98, v2
	v_mov_b32_e32 v99, v2
	v_mov_b32_e32 v100, v2
	v_mov_b32_e32 v101, v2
	v_mov_b32_e32 v102, v2
	v_mov_b32_e32 v103, v2
	v_mov_b32_e32 v104, v2
	v_mov_b32_e32 v105, v2
	v_mov_b32_e32 v138, v2
	v_mov_b32_e32 v139, v2
	v_mov_b32_e32 v140, v2
	v_mov_b32_e32 v141, v2
	v_mov_b32_e32 v142, v2
	v_mov_b32_e32 v143, v2
	v_mov_b32_e32 v144, v2
	v_mov_b32_e32 v145, v2
	v_mov_b32_e32 v146, v2
	v_mov_b32_e32 v147, v2
	v_mov_b32_e32 v148, v2
	v_mov_b32_e32 v149, v2
	v_mov_b32_e32 v150, v2
	v_mov_b32_e32 v151, v2
	v_mov_b32_e32 v152, v2
	v_mov_b32_e32 v153, v2
	v_mov_b32_e32 v154, v2
	v_mov_b32_e32 v155, v2
	v_mov_b32_e32 v156, v2
	v_mov_b32_e32 v157, v2
	v_mov_b32_e32 v158, v2
	v_mov_b32_e32 v159, v2
	v_mov_b32_e32 v160, v2
	v_mov_b32_e32 v161, v2
	s_waitcnt lgkmcnt(0)
	s_barrier
.LBB0_1462:
	s_bitcmp1_b32 s4, 0
	s_cselect_b32 s2, 0x12000, 0
	v_or_b32_e32 v218, s2, v206
	v_add_u32_e32 v214, v218, v0
	v_add_u32_e32 v246, v218, v167
	ds_read_b128 v[184:187], v214
	ds_read_b128 v[218:221], v246 offset:32768
	ds_read_b128 v[198:201], v214 offset:2048
	ds_read_b128 v[210:213], v214 offset:4096
	ds_read_b128 v[214:217], v214 offset:6144
	ds_read_b128 v[222:225], v246 offset:34816
	ds_read_b128 v[226:229], v246 offset:36864
	ds_read_b128 v[230:233], v246 offset:38912
	ds_read_b128 v[234:237], v246 offset:40960
	ds_read_b128 v[238:241], v246 offset:43008
	ds_read_b128 v[242:245], v246 offset:45056
	ds_read_b128 v[246:249], v246 offset:47104
	s_add_i32 s10, s4, 1
	s_bitcmp1_b32 s10, 0
	s_cselect_b32 s3, 0x12000, 0
	v_add_u32_e32 v171, s3, v166
	v_xor_b32_e32 v169, 64, v206
	v_add3_u32 v169, s2, v167, v169
	s_waitcnt lgkmcnt(10)
	v_mfma_f32_16x16x32_bf16 v[158:161], v[218:221], v[184:187], v[158:161]
	s_waitcnt lgkmcnt(9)
	v_mfma_f32_16x16x32_bf16 v[94:97], v[218:221], v[198:201], v[94:97]
	s_waitcnt lgkmcnt(8)
	v_mfma_f32_16x16x32_bf16 v[62:65], v[218:221], v[210:213], v[62:65]
	s_waitcnt lgkmcnt(7)
	v_mfma_f32_16x16x32_bf16 v[30:33], v[218:221], v[214:217], v[30:33]
	ds_read_b128 v[218:221], v169 offset:32768
	s_waitcnt lgkmcnt(7)
	v_mfma_f32_16x16x32_bf16 v[154:157], v[222:225], v[184:187], v[154:157]
	v_mfma_f32_16x16x32_bf16 v[90:93], v[222:225], v[198:201], v[90:93]
	v_mfma_f32_16x16x32_bf16 v[58:61], v[222:225], v[210:213], v[58:61]
	v_mfma_f32_16x16x32_bf16 v[26:29], v[222:225], v[214:217], v[26:29]
	ds_read_b128 v[222:225], v169 offset:34816
	s_waitcnt lgkmcnt(7)
	v_mfma_f32_16x16x32_bf16 v[150:153], v[226:229], v[184:187], v[150:153]
	v_mfma_f32_16x16x32_bf16 v[86:89], v[226:229], v[198:201], v[86:89]
	v_mfma_f32_16x16x32_bf16 v[54:57], v[226:229], v[210:213], v[54:57]
	v_mfma_f32_16x16x32_bf16 v[22:25], v[226:229], v[214:217], v[22:25]
	ds_read_b128 v[226:229], v169 offset:36864
	s_waitcnt lgkmcnt(7)
	v_mfma_f32_16x16x32_bf16 v[146:149], v[230:233], v[184:187], v[146:149]
	v_mfma_f32_16x16x32_bf16 v[82:85], v[230:233], v[198:201], v[82:85]
	v_mfma_f32_16x16x32_bf16 v[50:53], v[230:233], v[210:213], v[50:53]
	v_mfma_f32_16x16x32_bf16 v[18:21], v[230:233], v[214:217], v[18:21]
	ds_read_b128 v[230:233], v169 offset:38912
	s_waitcnt lgkmcnt(7)
	v_mfma_f32_16x16x32_bf16 v[142:145], v[234:237], v[184:187], v[142:145]
	v_mfma_f32_16x16x32_bf16 v[78:81], v[234:237], v[198:201], v[78:81]
	v_mfma_f32_16x16x32_bf16 v[46:49], v[234:237], v[210:213], v[46:49]
	v_mfma_f32_16x16x32_bf16 v[14:17], v[234:237], v[214:217], v[14:17]
	ds_read_b128 v[234:237], v169 offset:40960
	s_waitcnt lgkmcnt(7)
	v_mfma_f32_16x16x32_bf16 v[138:141], v[238:241], v[184:187], v[138:141]
	v_mfma_f32_16x16x32_bf16 v[74:77], v[238:241], v[198:201], v[74:77]
	v_mfma_f32_16x16x32_bf16 v[42:45], v[238:241], v[210:213], v[42:45]
	v_mfma_f32_16x16x32_bf16 v[10:13], v[238:241], v[214:217], v[10:13]
	ds_read_b128 v[238:241], v169 offset:43008
	s_waitcnt lgkmcnt(7)
	v_mfma_f32_16x16x32_bf16 v[102:105], v[242:245], v[184:187], v[102:105]
	v_mfma_f32_16x16x32_bf16 v[70:73], v[242:245], v[198:201], v[70:73]
	v_mfma_f32_16x16x32_bf16 v[38:41], v[242:245], v[210:213], v[38:41]
	v_mfma_f32_16x16x32_bf16 v[6:9], v[242:245], v[214:217], v[6:9]
	ds_read_b128 v[242:245], v169 offset:45056
	s_waitcnt lgkmcnt(7)
	v_mfma_f32_16x16x32_bf16 v[98:101], v[246:249], v[184:187], v[98:101]
	v_mfma_f32_16x16x32_bf16 v[66:69], v[246:249], v[198:201], v[66:69]
	v_xor_b32_e32 v169, 64, v206
	v_add3_u32 v169, s2, v0, v169
	ds_read_b128 v[184:187], v169
	ds_read_b128 v[198:201], v169 offset:2048
	v_mfma_f32_16x16x32_bf16 v[34:37], v[246:249], v[210:213], v[34:37]
	ds_read_b128 v[210:213], v169 offset:4096
	v_mfma_f32_16x16x32_bf16 v[2:5], v[246:249], v[214:217], v[2:5]
	ds_read_b128 v[214:217], v169 offset:6144
	v_xor_b32_e32 v169, 64, v206
	v_add3_u32 v169, s2, v167, v169
	ds_read_b128 v[246:249], v169 offset:47104
	s_waitcnt lgkmcnt(4)
	v_mfma_f32_16x16x32_bf16 v[158:161], v[218:221], v[184:187], v[158:161]
	s_waitcnt lgkmcnt(3)
	v_mfma_f32_16x16x32_bf16 v[94:97], v[218:221], v[198:201], v[94:97]
	s_waitcnt lgkmcnt(2)
	v_mfma_f32_16x16x32_bf16 v[62:65], v[218:221], v[210:213], v[62:65]
	s_waitcnt lgkmcnt(1)
	v_mfma_f32_16x16x32_bf16 v[30:33], v[218:221], v[214:217], v[30:33]
	s_waitcnt vmcnt(7)
	ds_write_b128 v171, v[114:117]
	v_mfma_f32_16x16x32_bf16 v[154:157], v[222:225], v[184:187], v[154:157]
	v_mfma_f32_16x16x32_bf16 v[90:93], v[222:225], v[198:201], v[90:93]
	global_load_dwordx4 v[114:117], v168, vcc offset:256
	v_mfma_f32_16x16x32_bf16 v[58:61], v[222:225], v[210:213], v[58:61]
	v_mfma_f32_16x16x32_bf16 v[26:29], v[222:225], v[214:217], v[26:29]
	s_waitcnt vmcnt(7)
	ds_write_b128 v171, v[106:109] offset:8192
	v_mfma_f32_16x16x32_bf16 v[150:153], v[226:229], v[184:187], v[150:153]
	v_mfma_f32_16x16x32_bf16 v[86:89], v[226:229], v[198:201], v[86:89]
	v_add_u32_e32 v106, s34, v168
	global_load_dwordx4 v[106:109], v106, vcc offset:256
	v_mfma_f32_16x16x32_bf16 v[54:57], v[226:229], v[210:213], v[54:57]
	v_mfma_f32_16x16x32_bf16 v[22:25], v[226:229], v[214:217], v[22:25]
	s_waitcnt vmcnt(7)
	ds_write_b128 v171, v[110:113] offset:16384
	v_mfma_f32_16x16x32_bf16 v[146:149], v[230:233], v[184:187], v[146:149]
	v_mfma_f32_16x16x32_bf16 v[82:85], v[230:233], v[198:201], v[82:85]
	v_add_u32_e32 v110, s35, v168
	global_load_dwordx4 v[110:113], v110, vcc offset:256
	v_mfma_f32_16x16x32_bf16 v[50:53], v[230:233], v[210:213], v[50:53]
	v_mfma_f32_16x16x32_bf16 v[18:21], v[230:233], v[214:217], v[18:21]
	s_waitcnt vmcnt(7)
	ds_write_b128 v171, v[126:129] offset:24576
	v_mfma_f32_16x16x32_bf16 v[142:145], v[234:237], v[184:187], v[142:145]
	v_mfma_f32_16x16x32_bf16 v[78:81], v[234:237], v[198:201], v[78:81]
	v_add_u32_e32 v126, s36, v168
	global_load_dwordx4 v[126:129], v126, vcc offset:256
	v_mfma_f32_16x16x32_bf16 v[46:49], v[234:237], v[210:213], v[46:49]
	v_mfma_f32_16x16x32_bf16 v[14:17], v[234:237], v[214:217], v[14:17]
	s_waitcnt vmcnt(7)
	ds_write_b128 v171, v[122:125] offset:32768
	v_mfma_f32_16x16x32_bf16 v[138:141], v[238:241], v[184:187], v[138:141]
	v_mfma_f32_16x16x32_bf16 v[74:77], v[238:241], v[198:201], v[74:77]
	global_load_dwordx4 v[122:125], v170, s[100:101] offset:256
	v_mfma_f32_16x16x32_bf16 v[42:45], v[238:241], v[210:213], v[42:45]
	v_mfma_f32_16x16x32_bf16 v[10:13], v[238:241], v[214:217], v[10:13]
	s_waitcnt vmcnt(7)
	ds_write_b128 v171, v[118:121] offset:40960
	v_mfma_f32_16x16x32_bf16 v[102:105], v[242:245], v[184:187], v[102:105]
	v_mfma_f32_16x16x32_bf16 v[70:73], v[242:245], v[198:201], v[70:73]
	v_add_u32_e32 v118, s34, v170
	global_load_dwordx4 v[118:121], v118, s[100:101] offset:256
	v_mfma_f32_16x16x32_bf16 v[38:41], v[242:245], v[210:213], v[38:41]
	v_mfma_f32_16x16x32_bf16 v[6:9], v[242:245], v[214:217], v[6:9]
	s_waitcnt vmcnt(7)
	ds_write_b128 v171, v[134:137] offset:49152
	s_waitcnt lgkmcnt(7)
	v_mfma_f32_16x16x32_bf16 v[98:101], v[246:249], v[184:187], v[98:101]
	v_mfma_f32_16x16x32_bf16 v[66:69], v[246:249], v[198:201], v[66:69]
	v_add_u32_e32 v134, s35, v170
	global_load_dwordx4 v[134:137], v134, s[100:101] offset:256
	v_mfma_f32_16x16x32_bf16 v[34:37], v[246:249], v[210:213], v[34:37]
	v_mfma_f32_16x16x32_bf16 v[2:5], v[246:249], v[214:217], v[2:5]
	s_waitcnt vmcnt(7)
	ds_write_b128 v171, v[130:133] offset:57344
	v_add_u32_e32 v130, s36, v170
	global_load_dwordx4 v[130:133], v130, s[100:101] offset:256
	v_add_u32_e32 v168, 0x80, v168
	v_add_u32_e32 v170, 0x80, v170
	s_waitcnt lgkmcnt(0)
	s_barrier
	s_cmp_eq_u32 s10, 16
	s_mov_b32 s4, s10
	s_cbranch_scc0 .LBB0_1462
	s_add_i32 m0, s14, s11
	s_cmpk_lt_i32 m0, 0x600
	s_cselect_b32 m0, m0, s14
	s_mul_hi_i32 s101, m0, 0x38e38e39
	s_lshr_b32 vcc_lo, s101, 31
	s_ashr_i32 s101, s101, 4
	s_add_i32 s101, s101, vcc_lo
	s_mul_i32 vcc_lo, s101, 0x48
	s_sub_i32 m0, m0, vcc_lo
	s_lshl_b32 m0, m0, 19
	s_lshl_b32 s101, s101, 19
	v_readfirstlane_b32 vcc_lo, v162
	v_readfirstlane_b32 vcc_hi, v163
	v_and_b32_e32 v242, 7, v172
	v_lshlrev_b32_e32 v242, 4, v242
	v_lshl_add_u32 v242, v204, 11, v242
	s_add_u32 vcc_lo, vcc_lo, m0
	s_addc_u32 vcc_hi, vcc_hi, 0
	s_mov_b32 m0, s101
	v_readfirstlane_b32 s100, v164
	v_readfirstlane_b32 s101, v165
	s_nop 0
	s_add_u32 s100, s100, m0
	s_addc_u32 s101, s101, 0
	global_load_dwordx4 v[210:213], v242, vcc
	v_add_u32_e32 v214, s34, v242
	global_load_dwordx4 v[214:217], v214, vcc
	v_add_u32_e32 v218, s35, v242
	global_load_dwordx4 v[218:221], v218, vcc
	v_add_u32_e32 v222, s36, v242
	global_load_dwordx4 v[222:225], v222, vcc
	global_load_dwordx4 v[226:229], v242, s[100:101]
	v_add_u32_e32 v230, s34, v242
	global_load_dwordx4 v[230:233], v230, s[100:101]
	v_add_u32_e32 v234, s35, v242
	global_load_dwordx4 v[234:237], v234, s[100:101]
	v_add_u32_e32 v238, s36, v242
	global_load_dwordx4 v[238:241], v238, s[100:101]
	s_waitcnt vmcnt(12)
	v_mul_f32_e32 v109, 0xbfb8aa3b, v158
	v_exp_f32_e32 v109, v109
	s_waitcnt vmcnt(11)
	v_mul_f32_e32 v111, 0xbfb8aa3b, v159
	v_exp_f32_e32 v111, v111
	v_mul_f32_e32 v115, 0xbfb8aa3b, v161
	v_add_f32_e32 v109, 1.0, v109
	v_rcp_f32_e32 v114, v109
	v_add_f32_e32 v109, 1.0, v111
	v_mul_f32_e32 v111, 0xbfb8aa3b, v160
	v_exp_f32_e32 v111, v111
	v_exp_f32_e32 v117, v115
	v_rcp_f32_e32 v116, v109
	s_waitcnt vmcnt(10)
	v_mov_b32_e32 v118, v158
	v_add_f32_e32 v109, 1.0, v111
	v_rcp_f32_e32 v115, v109
	v_add_f32_e32 v109, 1.0, v117
	v_rcp_f32_e32 v117, v109
	v_mov_b32_e32 v119, v160
	v_pk_mul_f32 v[114:115], v[118:119], v[114:115]
	v_mov_b32_e32 v118, v154
	v_mov_b32_e32 v119, v156
	v_mov_b32_e32 v160, v159
	v_pk_mul_f32 v[114:115], v[118:119], v[114:115]
	v_pk_mul_f32 v[116:117], v[160:161], v[116:117]
	v_mov_b32_e32 v156, v155
	v_pk_mul_f32 v[116:117], v[156:157], v[116:117]
	v_and_b32_sdwa v111, v115, v177 dst_sel:DWORD dst_unused:UNUSED_PAD src0_sel:WORD_1 src1_sel:DWORD
	v_and_b32_sdwa v118, v114, v177 dst_sel:DWORD dst_unused:UNUSED_PAD src0_sel:WORD_1 src1_sel:DWORD
	v_add3_u32 v111, v115, v111, s28
	v_and_b32_sdwa v115, v117, v177 dst_sel:DWORD dst_unused:UNUSED_PAD src0_sel:WORD_1 src1_sel:DWORD
	v_add3_u32 v114, v114, v118, s28
	v_and_b32_sdwa v118, v116, v177 dst_sel:DWORD dst_unused:UNUSED_PAD src0_sel:WORD_1 src1_sel:DWORD
	v_add3_u32 v115, v117, v115, s28
	v_or_b32_e32 v106, s7, v207
	v_add3_u32 v116, v116, v118, s28
	v_and_b32_e32 v115, 0xffff0000, v115
	v_ashrrev_i32_e32 v106, 1, v106
	v_and_b32_e32 v116, 0xffff0000, v116
	v_or_b32_sdwa v115, v115, v111 dst_sel:DWORD dst_unused:UNUSED_PAD src0_sel:DWORD src1_sel:WORD_1
	v_mul_f32_e32 v111, 0xbfb8aa3b, v150
	v_or_b32_e32 v108, v106, v208
	v_or_b32_sdwa v114, v116, v114 dst_sel:DWORD dst_unused:UNUSED_PAD src0_sel:DWORD src1_sel:WORD_1
	v_exp_f32_e32 v111, v111
	v_mul_f32_e32 v116, 0xbfb8aa3b, v151
	v_add_u32_e32 v110, s6, v205
	v_mov_b64_e32 v[106:107], s[12:13]
	v_ashrrev_i32_e32 v109, 31, v108
	v_exp_f32_e32 v116, v116
	v_mad_i64_i32 v[112:113], s[6:7], v110, s52, v[106:107]
	v_lshlrev_b64 v[108:109], 1, v[108:109]
	v_lshl_add_u64 v[112:113], v[112:113], 0, v[108:109]
	s_waitcnt vmcnt(8)
	global_store_dwordx2 v[112:113], v[114:115], off
	v_add_f32_e32 v111, 1.0, v111
	v_mul_f32_e32 v115, 0xbfb8aa3b, v152
	v_rcp_f32_e32 v114, v111
	v_add_f32_e32 v111, 1.0, v116
	v_exp_f32_e32 v115, v115
	v_mul_f32_e32 v116, 0xbfb8aa3b, v153
	v_exp_f32_e32 v117, v116
	v_rcp_f32_e32 v116, v111
	v_add_f32_e32 v111, 1.0, v115
	v_rcp_f32_e32 v115, v111
	v_add_f32_e32 v111, 1.0, v117
	v_rcp_f32_e32 v117, v111
	v_mov_b32_e32 v118, v150
	v_mov_b32_e32 v119, v152
	v_pk_mul_f32 v[114:115], v[118:119], v[114:115]
	v_mov_b32_e32 v118, v146
	v_mov_b32_e32 v119, v148
	v_mov_b32_e32 v152, v151
	v_pk_mul_f32 v[114:115], v[118:119], v[114:115]
	v_pk_mul_f32 v[116:117], v[152:153], v[116:117]
	v_mov_b32_e32 v148, v147
	v_pk_mul_f32 v[116:117], v[148:149], v[116:117]
	v_and_b32_sdwa v111, v115, v177 dst_sel:DWORD dst_unused:UNUSED_PAD src0_sel:WORD_1 src1_sel:DWORD
	v_and_b32_sdwa v118, v114, v177 dst_sel:DWORD dst_unused:UNUSED_PAD src0_sel:WORD_1 src1_sel:DWORD
	v_add3_u32 v111, v115, v111, s28
	v_and_b32_sdwa v115, v117, v177 dst_sel:DWORD dst_unused:UNUSED_PAD src0_sel:WORD_1 src1_sel:DWORD
	v_add3_u32 v114, v114, v118, s28
	v_and_b32_sdwa v118, v116, v177 dst_sel:DWORD dst_unused:UNUSED_PAD src0_sel:WORD_1 src1_sel:DWORD
	v_add3_u32 v115, v117, v115, s28
	v_add3_u32 v116, v116, v118, s28
	v_and_b32_e32 v115, 0xffff0000, v115
	v_and_b32_e32 v116, 0xffff0000, v116
	v_or_b32_sdwa v115, v115, v111 dst_sel:DWORD dst_unused:UNUSED_PAD src0_sel:DWORD src1_sel:WORD_1
	v_mul_f32_e32 v111, 0xbfb8aa3b, v142
	v_or_b32_sdwa v114, v116, v114 dst_sel:DWORD dst_unused:UNUSED_PAD src0_sel:DWORD src1_sel:WORD_1
	v_exp_f32_e32 v111, v111
	v_mul_f32_e32 v116, 0xbfb8aa3b, v143
	v_exp_f32_e32 v116, v116
	global_store_dwordx2 v[112:113], v[114:115], off offset:32
	v_add_f32_e32 v111, 1.0, v111
	v_mul_f32_e32 v115, 0xbfb8aa3b, v144
	v_rcp_f32_e32 v114, v111
	v_add_f32_e32 v111, 1.0, v116
	v_exp_f32_e32 v115, v115
	v_mul_f32_e32 v116, 0xbfb8aa3b, v145
	v_exp_f32_e32 v117, v116
	v_rcp_f32_e32 v116, v111
	v_add_f32_e32 v111, 1.0, v115
	v_rcp_f32_e32 v115, v111
	v_add_f32_e32 v111, 1.0, v117
	v_rcp_f32_e32 v117, v111
	v_mov_b32_e32 v118, v142
	v_mov_b32_e32 v119, v144
	v_pk_mul_f32 v[114:115], v[118:119], v[114:115]
	v_mov_b32_e32 v118, v138
	v_mov_b32_e32 v119, v140
	v_mov_b32_e32 v144, v143
	v_pk_mul_f32 v[114:115], v[118:119], v[114:115]
	v_pk_mul_f32 v[116:117], v[144:145], v[116:117]
	v_mov_b32_e32 v140, v139
	v_pk_mul_f32 v[116:117], v[140:141], v[116:117]
	v_and_b32_sdwa v111, v115, v177 dst_sel:DWORD dst_unused:UNUSED_PAD src0_sel:WORD_1 src1_sel:DWORD
	v_and_b32_sdwa v118, v114, v177 dst_sel:DWORD dst_unused:UNUSED_PAD src0_sel:WORD_1 src1_sel:DWORD
	v_add3_u32 v111, v115, v111, s28
	v_and_b32_sdwa v115, v117, v177 dst_sel:DWORD dst_unused:UNUSED_PAD src0_sel:WORD_1 src1_sel:DWORD
	v_add3_u32 v114, v114, v118, s28
	v_and_b32_sdwa v118, v116, v177 dst_sel:DWORD dst_unused:UNUSED_PAD src0_sel:WORD_1 src1_sel:DWORD
	v_add3_u32 v115, v117, v115, s28
	v_add3_u32 v116, v116, v118, s28
	v_and_b32_e32 v115, 0xffff0000, v115
	v_and_b32_e32 v116, 0xffff0000, v116
	v_or_b32_sdwa v115, v115, v111 dst_sel:DWORD dst_unused:UNUSED_PAD src0_sel:DWORD src1_sel:WORD_1
	v_mul_f32_e32 v111, 0xbfb8aa3b, v102
	v_or_b32_sdwa v114, v116, v114 dst_sel:DWORD dst_unused:UNUSED_PAD src0_sel:DWORD src1_sel:WORD_1
	v_exp_f32_e32 v111, v111
	v_mul_f32_e32 v116, 0xbfb8aa3b, v103
	v_exp_f32_e32 v116, v116
	global_store_dwordx2 v[112:113], v[114:115], off offset:64
	v_add_f32_e32 v111, 1.0, v111
	v_mul_f32_e32 v115, 0xbfb8aa3b, v104
	v_rcp_f32_e32 v114, v111
	v_add_f32_e32 v111, 1.0, v116
	v_exp_f32_e32 v115, v115
	v_mul_f32_e32 v116, 0xbfb8aa3b, v105
	v_exp_f32_e32 v117, v116
	v_rcp_f32_e32 v116, v111
	v_add_f32_e32 v111, 1.0, v115
	v_rcp_f32_e32 v115, v111
	v_add_f32_e32 v111, 1.0, v117
	v_rcp_f32_e32 v117, v111
	v_mov_b32_e32 v118, v102
	v_mov_b32_e32 v119, v104
	v_mov_b32_e32 v104, v103
	v_pk_mul_f32 v[114:115], v[118:119], v[114:115]
	v_mov_b32_e32 v119, v100
	v_pk_mul_f32 v[102:103], v[104:105], v[116:117]
	v_mov_b32_e32 v100, v99
	v_mov_b32_e32 v118, v98
	v_pk_mul_f32 v[98:99], v[100:101], v[102:103]
	v_pk_mul_f32 v[114:115], v[118:119], v[114:115]
	v_and_b32_sdwa v102, v99, v177 dst_sel:DWORD dst_unused:UNUSED_PAD src0_sel:WORD_1 src1_sel:DWORD
	v_and_b32_sdwa v103, v98, v177 dst_sel:DWORD dst_unused:UNUSED_PAD src0_sel:WORD_1 src1_sel:DWORD
	v_and_b32_sdwa v100, v115, v177 dst_sel:DWORD dst_unused:UNUSED_PAD src0_sel:WORD_1 src1_sel:DWORD
	v_and_b32_sdwa v101, v114, v177 dst_sel:DWORD dst_unused:UNUSED_PAD src0_sel:WORD_1 src1_sel:DWORD
	v_add3_u32 v99, v99, v102, s28
	v_add3_u32 v98, v98, v103, s28
	v_add3_u32 v101, v114, v101, s28
	v_add3_u32 v100, v115, v100, s28
	v_and_b32_e32 v99, 0xffff0000, v99
	v_and_b32_e32 v98, 0xffff0000, v98
	v_or_b32_sdwa v99, v99, v100 dst_sel:DWORD dst_unused:UNUSED_PAD src0_sel:DWORD src1_sel:WORD_1
	v_or_b32_sdwa v98, v98, v101 dst_sel:DWORD dst_unused:UNUSED_PAD src0_sel:DWORD src1_sel:WORD_1
	global_store_dwordx2 v[112:113], v[98:99], off offset:96
	v_mul_f32_e32 v99, 0xbfb8aa3b, v94
	v_exp_f32_e32 v100, v99
	v_mul_f32_e32 v99, 0xbfb8aa3b, v95
	v_mul_f32_e32 v102, 0xbfb8aa3b, v96
	v_exp_f32_e32 v101, v99
	v_exp_f32_e32 v103, v102
	v_mul_f32_e32 v102, 0xbfb8aa3b, v97
	v_exp_f32_e32 v104, v102
	v_add_f32_e32 v101, 1.0, v101
	v_add_f32_e32 v100, 1.0, v100
	v_rcp_f32_e32 v102, v101
	v_add_f32_e32 v101, 1.0, v103
	v_add_f32_e32 v103, 1.0, v104
	v_rcp_f32_e32 v100, v100
	v_rcp_f32_e32 v101, v101
	v_rcp_f32_e32 v103, v103
	v_mov_b32_e32 v104, v94
	v_mov_b32_e32 v105, v96
	v_mov_b32_e32 v96, v95
	v_pk_mul_f32 v[100:101], v[104:105], v[100:101]
	v_mov_b32_e32 v105, v92
	v_pk_mul_f32 v[94:95], v[96:97], v[102:103]
	v_mov_b32_e32 v92, v91
	v_mov_b32_e32 v104, v90
	v_pk_mul_f32 v[90:91], v[92:93], v[94:95]
	v_pk_mul_f32 v[100:101], v[104:105], v[100:101]
	v_and_b32_sdwa v94, v91, v177 dst_sel:DWORD dst_unused:UNUSED_PAD src0_sel:WORD_1 src1_sel:DWORD
	v_and_b32_sdwa v92, v101, v177 dst_sel:DWORD dst_unused:UNUSED_PAD src0_sel:WORD_1 src1_sel:DWORD
	v_and_b32_sdwa v95, v90, v177 dst_sel:DWORD dst_unused:UNUSED_PAD src0_sel:WORD_1 src1_sel:DWORD
	v_add3_u32 v91, v91, v94, s28
	v_and_b32_sdwa v93, v100, v177 dst_sel:DWORD dst_unused:UNUSED_PAD src0_sel:WORD_1 src1_sel:DWORD
	v_add3_u32 v92, v101, v92, s28
	v_add3_u32 v90, v90, v95, s28
	v_and_b32_e32 v91, 0xffff0000, v91
	v_add3_u32 v93, v100, v93, s28
	v_and_b32_e32 v90, 0xffff0000, v90
	v_or_b32_sdwa v91, v91, v92 dst_sel:DWORD dst_unused:UNUSED_PAD src0_sel:DWORD src1_sel:WORD_1
	v_mul_f32_e32 v92, 0xbfb8aa3b, v86
	v_or_b32_sdwa v90, v90, v93 dst_sel:DWORD dst_unused:UNUSED_PAD src0_sel:DWORD src1_sel:WORD_1
	v_exp_f32_e32 v92, v92
	v_mul_f32_e32 v93, 0xbfb8aa3b, v87
	v_or_b32_e32 v98, 16, v110
	v_exp_f32_e32 v93, v93
	v_mad_i64_i32 v[98:99], s[6:7], v98, s52, v[106:107]
	v_lshl_add_u64 v[98:99], v[98:99], 0, v[108:109]
	global_store_dwordx2 v[98:99], v[90:91], off
	v_add_f32_e32 v90, 1.0, v92
	v_mul_f32_e32 v92, 0xbfb8aa3b, v88
	v_add_f32_e32 v91, 1.0, v93
	v_exp_f32_e32 v93, v92
	v_mul_f32_e32 v92, 0xbfb8aa3b, v89
	v_exp_f32_e32 v94, v92
	v_rcp_f32_e32 v92, v91
	v_add_f32_e32 v91, 1.0, v93
	v_rcp_f32_e32 v90, v90
	v_add_f32_e32 v93, 1.0, v94
	v_rcp_f32_e32 v91, v91
	v_rcp_f32_e32 v93, v93
	v_mov_b32_e32 v94, v86
	v_mov_b32_e32 v95, v88
	v_mov_b32_e32 v88, v87
	v_pk_mul_f32 v[90:91], v[94:95], v[90:91]
	v_mov_b32_e32 v95, v84
	v_pk_mul_f32 v[86:87], v[88:89], v[92:93]
	v_mov_b32_e32 v84, v83
	v_mov_b32_e32 v94, v82
	v_pk_mul_f32 v[82:83], v[84:85], v[86:87]
	v_pk_mul_f32 v[90:91], v[94:95], v[90:91]
	v_and_b32_sdwa v86, v83, v177 dst_sel:DWORD dst_unused:UNUSED_PAD src0_sel:WORD_1 src1_sel:DWORD
	v_and_b32_sdwa v84, v91, v177 dst_sel:DWORD dst_unused:UNUSED_PAD src0_sel:WORD_1 src1_sel:DWORD
	v_and_b32_sdwa v87, v82, v177 dst_sel:DWORD dst_unused:UNUSED_PAD src0_sel:WORD_1 src1_sel:DWORD
	v_add3_u32 v83, v83, v86, s28
	v_and_b32_sdwa v85, v90, v177 dst_sel:DWORD dst_unused:UNUSED_PAD src0_sel:WORD_1 src1_sel:DWORD
	v_add3_u32 v84, v91, v84, s28
	v_add3_u32 v82, v82, v87, s28
	v_and_b32_e32 v83, 0xffff0000, v83
	v_add3_u32 v85, v90, v85, s28
	v_and_b32_e32 v82, 0xffff0000, v82
	v_or_b32_sdwa v83, v83, v84 dst_sel:DWORD dst_unused:UNUSED_PAD src0_sel:DWORD src1_sel:WORD_1
	v_mul_f32_e32 v84, 0xbfb8aa3b, v78
	v_or_b32_sdwa v82, v82, v85 dst_sel:DWORD dst_unused:UNUSED_PAD src0_sel:DWORD src1_sel:WORD_1
	v_exp_f32_e32 v84, v84
	v_mul_f32_e32 v85, 0xbfb8aa3b, v79
	v_exp_f32_e32 v85, v85
	global_store_dwordx2 v[98:99], v[82:83], off offset:32
	v_add_f32_e32 v82, 1.0, v84
	v_mul_f32_e32 v84, 0xbfb8aa3b, v80
	v_add_f32_e32 v83, 1.0, v85
	v_exp_f32_e32 v85, v84
	v_mul_f32_e32 v84, 0xbfb8aa3b, v81
	v_exp_f32_e32 v86, v84
	v_rcp_f32_e32 v84, v83
	v_add_f32_e32 v83, 1.0, v85
	v_rcp_f32_e32 v82, v82
	v_add_f32_e32 v85, 1.0, v86
	v_rcp_f32_e32 v83, v83
	v_rcp_f32_e32 v85, v85
	v_mov_b32_e32 v86, v78
	v_mov_b32_e32 v87, v80
	v_mov_b32_e32 v80, v79
	v_pk_mul_f32 v[82:83], v[86:87], v[82:83]
	v_mov_b32_e32 v87, v76
	v_pk_mul_f32 v[78:79], v[80:81], v[84:85]
	v_mov_b32_e32 v76, v75
	v_mov_b32_e32 v86, v74
	v_pk_mul_f32 v[74:75], v[76:77], v[78:79]
	v_pk_mul_f32 v[82:83], v[86:87], v[82:83]
	v_and_b32_sdwa v78, v75, v177 dst_sel:DWORD dst_unused:UNUSED_PAD src0_sel:WORD_1 src1_sel:DWORD
	v_and_b32_sdwa v76, v83, v177 dst_sel:DWORD dst_unused:UNUSED_PAD src0_sel:WORD_1 src1_sel:DWORD
	v_and_b32_sdwa v79, v74, v177 dst_sel:DWORD dst_unused:UNUSED_PAD src0_sel:WORD_1 src1_sel:DWORD
	v_add3_u32 v75, v75, v78, s28
	v_and_b32_sdwa v77, v82, v177 dst_sel:DWORD dst_unused:UNUSED_PAD src0_sel:WORD_1 src1_sel:DWORD
	v_add3_u32 v76, v83, v76, s28
	v_add3_u32 v74, v74, v79, s28
	v_and_b32_e32 v75, 0xffff0000, v75
	v_add3_u32 v77, v82, v77, s28
	v_and_b32_e32 v74, 0xffff0000, v74
	v_or_b32_sdwa v75, v75, v76 dst_sel:DWORD dst_unused:UNUSED_PAD src0_sel:DWORD src1_sel:WORD_1
	v_mul_f32_e32 v76, 0xbfb8aa3b, v70
	v_or_b32_sdwa v74, v74, v77 dst_sel:DWORD dst_unused:UNUSED_PAD src0_sel:DWORD src1_sel:WORD_1
	v_exp_f32_e32 v76, v76
	v_mul_f32_e32 v77, 0xbfb8aa3b, v71
	v_exp_f32_e32 v77, v77
	global_store_dwordx2 v[98:99], v[74:75], off offset:64
	v_add_f32_e32 v74, 1.0, v76
	v_mul_f32_e32 v76, 0xbfb8aa3b, v72
	v_add_f32_e32 v75, 1.0, v77
	v_exp_f32_e32 v77, v76
	v_mul_f32_e32 v76, 0xbfb8aa3b, v73
	v_exp_f32_e32 v78, v76
	v_rcp_f32_e32 v76, v75
	v_add_f32_e32 v75, 1.0, v77
	v_rcp_f32_e32 v74, v74
	v_add_f32_e32 v77, 1.0, v78
	v_rcp_f32_e32 v75, v75
	v_rcp_f32_e32 v77, v77
	v_mov_b32_e32 v78, v70
	v_mov_b32_e32 v79, v72
	v_mov_b32_e32 v72, v71
	v_pk_mul_f32 v[74:75], v[78:79], v[74:75]
	v_mov_b32_e32 v79, v68
	v_pk_mul_f32 v[70:71], v[72:73], v[76:77]
	v_mov_b32_e32 v68, v67
	v_mov_b32_e32 v78, v66
	v_pk_mul_f32 v[66:67], v[68:69], v[70:71]
	v_pk_mul_f32 v[74:75], v[78:79], v[74:75]
	v_and_b32_sdwa v70, v67, v177 dst_sel:DWORD dst_unused:UNUSED_PAD src0_sel:WORD_1 src1_sel:DWORD
	v_and_b32_sdwa v71, v66, v177 dst_sel:DWORD dst_unused:UNUSED_PAD src0_sel:WORD_1 src1_sel:DWORD
	v_and_b32_sdwa v68, v75, v177 dst_sel:DWORD dst_unused:UNUSED_PAD src0_sel:WORD_1 src1_sel:DWORD
	v_and_b32_sdwa v69, v74, v177 dst_sel:DWORD dst_unused:UNUSED_PAD src0_sel:WORD_1 src1_sel:DWORD
	v_add3_u32 v67, v67, v70, s28
	v_add3_u32 v66, v66, v71, s28
	v_add3_u32 v69, v74, v69, s28
	v_add3_u32 v68, v75, v68, s28
	v_and_b32_e32 v67, 0xffff0000, v67
	v_and_b32_e32 v66, 0xffff0000, v66
	v_or_b32_sdwa v67, v67, v68 dst_sel:DWORD dst_unused:UNUSED_PAD src0_sel:DWORD src1_sel:WORD_1
	v_or_b32_sdwa v66, v66, v69 dst_sel:DWORD dst_unused:UNUSED_PAD src0_sel:DWORD src1_sel:WORD_1
	global_store_dwordx2 v[98:99], v[66:67], off offset:96
	v_mul_f32_e32 v67, 0xbfb8aa3b, v62
	v_exp_f32_e32 v68, v67
	v_mul_f32_e32 v67, 0xbfb8aa3b, v63
	v_mul_f32_e32 v70, 0xbfb8aa3b, v64
	v_exp_f32_e32 v69, v67
	v_exp_f32_e32 v71, v70
	v_mul_f32_e32 v70, 0xbfb8aa3b, v65
	v_exp_f32_e32 v72, v70
	v_add_f32_e32 v69, 1.0, v69
	v_add_f32_e32 v68, 1.0, v68
	v_rcp_f32_e32 v70, v69
	v_add_f32_e32 v69, 1.0, v71
	v_add_f32_e32 v71, 1.0, v72
	v_rcp_f32_e32 v68, v68
	v_rcp_f32_e32 v69, v69
	v_rcp_f32_e32 v71, v71
	v_mov_b32_e32 v72, v62
	v_mov_b32_e32 v73, v64
	v_mov_b32_e32 v64, v63
	v_pk_mul_f32 v[68:69], v[72:73], v[68:69]
	v_mov_b32_e32 v73, v60
	v_pk_mul_f32 v[62:63], v[64:65], v[70:71]
	v_mov_b32_e32 v60, v59
	v_mov_b32_e32 v72, v58
	v_pk_mul_f32 v[58:59], v[60:61], v[62:63]
	v_pk_mul_f32 v[68:69], v[72:73], v[68:69]
	v_and_b32_sdwa v62, v59, v177 dst_sel:DWORD dst_unused:UNUSED_PAD src0_sel:WORD_1 src1_sel:DWORD
	v_and_b32_sdwa v60, v69, v177 dst_sel:DWORD dst_unused:UNUSED_PAD src0_sel:WORD_1 src1_sel:DWORD
	v_and_b32_sdwa v63, v58, v177 dst_sel:DWORD dst_unused:UNUSED_PAD src0_sel:WORD_1 src1_sel:DWORD
	v_add3_u32 v59, v59, v62, s28
	v_and_b32_sdwa v61, v68, v177 dst_sel:DWORD dst_unused:UNUSED_PAD src0_sel:WORD_1 src1_sel:DWORD
	v_add3_u32 v60, v69, v60, s28
	v_add3_u32 v58, v58, v63, s28
	v_and_b32_e32 v59, 0xffff0000, v59
	v_add3_u32 v61, v68, v61, s28
	v_and_b32_e32 v58, 0xffff0000, v58
	v_or_b32_sdwa v59, v59, v60 dst_sel:DWORD dst_unused:UNUSED_PAD src0_sel:DWORD src1_sel:WORD_1
	v_mul_f32_e32 v60, 0xbfb8aa3b, v54
	v_or_b32_sdwa v58, v58, v61 dst_sel:DWORD dst_unused:UNUSED_PAD src0_sel:DWORD src1_sel:WORD_1
	v_exp_f32_e32 v60, v60
	v_mul_f32_e32 v61, 0xbfb8aa3b, v55
	v_or_b32_e32 v66, 32, v110
	v_exp_f32_e32 v61, v61
	v_mad_i64_i32 v[66:67], s[6:7], v66, s52, v[106:107]
	v_lshl_add_u64 v[66:67], v[66:67], 0, v[108:109]
	global_store_dwordx2 v[66:67], v[58:59], off
	v_add_f32_e32 v58, 1.0, v60
	v_mul_f32_e32 v60, 0xbfb8aa3b, v56
	v_add_f32_e32 v59, 1.0, v61
	v_exp_f32_e32 v61, v60
	v_mul_f32_e32 v60, 0xbfb8aa3b, v57
	v_exp_f32_e32 v62, v60
	v_rcp_f32_e32 v60, v59
	v_add_f32_e32 v59, 1.0, v61
	v_rcp_f32_e32 v58, v58
	v_add_f32_e32 v61, 1.0, v62
	v_rcp_f32_e32 v59, v59
	v_rcp_f32_e32 v61, v61
	v_mov_b32_e32 v62, v54
	v_mov_b32_e32 v63, v56
	v_mov_b32_e32 v56, v55
	v_pk_mul_f32 v[58:59], v[62:63], v[58:59]
	v_mov_b32_e32 v63, v52
	v_pk_mul_f32 v[54:55], v[56:57], v[60:61]
	v_mov_b32_e32 v52, v51
	v_mov_b32_e32 v62, v50
	v_pk_mul_f32 v[50:51], v[52:53], v[54:55]
	v_pk_mul_f32 v[58:59], v[62:63], v[58:59]
	v_and_b32_sdwa v54, v51, v177 dst_sel:DWORD dst_unused:UNUSED_PAD src0_sel:WORD_1 src1_sel:DWORD
	v_and_b32_sdwa v52, v59, v177 dst_sel:DWORD dst_unused:UNUSED_PAD src0_sel:WORD_1 src1_sel:DWORD
	v_and_b32_sdwa v55, v50, v177 dst_sel:DWORD dst_unused:UNUSED_PAD src0_sel:WORD_1 src1_sel:DWORD
	v_add3_u32 v51, v51, v54, s28
	v_and_b32_sdwa v53, v58, v177 dst_sel:DWORD dst_unused:UNUSED_PAD src0_sel:WORD_1 src1_sel:DWORD
	v_add3_u32 v52, v59, v52, s28
	v_add3_u32 v50, v50, v55, s28
	v_and_b32_e32 v51, 0xffff0000, v51
	v_add3_u32 v53, v58, v53, s28
	v_and_b32_e32 v50, 0xffff0000, v50
	v_or_b32_sdwa v51, v51, v52 dst_sel:DWORD dst_unused:UNUSED_PAD src0_sel:DWORD src1_sel:WORD_1
	v_mul_f32_e32 v52, 0xbfb8aa3b, v46
	v_or_b32_sdwa v50, v50, v53 dst_sel:DWORD dst_unused:UNUSED_PAD src0_sel:DWORD src1_sel:WORD_1
	v_exp_f32_e32 v52, v52
	v_mul_f32_e32 v53, 0xbfb8aa3b, v47
	v_exp_f32_e32 v53, v53
	global_store_dwordx2 v[66:67], v[50:51], off offset:32
	v_add_f32_e32 v50, 1.0, v52
	v_mul_f32_e32 v52, 0xbfb8aa3b, v48
	v_add_f32_e32 v51, 1.0, v53
	v_exp_f32_e32 v53, v52
	v_mul_f32_e32 v52, 0xbfb8aa3b, v49
	v_exp_f32_e32 v54, v52
	v_rcp_f32_e32 v52, v51
	v_add_f32_e32 v51, 1.0, v53
	v_rcp_f32_e32 v50, v50
	v_add_f32_e32 v53, 1.0, v54
	v_rcp_f32_e32 v51, v51
	v_rcp_f32_e32 v53, v53
	v_mov_b32_e32 v54, v46
	v_mov_b32_e32 v55, v48
	v_mov_b32_e32 v48, v47
	v_pk_mul_f32 v[50:51], v[54:55], v[50:51]
	v_mov_b32_e32 v55, v44
	v_pk_mul_f32 v[46:47], v[48:49], v[52:53]
	v_mov_b32_e32 v44, v43
	v_mov_b32_e32 v54, v42
	v_pk_mul_f32 v[42:43], v[44:45], v[46:47]
	v_pk_mul_f32 v[50:51], v[54:55], v[50:51]
	v_and_b32_sdwa v46, v43, v177 dst_sel:DWORD dst_unused:UNUSED_PAD src0_sel:WORD_1 src1_sel:DWORD
	v_and_b32_sdwa v44, v51, v177 dst_sel:DWORD dst_unused:UNUSED_PAD src0_sel:WORD_1 src1_sel:DWORD
	v_and_b32_sdwa v47, v42, v177 dst_sel:DWORD dst_unused:UNUSED_PAD src0_sel:WORD_1 src1_sel:DWORD
	v_add3_u32 v43, v43, v46, s28
	v_and_b32_sdwa v45, v50, v177 dst_sel:DWORD dst_unused:UNUSED_PAD src0_sel:WORD_1 src1_sel:DWORD
	v_add3_u32 v44, v51, v44, s28
	v_add3_u32 v42, v42, v47, s28
	v_and_b32_e32 v43, 0xffff0000, v43
	v_add3_u32 v45, v50, v45, s28
	v_and_b32_e32 v42, 0xffff0000, v42
	v_or_b32_sdwa v43, v43, v44 dst_sel:DWORD dst_unused:UNUSED_PAD src0_sel:DWORD src1_sel:WORD_1
	v_mul_f32_e32 v44, 0xbfb8aa3b, v38
	v_or_b32_sdwa v42, v42, v45 dst_sel:DWORD dst_unused:UNUSED_PAD src0_sel:DWORD src1_sel:WORD_1
	v_exp_f32_e32 v44, v44
	v_mul_f32_e32 v45, 0xbfb8aa3b, v39
	v_exp_f32_e32 v45, v45
	global_store_dwordx2 v[66:67], v[42:43], off offset:64
	v_add_f32_e32 v42, 1.0, v44
	v_mul_f32_e32 v44, 0xbfb8aa3b, v40
	v_add_f32_e32 v43, 1.0, v45
	v_exp_f32_e32 v45, v44
	v_mul_f32_e32 v44, 0xbfb8aa3b, v41
	v_exp_f32_e32 v46, v44
	v_rcp_f32_e32 v44, v43
	v_add_f32_e32 v43, 1.0, v45
	v_rcp_f32_e32 v42, v42
	v_add_f32_e32 v45, 1.0, v46
	v_rcp_f32_e32 v43, v43
	v_rcp_f32_e32 v45, v45
	v_mov_b32_e32 v46, v38
	v_mov_b32_e32 v47, v40
	v_mov_b32_e32 v40, v39
	v_pk_mul_f32 v[42:43], v[46:47], v[42:43]
	v_mov_b32_e32 v47, v36
	v_pk_mul_f32 v[38:39], v[40:41], v[44:45]
	v_mov_b32_e32 v36, v35
	v_mov_b32_e32 v46, v34
	v_pk_mul_f32 v[34:35], v[36:37], v[38:39]
	v_pk_mul_f32 v[42:43], v[46:47], v[42:43]
	v_and_b32_sdwa v38, v35, v177 dst_sel:DWORD dst_unused:UNUSED_PAD src0_sel:WORD_1 src1_sel:DWORD
	v_and_b32_sdwa v39, v34, v177 dst_sel:DWORD dst_unused:UNUSED_PAD src0_sel:WORD_1 src1_sel:DWORD
	v_and_b32_sdwa v36, v43, v177 dst_sel:DWORD dst_unused:UNUSED_PAD src0_sel:WORD_1 src1_sel:DWORD
	v_and_b32_sdwa v37, v42, v177 dst_sel:DWORD dst_unused:UNUSED_PAD src0_sel:WORD_1 src1_sel:DWORD
	v_add3_u32 v35, v35, v38, s28
	v_add3_u32 v34, v34, v39, s28
	v_add3_u32 v37, v42, v37, s28
	v_add3_u32 v36, v43, v36, s28
	v_and_b32_e32 v35, 0xffff0000, v35
	v_and_b32_e32 v34, 0xffff0000, v34
	v_or_b32_sdwa v35, v35, v36 dst_sel:DWORD dst_unused:UNUSED_PAD src0_sel:DWORD src1_sel:WORD_1
	v_or_b32_sdwa v34, v34, v37 dst_sel:DWORD dst_unused:UNUSED_PAD src0_sel:DWORD src1_sel:WORD_1
	global_store_dwordx2 v[66:67], v[34:35], off offset:96
	v_mul_f32_e32 v35, 0xbfb8aa3b, v30
	v_exp_f32_e32 v36, v35
	v_mul_f32_e32 v35, 0xbfb8aa3b, v31
	v_mul_f32_e32 v38, 0xbfb8aa3b, v32
	v_exp_f32_e32 v37, v35
	v_exp_f32_e32 v39, v38
	v_mul_f32_e32 v38, 0xbfb8aa3b, v33
	v_exp_f32_e32 v40, v38
	v_add_f32_e32 v37, 1.0, v37
	v_add_f32_e32 v36, 1.0, v36
	v_rcp_f32_e32 v38, v37
	v_add_f32_e32 v37, 1.0, v39
	v_add_f32_e32 v39, 1.0, v40
	v_rcp_f32_e32 v36, v36
	v_rcp_f32_e32 v37, v37
	v_rcp_f32_e32 v39, v39
	v_mov_b32_e32 v40, v30
	v_mov_b32_e32 v41, v32
	v_mov_b32_e32 v32, v31
	v_pk_mul_f32 v[36:37], v[40:41], v[36:37]
	v_mov_b32_e32 v41, v28
	v_pk_mul_f32 v[30:31], v[32:33], v[38:39]
	v_mov_b32_e32 v28, v27
	v_mov_b32_e32 v40, v26
	v_pk_mul_f32 v[26:27], v[28:29], v[30:31]
	v_pk_mul_f32 v[36:37], v[40:41], v[36:37]
	v_and_b32_sdwa v30, v27, v177 dst_sel:DWORD dst_unused:UNUSED_PAD src0_sel:WORD_1 src1_sel:DWORD
	v_and_b32_sdwa v28, v37, v177 dst_sel:DWORD dst_unused:UNUSED_PAD src0_sel:WORD_1 src1_sel:DWORD
	v_and_b32_sdwa v31, v26, v177 dst_sel:DWORD dst_unused:UNUSED_PAD src0_sel:WORD_1 src1_sel:DWORD
	v_add3_u32 v27, v27, v30, s28
	v_and_b32_sdwa v29, v36, v177 dst_sel:DWORD dst_unused:UNUSED_PAD src0_sel:WORD_1 src1_sel:DWORD
	v_add3_u32 v28, v37, v28, s28
	v_add3_u32 v26, v26, v31, s28
	v_and_b32_e32 v27, 0xffff0000, v27
	v_add3_u32 v29, v36, v29, s28
	v_and_b32_e32 v26, 0xffff0000, v26
	v_or_b32_sdwa v27, v27, v28 dst_sel:DWORD dst_unused:UNUSED_PAD src0_sel:DWORD src1_sel:WORD_1
	v_mul_f32_e32 v28, 0xbfb8aa3b, v22
	v_or_b32_sdwa v26, v26, v29 dst_sel:DWORD dst_unused:UNUSED_PAD src0_sel:DWORD src1_sel:WORD_1
	v_exp_f32_e32 v28, v28
	v_mul_f32_e32 v29, 0xbfb8aa3b, v23
	v_or_b32_e32 v34, 48, v110
	v_exp_f32_e32 v29, v29
	v_mad_i64_i32 v[34:35], s[6:7], v34, s52, v[106:107]
	v_lshl_add_u64 v[34:35], v[34:35], 0, v[108:109]
	global_store_dwordx2 v[34:35], v[26:27], off
	v_add_f32_e32 v26, 1.0, v28
	v_mul_f32_e32 v28, 0xbfb8aa3b, v24
	v_add_f32_e32 v27, 1.0, v29
	v_exp_f32_e32 v29, v28
	v_mul_f32_e32 v28, 0xbfb8aa3b, v25
	v_exp_f32_e32 v30, v28
	v_rcp_f32_e32 v28, v27
	v_add_f32_e32 v27, 1.0, v29
	v_rcp_f32_e32 v26, v26
	v_add_f32_e32 v29, 1.0, v30
	v_rcp_f32_e32 v27, v27
	v_rcp_f32_e32 v29, v29
	v_mov_b32_e32 v30, v22
	v_mov_b32_e32 v31, v24
	v_mov_b32_e32 v24, v23
	v_pk_mul_f32 v[26:27], v[30:31], v[26:27]
	v_mov_b32_e32 v31, v20
	v_pk_mul_f32 v[22:23], v[24:25], v[28:29]
	v_mov_b32_e32 v20, v19
	v_mov_b32_e32 v30, v18
	v_pk_mul_f32 v[18:19], v[20:21], v[22:23]
	v_pk_mul_f32 v[26:27], v[30:31], v[26:27]
	v_and_b32_sdwa v22, v19, v177 dst_sel:DWORD dst_unused:UNUSED_PAD src0_sel:WORD_1 src1_sel:DWORD
	v_and_b32_sdwa v20, v27, v177 dst_sel:DWORD dst_unused:UNUSED_PAD src0_sel:WORD_1 src1_sel:DWORD
	v_and_b32_sdwa v23, v18, v177 dst_sel:DWORD dst_unused:UNUSED_PAD src0_sel:WORD_1 src1_sel:DWORD
	v_add3_u32 v19, v19, v22, s28
	v_and_b32_sdwa v21, v26, v177 dst_sel:DWORD dst_unused:UNUSED_PAD src0_sel:WORD_1 src1_sel:DWORD
	v_add3_u32 v20, v27, v20, s28
	v_add3_u32 v18, v18, v23, s28
	v_and_b32_e32 v19, 0xffff0000, v19
	v_add3_u32 v21, v26, v21, s28
	v_and_b32_e32 v18, 0xffff0000, v18
	v_or_b32_sdwa v19, v19, v20 dst_sel:DWORD dst_unused:UNUSED_PAD src0_sel:DWORD src1_sel:WORD_1
	v_mul_f32_e32 v20, 0xbfb8aa3b, v14
	v_or_b32_sdwa v18, v18, v21 dst_sel:DWORD dst_unused:UNUSED_PAD src0_sel:DWORD src1_sel:WORD_1
	v_exp_f32_e32 v20, v20
	v_mul_f32_e32 v21, 0xbfb8aa3b, v15
	v_exp_f32_e32 v21, v21
	global_store_dwordx2 v[34:35], v[18:19], off offset:32
	v_add_f32_e32 v18, 1.0, v20
	v_mul_f32_e32 v20, 0xbfb8aa3b, v16
	v_add_f32_e32 v19, 1.0, v21
	v_exp_f32_e32 v21, v20
	v_mul_f32_e32 v20, 0xbfb8aa3b, v17
	v_exp_f32_e32 v22, v20
	v_rcp_f32_e32 v20, v19
	v_add_f32_e32 v19, 1.0, v21
	v_rcp_f32_e32 v18, v18
	v_add_f32_e32 v21, 1.0, v22
	v_rcp_f32_e32 v19, v19
	v_rcp_f32_e32 v21, v21
	v_mov_b32_e32 v22, v14
	v_mov_b32_e32 v23, v16
	v_mov_b32_e32 v16, v15
	v_pk_mul_f32 v[18:19], v[22:23], v[18:19]
	v_mov_b32_e32 v23, v12
	v_pk_mul_f32 v[14:15], v[16:17], v[20:21]
	v_mov_b32_e32 v12, v11
	v_mov_b32_e32 v22, v10
	v_pk_mul_f32 v[10:11], v[12:13], v[14:15]
	v_pk_mul_f32 v[18:19], v[22:23], v[18:19]
	v_and_b32_sdwa v14, v11, v177 dst_sel:DWORD dst_unused:UNUSED_PAD src0_sel:WORD_1 src1_sel:DWORD
	v_and_b32_sdwa v12, v19, v177 dst_sel:DWORD dst_unused:UNUSED_PAD src0_sel:WORD_1 src1_sel:DWORD
	v_and_b32_sdwa v15, v10, v177 dst_sel:DWORD dst_unused:UNUSED_PAD src0_sel:WORD_1 src1_sel:DWORD
	v_add3_u32 v11, v11, v14, s28
	v_and_b32_sdwa v13, v18, v177 dst_sel:DWORD dst_unused:UNUSED_PAD src0_sel:WORD_1 src1_sel:DWORD
	v_add3_u32 v12, v19, v12, s28
	v_add3_u32 v10, v10, v15, s28
	v_and_b32_e32 v11, 0xffff0000, v11
	v_add3_u32 v13, v18, v13, s28
	v_and_b32_e32 v10, 0xffff0000, v10
	v_or_b32_sdwa v11, v11, v12 dst_sel:DWORD dst_unused:UNUSED_PAD src0_sel:DWORD src1_sel:WORD_1
	v_mul_f32_e32 v12, 0xbfb8aa3b, v6
	v_or_b32_sdwa v10, v10, v13 dst_sel:DWORD dst_unused:UNUSED_PAD src0_sel:DWORD src1_sel:WORD_1
	v_exp_f32_e32 v12, v12
	v_mul_f32_e32 v13, 0xbfb8aa3b, v7
	v_exp_f32_e32 v13, v13
	global_store_dwordx2 v[34:35], v[10:11], off offset:64
	v_add_f32_e32 v10, 1.0, v12
	v_mul_f32_e32 v12, 0xbfb8aa3b, v8
	v_add_f32_e32 v11, 1.0, v13
	v_exp_f32_e32 v13, v12
	v_mul_f32_e32 v12, 0xbfb8aa3b, v9
	v_exp_f32_e32 v14, v12
	v_rcp_f32_e32 v12, v11
	v_add_f32_e32 v11, 1.0, v13
	v_rcp_f32_e32 v10, v10
	v_add_f32_e32 v13, 1.0, v14
	v_rcp_f32_e32 v11, v11
	v_rcp_f32_e32 v13, v13
	v_mov_b32_e32 v14, v6
	v_mov_b32_e32 v15, v8
	v_mov_b32_e32 v8, v7
	v_pk_mul_f32 v[10:11], v[14:15], v[10:11]
	v_mov_b32_e32 v15, v4
	v_pk_mul_f32 v[6:7], v[8:9], v[12:13]
	v_mov_b32_e32 v4, v3
	v_mov_b32_e32 v14, v2
	v_pk_mul_f32 v[2:3], v[4:5], v[6:7]
	v_pk_mul_f32 v[10:11], v[14:15], v[10:11]
	v_and_b32_sdwa v6, v3, v177 dst_sel:DWORD dst_unused:UNUSED_PAD src0_sel:WORD_1 src1_sel:DWORD
	v_and_b32_sdwa v7, v2, v177 dst_sel:DWORD dst_unused:UNUSED_PAD src0_sel:WORD_1 src1_sel:DWORD
	v_and_b32_sdwa v4, v11, v177 dst_sel:DWORD dst_unused:UNUSED_PAD src0_sel:WORD_1 src1_sel:DWORD
	v_and_b32_sdwa v5, v10, v177 dst_sel:DWORD dst_unused:UNUSED_PAD src0_sel:WORD_1 src1_sel:DWORD
	v_add3_u32 v3, v3, v6, s28
	v_add3_u32 v2, v2, v7, s28
	v_add3_u32 v5, v10, v5, s28
	v_add3_u32 v4, v11, v4, s28
	v_and_b32_e32 v3, 0xffff0000, v3
	v_and_b32_e32 v2, 0xffff0000, v2
	s_add_i32 s14, s14, s11
	v_or_b32_sdwa v3, v3, v4 dst_sel:DWORD dst_unused:UNUSED_PAD src0_sel:DWORD src1_sel:WORD_1
	v_or_b32_sdwa v2, v2, v5 dst_sel:DWORD dst_unused:UNUSED_PAD src0_sel:DWORD src1_sel:WORD_1
	s_cmpk_gt_i32 s14, 0x5ff
	global_store_dwordx2 v[34:35], v[2:3], off offset:96
	s_cbranch_scc0 .LBB0_1461
